# packed-to-scalar split: 608 v_pk_mul_f32 in the G1 and G4 epilogues replaced by two v_mul_f32 each (bit-identical), on top of the peeled K step
# speedup vs baseline: 1.0134x; 1.0134x over previous
.Lsec78_a:
	s_lshl_b32 s0, s48, 8
	v_add_u32_e32 v134, s0, v241
	v_ashrrev_i32_e32 v135, 31, v134
	v_lshl_add_u64 v[146:147], v[134:135], 2, s[70:71]
	v_mov_b32_e32 v148, v164
	v_mov_b32_e32 v144, v165
	v_mov_b32_e32 v140, v166
	v_mov_b32_e32 v2, v167
	v_or_b32_e32 v132, s74, v178
	v_ashrrev_i32_e32 v133, 31, v132
	v_lshlrev_b64 v[132:133], 1, v[132:133]
	s_mov_b32 s0, 0x9ce6000
	s_cmp_eq_u32 s2, 8
	s_cselect_b32 s0, 0xbd25800, s0
	v_or_b32_e32 v142, 16, v134
	v_ashrrev_i32_e32 v143, 31, v142
	v_lshlrev_b64 v[142:143], 11, v[142:143]
	v_lshl_add_u64 v[142:143], s[94:95], 0, v[142:143]
	v_or_b32_e32 v138, 32, v134
	v_ashrrev_i32_e32 v139, 31, v138
	v_lshlrev_b64 v[138:139], 11, v[138:139]
	v_lshl_add_u64 v[138:139], s[94:95], 0, v[138:139]
	v_or_b32_e32 v136, 48, v134
	v_ashrrev_i32_e32 v137, 31, v136
	v_lshlrev_b64 v[136:137], 11, v[136:137]
	v_lshl_add_u64 v[136:137], s[94:95], 0, v[136:137]
	s_cmp_eq_u32 s48, 64
	v_mul_f32_e32 v146, v130, v148
	v_mul_f32_e32 v147, v131, v148
	s_nop 0
	v_mul_f32_e32 v146, 0xbfb8aa3b, v146
	v_exp_f32_e32 v146, v146
	v_mul_f32_e32 v150, v128, v148
	v_mul_f32_e32 v151, v129, v148
	v_add_f32_e32 v146, 1.0, v146
	v_rcp_f32_e32 v152, v146
	v_mul_f32_e32 v146, 0xbfb8aa3b, v147
	v_exp_f32_e32 v146, v146
	v_mul_f32_e32 v141, 0xbfb8aa3b, v150
	v_mul_f32_e32 v145, 0xbfb8aa3b, v151
	v_exp_f32_e32 v141, v141
	v_add_f32_e32 v146, 1.0, v146
	v_rcp_f32_e32 v153, v146
	v_mul_f32_e32 v146, v126, v148
	v_mul_f32_e32 v147, v127, v148
	v_mul_f32_e32 v149, v125, v148
	v_mul_f32_e32 v148, v124, v148
	v_mul_f32_e32 v146, 0xbfb8aa3b, v146
	v_exp_f32_e32 v146, v146
	v_mul_f32_e32 v148, 0xbfb8aa3b, v148
	v_mul_f32_e32 v149, 0xbfb8aa3b, v149
	v_exp_f32_e32 v145, v145
	v_add_f32_e32 v146, 1.0, v146
	v_rcp_f32_e32 v154, v146
	v_mul_f32_e32 v146, 0xbfb8aa3b, v147
	v_exp_f32_e32 v148, v148
	v_exp_f32_e32 v149, v149
	v_exp_f32_e32 v146, v146
	v_add_f32_e32 v141, 1.0, v141
	v_add_f32_e32 v145, 1.0, v145
	v_add_f32_e32 v148, 1.0, v148
	v_add_f32_e32 v149, 1.0, v149
	v_add_f32_e32 v146, 1.0, v146
	v_rcp_f32_e32 v141, v141
	v_rcp_f32_e32 v145, v145
	v_rcp_f32_e32 v148, v148
	v_rcp_f32_e32 v149, v149
	v_rcp_f32_e32 v155, v146
	v_lshlrev_b64 v[146:147], 11, v[134:135]
	v_lshl_add_u64 v[146:147], s[94:95], 0, v[146:147]
	v_lshl_add_u64 v[150:151], v[146:147], 0, v[132:133]
	v_add_co_u32_e32 v150, vcc, s0, v150
	v_cvt_pk_bf16_f32 v146, v141, v145
	v_cvt_pk_bf16_f32 v147, v152, v153
	v_cvt_pk_bf16_f32 v148, v148, v149
	v_cvt_pk_bf16_f32 v149, v154, v155
	v_addc_co_u32_e32 v151, vcc, 0, v151, vcc
	global_store_dwordx4 v[150:151], v[146:149], off offset:512
	s_nop 1
	v_mul_f32_e32 v146, v122, v144
	v_mul_f32_e32 v147, v123, v144
	v_mul_f32_e32 v148, v120, v144
	v_mul_f32_e32 v149, v121, v144
	v_mul_f32_e32 v145, 0xbfb8aa3b, v146
	v_exp_f32_e32 v145, v145
	v_mul_f32_e32 v135, 0xbfb8aa3b, v148
	v_mul_f32_e32 v141, 0xbfb8aa3b, v149
	v_exp_f32_e32 v135, v135
	v_add_f32_e32 v145, 1.0, v145
	v_rcp_f32_e32 v148, v145
	v_mul_f32_e32 v145, 0xbfb8aa3b, v147
	v_exp_f32_e32 v145, v145
	v_exp_f32_e32 v141, v141
	v_add_f32_e32 v135, 1.0, v135
	v_rcp_f32_e32 v135, v135
	v_add_f32_e32 v145, 1.0, v145
	v_mul_f32_e32 v146, v118, v144
	v_mul_f32_e32 v147, v119, v144
	v_rcp_f32_e32 v149, v145
	v_mul_f32_e32 v146, 0xbfb8aa3b, v146
	v_exp_f32_e32 v146, v146
	v_mul_f32_e32 v145, v117, v144
	v_mul_f32_e32 v144, v116, v144
	v_add_f32_e32 v141, 1.0, v141
	v_mul_f32_e32 v144, 0xbfb8aa3b, v144
	v_add_f32_e32 v146, 1.0, v146
	v_mul_f32_e32 v145, 0xbfb8aa3b, v145
	v_rcp_f32_e32 v150, v146
	v_mul_f32_e32 v146, 0xbfb8aa3b, v147
	v_exp_f32_e32 v144, v144
	v_exp_f32_e32 v145, v145
	v_exp_f32_e32 v146, v146
	v_rcp_f32_e32 v141, v141
	v_add_f32_e32 v144, 1.0, v144
	v_add_f32_e32 v145, 1.0, v145
	v_add_f32_e32 v146, 1.0, v146
	v_rcp_f32_e32 v144, v144
	v_rcp_f32_e32 v145, v145
	v_rcp_f32_e32 v151, v146
	v_lshl_add_u64 v[146:147], v[142:143], 0, v[132:133]
	v_add_co_u32_e32 v146, vcc, s0, v146
	v_cvt_pk_bf16_f32 v142, v135, v141
	v_cvt_pk_bf16_f32 v143, v148, v149
	v_cvt_pk_bf16_f32 v144, v144, v145
	v_cvt_pk_bf16_f32 v145, v150, v151
	v_addc_co_u32_e32 v147, vcc, 0, v147, vcc
	global_store_dwordx4 v[146:147], v[142:145], off offset:512
	s_nop 1
	v_mul_f32_e32 v144, v112, v140
	v_mul_f32_e32 v145, v113, v140
	v_mul_f32_e32 v142, v114, v140
	v_mul_f32_e32 v143, v115, v140
	v_mul_f32_e32 v141, 0xbfb8aa3b, v145
	v_exp_f32_e32 v141, v141
	v_mul_f32_e32 v135, 0xbfb8aa3b, v144
	v_exp_f32_e32 v135, v135
	v_add_f32_e32 v141, 1.0, v141
	v_rcp_f32_e32 v144, v141
	v_mul_f32_e32 v141, 0xbfb8aa3b, v142
	v_exp_f32_e32 v141, v141
	v_add_f32_e32 v135, 1.0, v135
	v_rcp_f32_e32 v135, v135
	v_add_f32_e32 v141, 1.0, v141
	v_rcp_f32_e32 v145, v141
	v_mul_f32_e32 v141, 0xbfb8aa3b, v143
	v_exp_f32_e32 v141, v141
	s_nop 0
	v_add_f32_e32 v141, 1.0, v141
	v_mul_f32_e32 v142, v110, v140
	v_mul_f32_e32 v143, v111, v140
	v_rcp_f32_e32 v146, v141
	v_mul_f32_e32 v142, 0xbfb8aa3b, v142
	v_exp_f32_e32 v142, v142
	v_mul_f32_e32 v141, v109, v140
	v_mul_f32_e32 v140, v108, v140
	v_add_f32_e32 v142, 1.0, v142
	v_mul_f32_e32 v140, 0xbfb8aa3b, v140
	v_mul_f32_e32 v141, 0xbfb8aa3b, v141
	v_rcp_f32_e32 v147, v142
	v_mul_f32_e32 v142, 0xbfb8aa3b, v143
	v_exp_f32_e32 v140, v140
	v_exp_f32_e32 v141, v141
	v_exp_f32_e32 v142, v142
	v_add_f32_e32 v140, 1.0, v140
	v_add_f32_e32 v141, 1.0, v141
	v_add_f32_e32 v142, 1.0, v142
	v_rcp_f32_e32 v140, v140
	v_rcp_f32_e32 v141, v141
	v_rcp_f32_e32 v148, v142
	v_lshl_add_u64 v[142:143], v[138:139], 0, v[132:133]
	v_add_co_u32_e32 v142, vcc, s0, v142
	v_cvt_pk_bf16_f32 v138, v135, v144
	v_cvt_pk_bf16_f32 v139, v145, v146
	v_cvt_pk_bf16_f32 v140, v140, v141
	v_cvt_pk_bf16_f32 v141, v147, v148
	v_addc_co_u32_e32 v143, vcc, 0, v143, vcc
	global_store_dwordx4 v[142:143], v[138:141], off offset:512
	s_nop 1
	v_mul_f32_e32 v138, v106, v2
	v_mul_f32_e32 v139, v107, v2
	v_mul_f32_e32 v140, v104, v2
	v_mul_f32_e32 v141, v105, v2
	v_mul_f32_e32 v138, 0xbfb8aa3b, v138
	v_exp_f32_e32 v138, v138
	v_mul_f32_e32 v135, 0xbfb8aa3b, v140
	v_mul_f32_e32 v140, 0xbfb8aa3b, v141
	v_exp_f32_e32 v140, v140
	v_add_f32_e32 v138, 1.0, v138
	v_rcp_f32_e32 v143, v138
	v_mul_f32_e32 v138, 0xbfb8aa3b, v139
	v_exp_f32_e32 v138, v138
	v_add_f32_e32 v140, 1.0, v140
	v_rcp_f32_e32 v142, v140
	v_mul_f32_e32 v140, v100, v2
	v_mul_f32_e32 v141, v101, v2
	v_add_f32_e32 v138, 1.0, v138
	v_rcp_f32_e32 v144, v138
	v_mul_f32_e32 v138, v102, v2
	v_mul_f32_e32 v139, v103, v2
	v_mul_f32_e32 v2, 0xbfb8aa3b, v140
	v_mul_f32_e32 v138, 0xbfb8aa3b, v138
	v_exp_f32_e32 v138, v138
	v_mul_f32_e32 v140, 0xbfb8aa3b, v141
	v_exp_f32_e32 v135, v135
	v_exp_f32_e32 v2, v2
	v_add_f32_e32 v138, 1.0, v138
	v_rcp_f32_e32 v146, v138
	v_mul_f32_e32 v138, 0xbfb8aa3b, v139
	v_exp_f32_e32 v140, v140
	v_exp_f32_e32 v138, v138
	v_add_f32_e32 v135, 1.0, v135
	v_add_f32_e32 v2, 1.0, v2
	v_add_f32_e32 v140, 1.0, v140
	v_add_f32_e32 v138, 1.0, v138
	v_rcp_f32_e32 v135, v135
	v_rcp_f32_e32 v2, v2
	v_rcp_f32_e32 v145, v140
	v_rcp_f32_e32 v139, v138
	v_lshl_add_u64 v[140:141], v[136:137], 0, v[132:133]
	v_add_co_u32_e32 v140, vcc, s0, v140
	v_cvt_pk_bf16_f32 v136, v135, v142
	v_cvt_pk_bf16_f32 v137, v143, v144
	v_cvt_pk_bf16_f32 v138, v2, v145
	v_cvt_pk_bf16_f32 v139, v146, v139
	v_addc_co_u32_e32 v141, vcc, 0, v141, vcc
	global_store_dwordx4 v[140:141], v[136:139], off offset:512
	s_cbranch_scc1 .LBB0_70
	v_add_u32_e32 v144, 0x80, v134
	v_ashrrev_i32_e32 v145, 31, v144
	v_lshl_add_u64 v[146:147], v[144:145], 2, s[70:71]
	v_mov_b32_e32 v148, v246
	v_mov_b32_e32 v142, v247
	v_mov_b32_e32 v138, v248
	v_mov_b32_e32 v2, v249
	v_lshlrev_b64 v[144:145], 11, v[144:145]
	v_lshl_add_u64 v[144:145], s[94:95], 0, v[144:145]
	v_add_u32_e32 v140, 0x90, v134
	v_ashrrev_i32_e32 v141, 31, v140
	v_lshlrev_b64 v[140:141], 11, v[140:141]
	v_lshl_add_u64 v[140:141], s[94:95], 0, v[140:141]
	v_add_u32_e32 v136, 0xa0, v134
	v_ashrrev_i32_e32 v137, 31, v136
	v_lshlrev_b64 v[136:137], 11, v[136:137]
	v_lshl_add_u64 v[136:137], s[94:95], 0, v[136:137]
	v_add_u32_e32 v134, 0xb0, v134
	v_ashrrev_i32_e32 v135, 31, v134
	v_lshlrev_b64 v[134:135], 11, v[134:135]
	v_lshl_add_u64 v[134:135], s[94:95], 0, v[134:135]
	v_mul_f32_e32 v146, v98, v148
	v_mul_f32_e32 v147, v99, v148
	s_nop 0
	v_mul_f32_e32 v146, 0xbfb8aa3b, v146
	v_exp_f32_e32 v146, v146
	v_mul_f32_e32 v150, v96, v148
	v_mul_f32_e32 v151, v97, v148
	v_add_f32_e32 v146, 1.0, v146
	v_mul_f32_e32 v139, 0xbfb8aa3b, v150
	v_rcp_f32_e32 v150, v146
	v_mul_f32_e32 v146, 0xbfb8aa3b, v147
	v_exp_f32_e32 v146, v146
	v_mul_f32_e32 v143, 0xbfb8aa3b, v151
	v_exp_f32_e32 v139, v139
	v_exp_f32_e32 v143, v143
	v_add_f32_e32 v146, 1.0, v146
	v_rcp_f32_e32 v151, v146
	v_mul_f32_e32 v146, v94, v148
	v_mul_f32_e32 v147, v95, v148
	v_mul_f32_e32 v149, v93, v148
	v_mul_f32_e32 v148, v92, v148
	v_mul_f32_e32 v146, 0xbfb8aa3b, v146
	v_mul_f32_e32 v148, 0xbfb8aa3b, v148
	v_exp_f32_e32 v148, v148
	v_exp_f32_e32 v146, v146
	v_add_f32_e32 v139, 1.0, v139
	v_add_f32_e32 v143, 1.0, v143
	v_add_f32_e32 v148, 1.0, v148
	v_add_f32_e32 v146, 1.0, v146
	v_rcp_f32_e32 v152, v148
	v_mul_f32_e32 v148, 0xbfb8aa3b, v149
	v_rcp_f32_e32 v154, v146
	v_mul_f32_e32 v146, 0xbfb8aa3b, v147
	v_exp_f32_e32 v148, v148
	v_exp_f32_e32 v146, v146
	v_rcp_f32_e32 v139, v139
	v_rcp_f32_e32 v143, v143
	v_add_f32_e32 v148, 1.0, v148
	v_add_f32_e32 v146, 1.0, v146
	v_rcp_f32_e32 v153, v148
	v_rcp_f32_e32 v147, v146
	v_lshl_add_u64 v[148:149], v[144:145], 0, v[132:133]
	v_add_co_u32_e32 v148, vcc, s0, v148
	v_cvt_pk_bf16_f32 v144, v139, v143
	v_cvt_pk_bf16_f32 v145, v150, v151
	v_cvt_pk_bf16_f32 v146, v152, v153
	v_cvt_pk_bf16_f32 v147, v154, v147
	v_addc_co_u32_e32 v149, vcc, 0, v149, vcc
	global_store_dwordx4 v[148:149], v[144:147], off offset:512
	s_nop 1
	v_mul_f32_e32 v146, v88, v142
	v_mul_f32_e32 v147, v89, v142
	v_mul_f32_e32 v144, v90, v142
	v_mul_f32_e32 v145, v91, v142
	v_mul_f32_e32 v143, 0xbfb8aa3b, v147
	v_exp_f32_e32 v143, v143
	v_mul_f32_e32 v139, 0xbfb8aa3b, v146
	v_exp_f32_e32 v139, v139
	v_add_f32_e32 v143, 1.0, v143
	v_rcp_f32_e32 v146, v143
	v_mul_f32_e32 v143, 0xbfb8aa3b, v144
	v_exp_f32_e32 v143, v143
	v_add_f32_e32 v139, 1.0, v139
	v_rcp_f32_e32 v139, v139
	v_add_f32_e32 v143, 1.0, v143
	v_rcp_f32_e32 v147, v143
	v_mul_f32_e32 v143, 0xbfb8aa3b, v145
	v_exp_f32_e32 v143, v143
	s_nop 0
	v_add_f32_e32 v143, 1.0, v143
	v_mul_f32_e32 v144, v86, v142
	v_mul_f32_e32 v145, v87, v142
	v_rcp_f32_e32 v148, v143
	v_mul_f32_e32 v144, 0xbfb8aa3b, v144
	v_exp_f32_e32 v144, v144
	v_mul_f32_e32 v143, v85, v142
	v_mul_f32_e32 v142, v84, v142
	v_add_f32_e32 v144, 1.0, v144
	v_mul_f32_e32 v142, 0xbfb8aa3b, v142
	v_mul_f32_e32 v143, 0xbfb8aa3b, v143
	v_rcp_f32_e32 v149, v144
	v_mul_f32_e32 v144, 0xbfb8aa3b, v145
	v_exp_f32_e32 v142, v142
	v_exp_f32_e32 v143, v143
	v_exp_f32_e32 v144, v144
	v_add_f32_e32 v142, 1.0, v142
	v_add_f32_e32 v143, 1.0, v143
	v_add_f32_e32 v144, 1.0, v144
	v_rcp_f32_e32 v142, v142
	v_rcp_f32_e32 v143, v143
	v_rcp_f32_e32 v150, v144
	v_lshl_add_u64 v[144:145], v[140:141], 0, v[132:133]
	v_add_co_u32_e32 v144, vcc, s0, v144
	v_cvt_pk_bf16_f32 v140, v139, v146
	v_cvt_pk_bf16_f32 v141, v147, v148
	v_cvt_pk_bf16_f32 v142, v142, v143
	v_cvt_pk_bf16_f32 v143, v149, v150
	v_addc_co_u32_e32 v145, vcc, 0, v145, vcc
	global_store_dwordx4 v[144:145], v[140:143], off offset:512
	s_nop 1
	v_mul_f32_e32 v142, v80, v138
	v_mul_f32_e32 v143, v81, v138
	v_mul_f32_e32 v140, v82, v138
	v_mul_f32_e32 v141, v83, v138
	v_mul_f32_e32 v139, 0xbfb8aa3b, v142
	v_exp_f32_e32 v139, v139
	s_nop 0
	v_add_f32_e32 v139, 1.0, v139
	v_rcp_f32_e32 v142, v139
	v_mul_f32_e32 v139, 0xbfb8aa3b, v143
	v_exp_f32_e32 v139, v139
	s_nop 0
	v_add_f32_e32 v139, 1.0, v139
	v_rcp_f32_e32 v143, v139
	v_mul_f32_e32 v139, 0xbfb8aa3b, v140
	v_exp_f32_e32 v139, v139
	s_nop 0
	v_add_f32_e32 v139, 1.0, v139
	v_rcp_f32_e32 v144, v139
	v_mul_f32_e32 v139, 0xbfb8aa3b, v141
	v_exp_f32_e32 v139, v139
	s_nop 0
	v_add_f32_e32 v139, 1.0, v139
	v_mul_f32_e32 v140, v78, v138
	v_mul_f32_e32 v141, v79, v138
	v_rcp_f32_e32 v145, v139
	v_mul_f32_e32 v140, 0xbfb8aa3b, v140
	v_exp_f32_e32 v140, v140
	v_mul_f32_e32 v139, v77, v138
	v_mul_f32_e32 v138, v76, v138
	v_add_f32_e32 v140, 1.0, v140
	v_mul_f32_e32 v138, 0xbfb8aa3b, v138
	v_mul_f32_e32 v139, 0xbfb8aa3b, v139
	v_rcp_f32_e32 v146, v140
	v_mul_f32_e32 v140, 0xbfb8aa3b, v141
	v_exp_f32_e32 v138, v138
	v_exp_f32_e32 v139, v139
	v_exp_f32_e32 v140, v140
	v_add_f32_e32 v138, 1.0, v138
	v_add_f32_e32 v139, 1.0, v139
	v_add_f32_e32 v140, 1.0, v140
	v_rcp_f32_e32 v138, v138
	v_rcp_f32_e32 v139, v139
	v_rcp_f32_e32 v147, v140
	v_lshl_add_u64 v[140:141], v[136:137], 0, v[132:133]
	v_add_co_u32_e32 v140, vcc, s0, v140
	v_cvt_pk_bf16_f32 v136, v142, v143
	v_cvt_pk_bf16_f32 v137, v144, v145
	v_cvt_pk_bf16_f32 v138, v138, v139
	v_cvt_pk_bf16_f32 v139, v146, v147
	v_addc_co_u32_e32 v141, vcc, 0, v141, vcc
	global_store_dwordx4 v[140:141], v[136:139], off offset:512
	s_nop 1
	v_mul_f32_e32 v136, v74, v2
	v_mul_f32_e32 v137, v75, v2
	v_mul_f32_e32 v138, v72, v2
	v_mul_f32_e32 v139, v73, v2
	v_mul_f32_e32 v136, 0xbfb8aa3b, v136
	v_exp_f32_e32 v136, v136
	v_mul_f32_e32 v138, 0xbfb8aa3b, v138
	v_exp_f32_e32 v138, v138
	v_add_f32_e32 v136, 1.0, v136
	v_rcp_f32_e32 v142, v136
	v_mul_f32_e32 v136, 0xbfb8aa3b, v137
	v_exp_f32_e32 v136, v136
	v_add_f32_e32 v138, 1.0, v138
	v_rcp_f32_e32 v140, v138
	v_mul_f32_e32 v138, 0xbfb8aa3b, v139
	v_add_f32_e32 v136, 1.0, v136
	v_rcp_f32_e32 v143, v136
	v_mul_f32_e32 v136, v70, v2
	v_mul_f32_e32 v137, v71, v2
	v_exp_f32_e32 v138, v138
	v_mul_f32_e32 v136, 0xbfb8aa3b, v136
	v_exp_f32_e32 v136, v136
	v_add_f32_e32 v138, 1.0, v138
	v_rcp_f32_e32 v141, v138
	v_mul_f32_e32 v138, v68, v2
	v_mul_f32_e32 v139, v69, v2
	v_add_f32_e32 v136, 1.0, v136
	v_mul_f32_e32 v2, 0xbfb8aa3b, v138
	v_mul_f32_e32 v138, 0xbfb8aa3b, v139
	v_rcp_f32_e32 v139, v136
	v_mul_f32_e32 v136, 0xbfb8aa3b, v137
	v_exp_f32_e32 v2, v2
	v_exp_f32_e32 v138, v138
	v_exp_f32_e32 v136, v136
	v_add_f32_e32 v2, 1.0, v2
	v_add_f32_e32 v138, 1.0, v138
	v_add_f32_e32 v136, 1.0, v136
	v_rcp_f32_e32 v2, v2
	v_rcp_f32_e32 v138, v138
	v_rcp_f32_e32 v144, v136
	v_lshl_add_u64 v[136:137], v[134:135], 0, v[132:133]
	v_add_co_u32_e32 v136, vcc, s0, v136
	v_cvt_pk_bf16_f32 v132, v140, v141
	v_cvt_pk_bf16_f32 v133, v142, v143
	v_cvt_pk_bf16_f32 v134, v2, v138
	v_cvt_pk_bf16_f32 v135, v139, v144
	v_addc_co_u32_e32 v137, vcc, 0, v137, vcc
	global_store_dwordx4 v[136:137], v[132:135], off offset:512

.LBB0_71:
	s_andn2_b64 vcc, exec, s[0:1]
	s_cbranch_vccnz .LBB0_74
	s_lshl_b32 s0, s48, 8
	s_add_i32 s0, s0, s31
	v_or_b32_e32 v134, s0, v181
	v_ashrrev_i32_e32 v135, 31, v134
	v_lshl_add_u64 v[142:143], v[134:135], 2, s[70:71]
	v_mov_b32_e32 v144, v164
	v_mov_b32_e32 v146, v165
	v_mov_b32_e32 v138, v166
	v_mov_b32_e32 v136, v167
	s_or_b32 s1, s74, s49
	v_or_b32_e32 v2, s1, v242
	s_add_i32 s3, s1, 0xfffff180
	s_add_i32 s4, s0, 0xffffc000
	v_bitop3_b32 v140, s1, 56, v242 bitop3:0xc8
	s_ashr_i32 s1, s3, 6
	v_add_u32_e32 v2, 0xfffff184, v2
	s_ashr_i32 s3, s0, 11
	v_bitop3_b32 v135, s0, v250, v181 bitop3:0xc8
	s_lshr_b32 s4, s4, 4
	v_ashrrev_i32_e32 v139, 6, v2
	v_add_u32_e32 v2, 0x80, v135
	v_mov_b32_e32 v135, s3
	v_mov_b32_e32 v145, s4
	v_cmp_gt_i32_e32 vcc, s20, v134
	v_mov_b64_e32 v[132:133], s[92:93]
	v_or_b32_e32 v137, 4, v140
	v_cndmask_b32_e32 v142, v145, v135, vcc
	v_lshlrev_b32_e32 v143, 1, v142
	v_add_u32_e32 v142, s1, v143
	v_add_u32_e32 v148, v143, v139
	v_ashrrev_i32_e32 v143, 31, v142
	v_lshlrev_b64 v[142:143], 6, v[142:143]
	v_or_b32_e32 v142, v142, v140
	v_cndmask_b32_e32 v2, v244, v2, vcc
	v_ashrrev_i32_e32 v149, 31, v148
	v_mad_u64_u32 v[150:151], s[4:5], v142, s89, v[132:133]
	v_lshlrev_b32_e32 v2, 1, v2
	v_lshlrev_b64 v[148:149], 6, v[148:149]
	v_mad_i32_i24 v151, v143, s89, v151
	v_or_b32_e32 v145, v148, v137
	v_lshl_add_u64 v[142:143], v[150:151], 0, v[2:3]
	s_movk_i32 s17, 0x1000
	v_mad_u64_u32 v[152:153], s[4:5], v145, s89, v[132:133]
	v_add_co_u32_e32 v150, vcc, s17, v142
	v_mad_i32_i24 v153, v149, s89, v153
	s_nop 0
	v_addc_co_u32_e32 v151, vcc, 0, v143, vcc
	s_movk_i32 s16, 0x2000
	v_lshl_add_u64 v[148:149], v[152:153], 0, v[2:3]
	v_add_co_u32_e32 v152, vcc, s16, v142
	s_movk_i32 s21, 0x3000
	s_nop 0
	v_addc_co_u32_e32 v153, vcc, 0, v143, vcc
	v_add_co_u32_e32 v154, vcc, s21, v142
	s_movk_i32 s3, 0x7df
	s_nop 0
	v_addc_co_u32_e32 v155, vcc, 0, v143, vcc
	v_add_co_u32_e32 v156, vcc, s17, v148
	v_or_b32_e32 v141, 16, v134
	s_nop 0
	v_addc_co_u32_e32 v157, vcc, 0, v149, vcc
	v_add_co_u32_e32 v158, vcc, s16, v148
	v_or_b32_e32 v188, 32, v134
	s_nop 0
	v_addc_co_u32_e32 v159, vcc, 0, v149, vcc
	v_or_b32_e32 v189, 48, v134
	v_mul_f32_e32 v162, v128, v144
	v_mul_f32_e32 v163, v129, v144
	v_mul_f32_e32 v160, v130, v144
	v_mul_f32_e32 v161, v131, v144
	v_mul_f32_e32 v168, v126, v144
	v_mul_f32_e32 v169, v127, v144
	v_mul_f32_e32 v145, v125, v144
	v_mul_f32_e32 v144, v124, v144
	v_cvt_pk_bf16_f32 v2, v162, s0
	v_cvt_pk_bf16_f32 v147, v163, s0
	v_cvt_pk_bf16_f32 v160, v160, s0
	v_cvt_pk_bf16_f32 v161, v161, s0
	v_cvt_pk_bf16_f32 v144, v144, s0
	v_cvt_pk_bf16_f32 v145, v145, s0
	v_cvt_pk_bf16_f32 v162, v168, s0
	global_store_short v[142:143], v2, off
	global_store_short v[150:151], v147, off offset:256
	global_store_short v[152:153], v160, off offset:512
	global_store_short v[154:155], v161, off offset:768
	global_store_short v[148:149], v144, off
	global_store_short v[156:157], v145, off offset:256
	global_store_short v[158:159], v162, off offset:512
	v_add_co_u32_e32 v142, vcc, s21, v148
	v_bitop3_b32 v2, v134, s3, 16 bitop3:0xc8
	s_add_i32 s3, s0, 0xffffc010
	v_cvt_pk_bf16_f32 v163, v169, s0
	v_addc_co_u32_e32 v143, vcc, 0, v149, vcc
	s_lshr_b32 s3, s3, 4
	global_store_short v[142:143], v163, off offset:768
	v_mul_f32_e32 v142, v122, v146
	v_mul_f32_e32 v143, v123, v146
	v_mul_f32_e32 v144, v120, v146
	v_mul_f32_e32 v145, v121, v146
	v_mov_b32_e32 v147, s3
	v_cmp_gt_i32_e32 vcc, s20, v141
	v_add_u32_e32 v2, 0x80, v2
	v_cvt_pk_bf16_f32 v144, v144, s0
	v_cndmask_b32_e32 v141, v147, v135, vcc
	v_lshlrev_b32_e32 v141, 1, v141
	v_add_u32_e32 v148, s1, v141
	v_ashrrev_i32_e32 v149, 31, v148
	v_lshlrev_b64 v[148:149], 6, v[148:149]
	v_or_b32_e32 v147, v148, v140
	v_cndmask_b32_e32 v2, v244, v2, vcc
	v_mad_u64_u32 v[150:151], s[4:5], v147, s89, v[132:133]
	v_mad_i32_i24 v151, v149, s89, v151
	v_lshlrev_b32_e32 v2, 1, v2
	v_lshl_add_u64 v[148:149], v[150:151], 0, v[2:3]
	global_store_short v[148:149], v144, off
	v_add_co_u32_e32 v144, vcc, s17, v148
	v_cvt_pk_bf16_f32 v147, v145, s0
	s_nop 0
	v_addc_co_u32_e32 v145, vcc, 0, v149, vcc
	global_store_short v[144:145], v147, off offset:256
	v_add_co_u32_e32 v144, vcc, s16, v148
	v_cvt_pk_bf16_f32 v142, v142, s0
	s_nop 0
	v_addc_co_u32_e32 v145, vcc, 0, v149, vcc
	global_store_short v[144:145], v142, off offset:512
	v_add_co_u32_e32 v142, vcc, s21, v148
	v_cvt_pk_bf16_f32 v144, v143, s0
	s_nop 0
	v_addc_co_u32_e32 v143, vcc, 0, v149, vcc
	global_store_short v[142:143], v144, off offset:768
	v_mul_f32_e32 v142, v118, v146
	v_mul_f32_e32 v143, v119, v146
	v_mul_f32_e32 v144, v116, v146
	v_mul_f32_e32 v145, v117, v146
	v_add_u32_e32 v146, v141, v139
	v_ashrrev_i32_e32 v147, 31, v146
	v_lshlrev_b64 v[146:147], 6, v[146:147]
	v_or_b32_e32 v141, v146, v137
	v_mad_u64_u32 v[148:149], s[4:5], v141, s89, v[132:133]
	v_mad_i32_i24 v149, v147, s89, v149
	v_lshl_add_u64 v[146:147], v[148:149], 0, v[2:3]
	v_cvt_pk_bf16_f32 v2, v144, s0
	v_add_co_u32_e32 v144, vcc, s17, v146
	global_store_short v[146:147], v2, off
	v_cvt_pk_bf16_f32 v2, v145, s0
	v_addc_co_u32_e32 v145, vcc, 0, v147, vcc
	global_store_short v[144:145], v2, off offset:256
	v_add_co_u32_e32 v144, vcc, s16, v146
	v_cvt_pk_bf16_f32 v2, v142, s0
	s_nop 0
	v_addc_co_u32_e32 v145, vcc, 0, v147, vcc
	v_add_co_u32_e32 v142, vcc, s21, v146
	global_store_short v[144:145], v2, off offset:512
	v_cvt_pk_bf16_f32 v2, v143, s0
	v_addc_co_u32_e32 v143, vcc, 0, v147, vcc
	s_movk_i32 s3, 0x7ef
	global_store_short v[142:143], v2, off offset:768
	v_bitop3_b32 v2, v134, s3, 32 bitop3:0xc8
	s_add_i32 s3, s0, 0xffffc020
	s_lshr_b32 s3, s3, 4
	v_mov_b32_e32 v141, s3
	v_cmp_gt_i32_e32 vcc, s20, v188
	v_add_u32_e32 v2, 0x80, v2
	v_mul_f32_e32 v144, v112, v138
	v_mul_f32_e32 v145, v113, v138
	v_cndmask_b32_e32 v141, v141, v135, vcc
	v_lshlrev_b32_e32 v141, 1, v141
	v_add_u32_e32 v146, s1, v141
	v_ashrrev_i32_e32 v147, 31, v146
	v_lshlrev_b64 v[146:147], 6, v[146:147]
	v_or_b32_e32 v146, v146, v140
	v_cndmask_b32_e32 v2, v244, v2, vcc
	v_mad_u64_u32 v[148:149], s[4:5], v146, s89, v[132:133]
	v_mad_i32_i24 v149, v147, s89, v149
	v_lshlrev_b32_e32 v2, 1, v2
	v_lshl_add_u64 v[146:147], v[148:149], 0, v[2:3]
	v_cvt_pk_bf16_f32 v144, v144, s0
	global_store_short v[146:147], v144, off
	v_add_co_u32_e32 v144, vcc, s17, v146
	v_cvt_pk_bf16_f32 v148, v145, s0
	s_nop 0
	v_addc_co_u32_e32 v145, vcc, 0, v147, vcc
	v_mul_f32_e32 v142, v114, v138
	v_mul_f32_e32 v143, v115, v138
	global_store_short v[144:145], v148, off offset:256
	v_add_co_u32_e32 v144, vcc, s16, v146
	v_cvt_pk_bf16_f32 v142, v142, s0
	s_nop 0
	v_addc_co_u32_e32 v145, vcc, 0, v147, vcc
	global_store_short v[144:145], v142, off offset:512
	v_add_co_u32_e32 v142, vcc, s21, v146
	v_add_u32_e32 v146, v141, v139
	v_cvt_pk_bf16_f32 v144, v143, s0
	v_addc_co_u32_e32 v143, vcc, 0, v147, vcc
	v_ashrrev_i32_e32 v147, 31, v146
	v_lshlrev_b64 v[146:147], 6, v[146:147]
	global_store_short v[142:143], v144, off offset:768
	v_mul_f32_e32 v142, v110, v138
	v_mul_f32_e32 v143, v111, v138
	v_mul_f32_e32 v144, v108, v138
	v_mul_f32_e32 v145, v109, v138
	v_or_b32_e32 v138, v146, v137
	v_mad_u64_u32 v[148:149], s[4:5], v138, s89, v[132:133]
	v_mad_i32_i24 v149, v147, s89, v149
	v_lshl_add_u64 v[146:147], v[148:149], 0, v[2:3]
	v_cvt_pk_bf16_f32 v2, v144, s0
	v_add_co_u32_e32 v144, vcc, s17, v146
	global_store_short v[146:147], v2, off
	v_cvt_pk_bf16_f32 v2, v145, s0
	v_addc_co_u32_e32 v145, vcc, 0, v147, vcc
	global_store_short v[144:145], v2, off offset:256
	v_add_co_u32_e32 v144, vcc, s16, v146
	v_cvt_pk_bf16_f32 v2, v142, s0
	s_nop 0
	v_addc_co_u32_e32 v145, vcc, 0, v147, vcc
	v_add_co_u32_e32 v142, vcc, s21, v146
	global_store_short v[144:145], v2, off offset:512
	v_cvt_pk_bf16_f32 v2, v143, s0
	v_addc_co_u32_e32 v143, vcc, 0, v147, vcc
	s_movk_i32 s3, 0x7ff
	global_store_short v[142:143], v2, off offset:768
	v_bitop3_b32 v2, v134, s3, 48 bitop3:0xc8
	s_add_i32 s3, s0, 0xffffc030
	s_lshr_b32 s3, s3, 4
	v_mov_b32_e32 v134, s3
	v_cmp_gt_i32_e32 vcc, s20, v189
	v_add_u32_e32 v2, 0x80, v2
	v_mul_f32_e32 v144, v104, v136
	v_mul_f32_e32 v145, v105, v136
	v_cndmask_b32_e32 v134, v134, v135, vcc
	v_lshlrev_b32_e32 v138, 1, v134
	v_add_u32_e32 v134, s1, v138
	v_ashrrev_i32_e32 v135, 31, v134
	v_lshlrev_b64 v[134:135], 6, v[134:135]
	v_or_b32_e32 v134, v134, v140
	v_cndmask_b32_e32 v2, v244, v2, vcc
	v_mad_u64_u32 v[146:147], s[4:5], v134, s89, v[132:133]
	v_mad_i32_i24 v147, v135, s89, v147
	v_lshlrev_b32_e32 v2, 1, v2
	v_lshl_add_u64 v[134:135], v[146:147], 0, v[2:3]
	v_cvt_pk_bf16_f32 v141, v144, s0
	v_add_co_u32_e32 v144, vcc, s17, v134
	global_store_short v[134:135], v141, off
	v_cvt_pk_bf16_f32 v141, v145, s0
	v_addc_co_u32_e32 v145, vcc, 0, v135, vcc
	v_mul_f32_e32 v142, v106, v136
	v_mul_f32_e32 v143, v107, v136
	global_store_short v[144:145], v141, off offset:256
	v_add_co_u32_e32 v144, vcc, s16, v134
	v_cvt_pk_bf16_f32 v141, v142, s0
	s_nop 0
	v_addc_co_u32_e32 v145, vcc, 0, v135, vcc
	global_store_short v[144:145], v141, off offset:512
	v_add_u32_e32 v144, v138, v139
	v_add_co_u32_e32 v134, vcc, s21, v134
	v_ashrrev_i32_e32 v145, 31, v144
	v_cvt_pk_bf16_f32 v141, v143, s0
	v_addc_co_u32_e32 v135, vcc, 0, v135, vcc
	v_lshlrev_b64 v[144:145], 6, v[144:145]
	global_store_short v[134:135], v141, off offset:768
	v_mul_f32_e32 v134, v102, v136
	v_mul_f32_e32 v135, v103, v136
	v_mul_f32_e32 v142, v100, v136
	v_mul_f32_e32 v143, v101, v136
	v_or_b32_e32 v136, v144, v137
	v_mad_u64_u32 v[132:133], s[4:5], v136, s89, v[132:133]
	v_mad_i32_i24 v133, v145, s89, v133
	v_lshl_add_u64 v[132:133], v[132:133], 0, v[2:3]
	v_cvt_pk_bf16_f32 v2, v142, s0
	v_add_co_u32_e32 v142, vcc, 0x1000, v132
	global_store_short v[132:133], v2, off
	v_cvt_pk_bf16_f32 v2, v143, s0
	v_addc_co_u32_e32 v143, vcc, 0, v133, vcc
	global_store_short v[142:143], v2, off offset:256
	v_add_co_u32_e32 v142, vcc, 0x2000, v132
	v_cvt_pk_bf16_f32 v2, v134, s0
	s_nop 0
	v_addc_co_u32_e32 v143, vcc, 0, v133, vcc
	v_add_co_u32_e32 v132, vcc, 0x3000, v132
	global_store_short v[142:143], v2, off offset:512
	v_cvt_pk_bf16_f32 v2, v135, s0
	v_addc_co_u32_e32 v133, vcc, 0, v133, vcc
	s_cmp_eq_u32 s48, 64
	global_store_short v[132:133], v2, off offset:768
	s_cbranch_scc1 .LBB0_74
	s_add_i32 s3, s0, 0x80
	v_or_b32_e32 v134, s3, v181
	v_ashrrev_i32_e32 v135, 31, v134
	v_lshl_add_u64 v[142:143], v[134:135], 2, s[70:71]
	v_mov_b32_e32 v138, v246
	v_mov_b32_e32 v144, v247
	s_add_i32 s4, s0, 0xffffc080
	s_ashr_i32 s5, s3, 11
	v_bitop3_b32 v2, s3, v250, v181 bitop3:0xc8
	s_lshr_b32 s3, s4, 4
	v_mov_b32_e32 v136, s3
	v_mov_b32_e32 v197, s5
	v_cmp_gt_i32_e32 vcc, s20, v134
	v_mov_b64_e32 v[132:133], s[92:93]
	v_add_u32_e32 v2, 0x80, v2
	v_cndmask_b32_e32 v147, v136, v197, vcc
	v_mov_b32_e32 v146, v248
	v_mov_b32_e32 v136, v249
	v_lshlrev_b32_e32 v143, 1, v147
	v_add_u32_e32 v142, s1, v143
	v_add_u32_e32 v148, v143, v139
	v_ashrrev_i32_e32 v143, 31, v142
	v_lshlrev_b64 v[142:143], 6, v[142:143]
	v_or_b32_e32 v142, v142, v140
	v_cndmask_b32_e32 v2, v244, v2, vcc
	v_ashrrev_i32_e32 v149, 31, v148
	v_mad_u64_u32 v[150:151], s[4:5], v142, s89, v[132:133]
	v_lshlrev_b32_e32 v2, 1, v2
	v_lshlrev_b64 v[148:149], 6, v[148:149]
	v_mad_i32_i24 v151, v143, s89, v151
	v_or_b32_e32 v147, v148, v137
	v_lshl_add_u64 v[142:143], v[150:151], 0, v[2:3]
	v_mad_u64_u32 v[152:153], s[4:5], v147, s89, v[132:133]
	v_add_co_u32_e32 v150, vcc, s17, v142
	v_mad_i32_i24 v153, v149, s89, v153
	s_nop 0
	v_addc_co_u32_e32 v151, vcc, 0, v143, vcc
	v_lshl_add_u64 v[148:149], v[152:153], 0, v[2:3]
	v_add_co_u32_e32 v152, vcc, s16, v142
	s_movk_i32 s3, 0x7df
	s_nop 0
	v_addc_co_u32_e32 v153, vcc, 0, v143, vcc
	v_add_co_u32_e32 v154, vcc, s21, v142
	v_bitop3_b32 v145, v134, s3, 16 bitop3:0xc8
	s_nop 0
	v_addc_co_u32_e32 v155, vcc, 0, v143, vcc
	v_add_co_u32_e32 v156, vcc, s17, v148
	s_add_i32 s3, s0, 0xffffc090
	s_nop 0
	v_addc_co_u32_e32 v157, vcc, 0, v149, vcc
	v_add_co_u32_e32 v158, vcc, s16, v148
	v_or_b32_e32 v135, 16, v134
	s_nop 0
	v_addc_co_u32_e32 v159, vcc, 0, v149, vcc
	v_add_co_u32_e32 v160, vcc, s21, v148
	s_lshr_b32 s3, s3, 4
	s_nop 0
	v_addc_co_u32_e32 v161, vcc, 0, v149, vcc
	v_cmp_gt_i32_e32 vcc, s20, v135
	v_or_b32_e32 v141, 32, v134
	v_or_b32_e32 v196, 48, v134
	v_mul_f32_e32 v168, v96, v138
	v_mul_f32_e32 v169, v97, v138
	v_mul_f32_e32 v162, v98, v138
	v_mul_f32_e32 v163, v99, v138
	v_mul_f32_e32 v188, v94, v138
	v_mul_f32_e32 v189, v95, v138
	v_mul_f32_e32 v190, v92, v138
	v_mul_f32_e32 v191, v93, v138
	v_cvt_pk_bf16_f32 v2, v168, s0
	v_cvt_pk_bf16_f32 v138, v169, s0
	v_cvt_pk_bf16_f32 v147, v162, s0
	v_cvt_pk_bf16_f32 v162, v163, s0
	v_cvt_pk_bf16_f32 v163, v190, s0
	v_cvt_pk_bf16_f32 v168, v191, s0
	v_cvt_pk_bf16_f32 v169, v188, s0
	v_cvt_pk_bf16_f32 v188, v189, s0
	global_store_short v[142:143], v2, off
	global_store_short v[150:151], v138, off offset:256
	global_store_short v[152:153], v147, off offset:512
	global_store_short v[154:155], v162, off offset:768
	global_store_short v[148:149], v163, off
	global_store_short v[156:157], v168, off offset:256
	global_store_short v[158:159], v169, off offset:512
	global_store_short v[160:161], v188, off offset:768
	v_mov_b32_e32 v138, s3
	v_cndmask_b32_e32 v135, v138, v197, vcc
	v_lshlrev_b32_e32 v135, 1, v135
	v_add_u32_e32 v142, s1, v135
	v_ashrrev_i32_e32 v143, 31, v142
	v_lshlrev_b64 v[142:143], 6, v[142:143]
	v_add_u32_e32 v2, 0x80, v145
	v_or_b32_e32 v138, v142, v140
	v_cndmask_b32_e32 v2, v244, v2, vcc
	v_mad_u64_u32 v[148:149], s[4:5], v138, s89, v[132:133]
	v_mad_i32_i24 v149, v143, s89, v149
	v_lshlrev_b32_e32 v2, 1, v2
	v_mul_f32_e32 v194, v88, v144
	v_mul_f32_e32 v195, v89, v144
	v_lshl_add_u64 v[142:143], v[148:149], 0, v[2:3]
	v_cvt_pk_bf16_f32 v138, v194, s0
	v_add_co_u32_e32 v148, vcc, s17, v142
	global_store_short v[142:143], v138, off
	v_cvt_pk_bf16_f32 v138, v195, s0
	v_addc_co_u32_e32 v149, vcc, 0, v143, vcc
	v_mul_f32_e32 v192, v90, v144
	v_mul_f32_e32 v193, v91, v144
	global_store_short v[148:149], v138, off offset:256
	v_add_co_u32_e32 v148, vcc, s16, v142
	v_cvt_pk_bf16_f32 v138, v192, s0
	s_nop 0
	v_addc_co_u32_e32 v149, vcc, 0, v143, vcc
	global_store_short v[148:149], v138, off offset:512
	v_add_u32_e32 v148, v135, v139
	v_ashrrev_i32_e32 v149, 31, v148
	v_lshlrev_b64 v[148:149], 6, v[148:149]
	v_or_b32_e32 v135, v148, v137
	v_add_co_u32_e32 v142, vcc, s21, v142
	v_mad_u64_u32 v[150:151], s[4:5], v135, s89, v[132:133]
	v_cvt_pk_bf16_f32 v138, v193, s0
	v_addc_co_u32_e32 v143, vcc, 0, v143, vcc
	v_mad_i32_i24 v151, v149, s89, v151
	global_store_short v[142:143], v138, off offset:768
	v_mul_f32_e32 v142, v86, v144
	v_mul_f32_e32 v143, v87, v144
	v_mul_f32_e32 v145, v85, v144
	v_mul_f32_e32 v144, v84, v144
	v_lshl_add_u64 v[148:149], v[150:151], 0, v[2:3]
	v_cvt_pk_bf16_f32 v2, v144, s0
	v_add_co_u32_e32 v144, vcc, s17, v148
	global_store_short v[148:149], v2, off
	v_cvt_pk_bf16_f32 v2, v145, s0
	v_addc_co_u32_e32 v145, vcc, 0, v149, vcc
	global_store_short v[144:145], v2, off offset:256
	v_add_co_u32_e32 v144, vcc, s16, v148
	v_cvt_pk_bf16_f32 v2, v142, s0
	s_nop 0
	v_addc_co_u32_e32 v145, vcc, 0, v149, vcc
	v_add_co_u32_e32 v142, vcc, s21, v148
	global_store_short v[144:145], v2, off offset:512
	v_cvt_pk_bf16_f32 v2, v143, s0
	v_addc_co_u32_e32 v143, vcc, 0, v149, vcc
	s_movk_i32 s3, 0x7ef
	global_store_short v[142:143], v2, off offset:768
	v_bitop3_b32 v2, v134, s3, 32 bitop3:0xc8
	s_add_i32 s3, s0, 0xffffc0a0
	s_lshr_b32 s3, s3, 4
	v_mov_b32_e32 v135, s3
	v_cmp_gt_i32_e32 vcc, s20, v141
	v_add_u32_e32 v2, 0x80, v2
	v_mul_f32_e32 v144, v80, v146
	v_mul_f32_e32 v145, v81, v146
	v_cndmask_b32_e32 v135, v135, v197, vcc
	v_lshlrev_b32_e32 v135, 1, v135
	v_add_u32_e32 v148, s1, v135
	v_ashrrev_i32_e32 v149, 31, v148
	v_lshlrev_b64 v[148:149], 6, v[148:149]
	v_or_b32_e32 v138, v148, v140
	v_cndmask_b32_e32 v2, v244, v2, vcc
	v_mad_u64_u32 v[150:151], s[4:5], v138, s89, v[132:133]
	v_mad_i32_i24 v151, v149, s89, v151
	v_lshlrev_b32_e32 v2, 1, v2
	v_lshl_add_u64 v[148:149], v[150:151], 0, v[2:3]
	v_cvt_pk_bf16_f32 v138, v144, s0
	v_add_co_u32_e32 v144, vcc, s17, v148
	global_store_short v[148:149], v138, off
	v_cvt_pk_bf16_f32 v138, v145, s0
	v_addc_co_u32_e32 v145, vcc, 0, v149, vcc
	global_store_short v[144:145], v138, off offset:256
	v_add_co_u32_e32 v144, vcc, s16, v148
	v_mul_f32_e32 v142, v82, v146
	v_mul_f32_e32 v143, v83, v146
	s_nop 0
	v_addc_co_u32_e32 v145, vcc, 0, v149, vcc
	v_cvt_pk_bf16_f32 v138, v142, s0
	v_add_co_u32_e32 v142, vcc, s21, v148
	global_store_short v[144:145], v138, off offset:512
	v_cvt_pk_bf16_f32 v138, v143, s0
	v_addc_co_u32_e32 v143, vcc, 0, v149, vcc
	global_store_short v[142:143], v138, off offset:768
	v_mul_f32_e32 v142, v78, v146
	v_mul_f32_e32 v143, v79, v146
	v_mul_f32_e32 v144, v76, v146
	v_mul_f32_e32 v145, v77, v146
	v_add_u32_e32 v146, v135, v139
	v_ashrrev_i32_e32 v147, 31, v146
	v_lshlrev_b64 v[146:147], 6, v[146:147]
	v_or_b32_e32 v135, v146, v137
	v_mad_u64_u32 v[148:149], s[4:5], v135, s89, v[132:133]
	v_mad_i32_i24 v149, v147, s89, v149
	v_lshl_add_u64 v[146:147], v[148:149], 0, v[2:3]
	v_cvt_pk_bf16_f32 v2, v144, s0
	v_add_co_u32_e32 v144, vcc, s17, v146
	global_store_short v[146:147], v2, off
	v_cvt_pk_bf16_f32 v2, v145, s0
	v_addc_co_u32_e32 v145, vcc, 0, v147, vcc
	global_store_short v[144:145], v2, off offset:256
	v_add_co_u32_e32 v144, vcc, s16, v146
	v_cvt_pk_bf16_f32 v2, v142, s0
	s_nop 0
	v_addc_co_u32_e32 v145, vcc, 0, v147, vcc
	global_store_short v[144:145], v2, off offset:512
	v_cvt_pk_bf16_f32 v2, v143, s0
	v_add_co_u32_e32 v142, vcc, s21, v146
	s_addk_i32 s0, 0xc0b0
	s_nop 0
	v_addc_co_u32_e32 v143, vcc, 0, v147, vcc
	s_movk_i32 s3, 0x7ff
	s_lshr_b32 s0, s0, 4
	global_store_short v[142:143], v2, off offset:768
	v_bitop3_b32 v2, v134, s3, 48 bitop3:0xc8
	v_mov_b32_e32 v134, s0
	v_cmp_gt_i32_e32 vcc, s20, v196
	v_add_u32_e32 v2, 0x80, v2
	v_mul_f32_e32 v144, v72, v136
	v_mul_f32_e32 v145, v73, v136
	v_cndmask_b32_e32 v134, v134, v197, vcc
	v_lshlrev_b32_e32 v138, 1, v134
	v_add_u32_e32 v134, s1, v138
	v_ashrrev_i32_e32 v135, 31, v134
	v_lshlrev_b64 v[134:135], 6, v[134:135]
	v_or_b32_e32 v134, v134, v140
	v_cndmask_b32_e32 v2, v244, v2, vcc
	v_mad_u64_u32 v[140:141], s[0:1], v134, s89, v[132:133]
	v_mad_i32_i24 v141, v135, s89, v141
	v_lshlrev_b32_e32 v2, 1, v2
	v_lshl_add_u64 v[134:135], v[140:141], 0, v[2:3]
	v_cvt_pk_bf16_f32 v140, v144, s0
	global_store_short v[134:135], v140, off
	v_add_co_u32_e32 v140, vcc, s17, v134
	v_cvt_pk_bf16_f32 v144, v145, s0
	s_nop 0
	v_addc_co_u32_e32 v141, vcc, 0, v135, vcc
	global_store_short v[140:141], v144, off offset:256
	v_add_co_u32_e32 v140, vcc, s16, v134
	v_mul_f32_e32 v142, v74, v136
	v_mul_f32_e32 v143, v75, v136
	s_nop 0
	v_addc_co_u32_e32 v141, vcc, 0, v135, vcc
	v_add_u32_e32 v138, v138, v139
	v_cvt_pk_bf16_f32 v142, v142, s0
	v_add_co_u32_e32 v134, vcc, s21, v134
	v_ashrrev_i32_e32 v139, 31, v138
	global_store_short v[140:141], v142, off offset:512
	v_cvt_pk_bf16_f32 v140, v143, s0
	v_addc_co_u32_e32 v135, vcc, 0, v135, vcc
	v_lshlrev_b64 v[138:139], 6, v[138:139]
	global_store_short v[134:135], v140, off offset:768
	v_mul_f32_e32 v134, v70, v136
	v_mul_f32_e32 v135, v71, v136
	v_mul_f32_e32 v140, v68, v136
	v_mul_f32_e32 v141, v69, v136
	v_or_b32_e32 v136, v138, v137
	v_mad_u64_u32 v[132:133], s[0:1], v136, s89, v[132:133]
	v_mad_i32_i24 v133, v139, s89, v133
	v_lshl_add_u64 v[132:133], v[132:133], 0, v[2:3]
	v_cvt_pk_bf16_f32 v2, v140, s0
	v_add_co_u32_e32 v136, vcc, 0x1000, v132
	global_store_short v[132:133], v2, off
	v_cvt_pk_bf16_f32 v2, v141, s0
	v_addc_co_u32_e32 v137, vcc, 0, v133, vcc
	global_store_short v[136:137], v2, off offset:256
	v_add_co_u32_e32 v136, vcc, 0x2000, v132
	v_cvt_pk_bf16_f32 v2, v134, s0
	s_nop 0
	v_addc_co_u32_e32 v137, vcc, 0, v133, vcc
	v_add_co_u32_e32 v132, vcc, 0x3000, v132
	global_store_short v[136:137], v2, off offset:512
	v_cvt_pk_bf16_f32 v2, v135, s0
	v_addc_co_u32_e32 v133, vcc, 0, v133, vcc
	global_store_short v[132:133], v2, off offset:768

.LBB0_93:
	s_or_b64 exec, exec, s[0:1]
	s_waitcnt vmcnt(0)
	v_mul_f32_e32 v206, v128, v188
	v_mul_f32_e32 v207, v129, v188
	v_mov_b32_e32 v2, v141
	v_mul_f32_e32 v204, v130, v188
	v_mul_f32_e32 v205, v131, v188
	v_pk_mul_f32 v[208:209], v[206:207], v[2:3] op_sel:[1,0] op_sel_hi:[0,0]
	v_mov_b32_e32 v2, v143
	v_pk_fma_f32 v[210:211], v[206:207], v[140:141], v[208:209] neg_lo:[0,0,1] neg_hi:[0,0,1]
	v_pk_fma_f32 v[140:141], v[206:207], v[140:141], v[208:209] op_sel_hi:[1,0,1]
	v_pk_mul_f32 v[206:207], v[204:205], v[2:3] op_sel:[1,0] op_sel_hi:[0,0]
	v_pk_fma_f32 v[208:209], v[204:205], v[142:143], v[206:207] neg_lo:[0,0,1] neg_hi:[0,0,1]
	v_pk_fma_f32 v[142:143], v[204:205], v[142:143], v[206:207] op_sel_hi:[1,0,1]
	v_mul_f32_e32 v204, v126, v188
	v_mul_f32_e32 v205, v127, v188
	v_mul_f32_e32 v189, v125, v188
	v_mul_f32_e32 v188, v124, v188
	v_mov_b32_e32 v2, v133
	v_pk_mul_f32 v[206:207], v[188:189], v[2:3] op_sel:[1,0] op_sel_hi:[0,0]
	v_mov_b32_e32 v2, v135
	v_or_b32_e32 v168, s74, v178
	v_pk_fma_f32 v[220:221], v[188:189], v[132:133], v[206:207] neg_lo:[0,0,1] neg_hi:[0,0,1]
	v_pk_fma_f32 v[206:207], v[188:189], v[132:133], v[206:207] op_sel_hi:[1,0,1]
	v_pk_mul_f32 v[132:133], v[204:205], v[2:3] op_sel:[1,0] op_sel_hi:[0,0]
	v_ashrrev_i32_e32 v169, 31, v168
	v_pk_fma_f32 v[222:223], v[204:205], v[134:135], v[132:133] neg_lo:[0,0,1] neg_hi:[0,0,1]
	v_pk_fma_f32 v[134:135], v[204:205], v[134:135], v[132:133] op_sel_hi:[1,0,1]
	v_lshlrev_b64 v[132:133], 8, v[190:191]
	v_lshl_add_u64 v[132:133], s[94:95], 0, v[132:133]
	v_lshlrev_b64 v[188:189], 1, v[168:169]
	v_lshl_add_u64 v[168:169], v[132:133], 0, v[188:189]
	s_mov_b32 s0, 0x949e000
	v_add_co_u32_e32 v140, vcc, s0, v168
	v_cvt_pk_bf16_f32 v132, v210, v141
	v_cvt_pk_bf16_f32 v133, v208, v143
	v_cvt_pk_bf16_f32 v134, v220, v207
	v_cvt_pk_bf16_f32 v135, v222, v135
	v_addc_co_u32_e32 v141, vcc, 0, v169, vcc
	global_store_dwordx4 v[140:141], v[132:135], off offset:1024
	v_mov_b32_e32 v2, v149
	v_ashrrev_i32_e32 v193, 31, v192
	v_mul_f32_e32 v134, v120, v194
	v_mul_f32_e32 v135, v121, v194
	v_mul_f32_e32 v132, v122, v194
	v_mul_f32_e32 v133, v123, v194
	v_pk_mul_f32 v[140:141], v[134:135], v[2:3] op_sel:[1,0] op_sel_hi:[0,0]
	v_mov_b32_e32 v2, v151
	v_pk_fma_f32 v[142:143], v[134:135], v[148:149], v[140:141] neg_lo:[0,0,1] neg_hi:[0,0,1]
	v_pk_fma_f32 v[134:135], v[134:135], v[148:149], v[140:141] op_sel_hi:[1,0,1]
	v_pk_mul_f32 v[140:141], v[132:133], v[2:3] op_sel:[1,0] op_sel_hi:[0,0]
	v_pk_fma_f32 v[148:149], v[132:133], v[150:151], v[140:141] neg_lo:[0,0,1] neg_hi:[0,0,1]
	v_pk_fma_f32 v[132:133], v[132:133], v[150:151], v[140:141] op_sel_hi:[1,0,1]
	v_mul_f32_e32 v150, v116, v194
	v_mul_f32_e32 v151, v117, v194
	v_mov_b32_e32 v2, v137
	v_mul_f32_e32 v140, v118, v194
	v_mul_f32_e32 v141, v119, v194
	v_pk_mul_f32 v[168:169], v[150:151], v[2:3] op_sel:[1,0] op_sel_hi:[0,0]
	v_mov_b32_e32 v2, v139
	v_pk_fma_f32 v[194:195], v[150:151], v[136:137], v[168:169] neg_lo:[0,0,1] neg_hi:[0,0,1]
	v_pk_fma_f32 v[136:137], v[150:151], v[136:137], v[168:169] op_sel_hi:[1,0,1]
	v_pk_mul_f32 v[150:151], v[140:141], v[2:3] op_sel:[1,0] op_sel_hi:[0,0]
	v_pk_fma_f32 v[168:169], v[140:141], v[138:139], v[150:151] neg_lo:[0,0,1] neg_hi:[0,0,1]
	v_pk_fma_f32 v[138:139], v[140:141], v[138:139], v[150:151] op_sel_hi:[1,0,1]
	v_lshlrev_b64 v[140:141], 8, v[192:193]
	v_lshl_add_u64 v[140:141], s[94:95], 0, v[140:141]
	v_lshl_add_u64 v[140:141], v[140:141], 0, v[188:189]
	v_add_co_u32_e32 v136, vcc, s0, v140
	v_cvt_pk_bf16_f32 v132, v142, v135
	v_cvt_pk_bf16_f32 v133, v148, v133
	v_cvt_pk_bf16_f32 v134, v194, v137
	v_cvt_pk_bf16_f32 v135, v168, v139
	v_addc_co_u32_e32 v137, vcc, 0, v141, vcc
	global_store_dwordx4 v[136:137], v[132:135], off offset:1024
	v_mov_b32_e32 v2, v157
	v_mul_f32_e32 v142, v108, v198
	v_mul_f32_e32 v143, v109, v198
	v_mul_f32_e32 v134, v112, v198
	v_mul_f32_e32 v135, v113, v198
	v_mul_f32_e32 v132, v114, v198
	v_mul_f32_e32 v133, v115, v198
	v_pk_mul_f32 v[136:137], v[134:135], v[2:3] op_sel:[1,0] op_sel_hi:[0,0]
	v_mov_b32_e32 v2, v159
	v_pk_fma_f32 v[138:139], v[134:135], v[156:157], v[136:137] neg_lo:[0,0,1] neg_hi:[0,0,1]
	v_pk_fma_f32 v[134:135], v[134:135], v[156:157], v[136:137] op_sel_hi:[1,0,1]
	v_pk_mul_f32 v[136:137], v[132:133], v[2:3] op_sel:[1,0] op_sel_hi:[0,0]
	v_mov_b32_e32 v2, v145
	v_pk_fma_f32 v[140:141], v[132:133], v[158:159], v[136:137] neg_lo:[0,0,1] neg_hi:[0,0,1]
	v_pk_fma_f32 v[132:133], v[132:133], v[158:159], v[136:137] op_sel_hi:[1,0,1]
	v_mul_f32_e32 v136, v110, v198
	v_mul_f32_e32 v137, v111, v198
	v_pk_mul_f32 v[148:149], v[142:143], v[2:3] op_sel:[1,0] op_sel_hi:[0,0]
	v_mov_b32_e32 v2, v147
	v_ashrrev_i32_e32 v197, 31, v196
	v_pk_fma_f32 v[150:151], v[142:143], v[144:145], v[148:149] neg_lo:[0,0,1] neg_hi:[0,0,1]
	v_pk_fma_f32 v[142:143], v[142:143], v[144:145], v[148:149] op_sel_hi:[1,0,1]
	v_pk_mul_f32 v[144:145], v[136:137], v[2:3] op_sel:[1,0] op_sel_hi:[0,0]
	v_pk_fma_f32 v[148:149], v[136:137], v[146:147], v[144:145] neg_lo:[0,0,1] neg_hi:[0,0,1]
	v_pk_fma_f32 v[136:137], v[136:137], v[146:147], v[144:145] op_sel_hi:[1,0,1]
	v_lshlrev_b64 v[144:145], 8, v[196:197]
	v_lshl_add_u64 v[144:145], s[94:95], 0, v[144:145]
	v_lshl_add_u64 v[144:145], v[144:145], 0, v[188:189]
	v_add_co_u32_e32 v136, vcc, s0, v144
	v_cvt_pk_bf16_f32 v132, v138, v135
	v_cvt_pk_bf16_f32 v133, v140, v133
	v_cvt_pk_bf16_f32 v134, v150, v143
	v_cvt_pk_bf16_f32 v135, v148, v137
	v_addc_co_u32_e32 v137, vcc, 0, v145, vcc
	global_store_dwordx4 v[136:137], v[132:135], off offset:1024
	v_mov_b32_e32 v2, v161
	v_mul_f32_e32 v142, v100, v202
	v_mul_f32_e32 v143, v101, v202
	v_mul_f32_e32 v134, v104, v202
	v_mul_f32_e32 v135, v105, v202
	v_mul_f32_e32 v132, v106, v202
	v_mul_f32_e32 v133, v107, v202
	v_pk_mul_f32 v[136:137], v[134:135], v[2:3] op_sel:[1,0] op_sel_hi:[0,0]
	v_mov_b32_e32 v2, v163
	v_pk_fma_f32 v[138:139], v[134:135], v[160:161], v[136:137] neg_lo:[0,0,1] neg_hi:[0,0,1]
	v_pk_fma_f32 v[134:135], v[134:135], v[160:161], v[136:137] op_sel_hi:[1,0,1]
	v_pk_mul_f32 v[136:137], v[132:133], v[2:3] op_sel:[1,0] op_sel_hi:[0,0]
	v_mov_b32_e32 v2, v153
	v_pk_fma_f32 v[140:141], v[132:133], v[162:163], v[136:137] neg_lo:[0,0,1] neg_hi:[0,0,1]
	v_pk_fma_f32 v[132:133], v[132:133], v[162:163], v[136:137] op_sel_hi:[1,0,1]
	v_mul_f32_e32 v136, v102, v202
	v_mul_f32_e32 v137, v103, v202
	v_pk_mul_f32 v[144:145], v[142:143], v[2:3] op_sel:[1,0] op_sel_hi:[0,0]
	v_mov_b32_e32 v2, v155
	v_ashrrev_i32_e32 v201, 31, v200
	v_pk_fma_f32 v[146:147], v[142:143], v[152:153], v[144:145] neg_lo:[0,0,1] neg_hi:[0,0,1]
	v_pk_fma_f32 v[142:143], v[142:143], v[152:153], v[144:145] op_sel_hi:[1,0,1]
	v_pk_mul_f32 v[144:145], v[136:137], v[2:3] op_sel:[1,0] op_sel_hi:[0,0]
	v_pk_fma_f32 v[148:149], v[136:137], v[154:155], v[144:145] neg_lo:[0,0,1] neg_hi:[0,0,1]
	v_pk_fma_f32 v[136:137], v[136:137], v[154:155], v[144:145] op_sel_hi:[1,0,1]
	v_lshlrev_b64 v[144:145], 8, v[200:201]
	v_lshl_add_u64 v[144:145], s[94:95], 0, v[144:145]
	v_lshl_add_u64 v[144:145], v[144:145], 0, v[188:189]
	v_add_co_u32_e32 v136, vcc, 0x949e000, v144
	v_cvt_pk_bf16_f32 v132, v138, v135
	v_cvt_pk_bf16_f32 v133, v140, v133
	v_cvt_pk_bf16_f32 v134, v146, v143
	v_cvt_pk_bf16_f32 v135, v148, v137
	v_addc_co_u32_e32 v137, vcc, 0, v145, vcc
	s_cmp_eq_u32 s48, 64
	global_store_dwordx4 v[136:137], v[132:135], off offset:1024
	s_cbranch_scc1 .LBB0_111
	v_add_u32_e32 v190, 0x80, v190
	v_ashrrev_i32_e32 v191, 31, v190
	v_lshl_add_u64 v[152:153], v[190:191], 2, s[70:71]
	v_mov_b32_e32 v192, v246
	s_movk_i32 s0, 0x7cf
	v_and_or_b32 v2, v190, s0, 16
	v_cmp_gt_i32_e32 vcc, s20, v190
	v_mov_b32_e32 v133, 0
	v_mov_b32_e32 v132, 1.0
	v_cndmask_b32_e32 v2, v181, v2, vcc
	v_lshlrev_b32_e32 v2, 6, v2
	v_lshl_add_u64 v[140:141], s[84:85], 0, v[2:3]
	v_mov_b32_e32 v136, 1.0
	v_mov_b32_e32 v137, 0
	v_mov_b32_e32 v138, 1.0
	v_mov_b32_e32 v139, 0
	s_and_saveexec_b64 s[0:1], s[38:39]
	s_cbranch_execz .LBB0_96
	v_lshlrev_b32_e32 v2, 2, v170
	v_lshl_add_u64 v[134:135], v[140:141], 0, v[2:3]
	global_load_dwordx4 v[136:139], v[134:135], off

.LBB0_110:
	s_or_b64 exec, exec, s[0:1]
	s_waitcnt vmcnt(0)
	v_mul_f32_e32 v206, v96, v192
	v_mul_f32_e32 v207, v97, v192
	v_mov_b32_e32 v2, v137
	v_mul_f32_e32 v168, v98, v192
	v_mul_f32_e32 v169, v99, v192
	v_pk_mul_f32 v[208:209], v[206:207], v[2:3] op_sel:[1,0] op_sel_hi:[0,0]
	v_mov_b32_e32 v2, v139
	v_pk_fma_f32 v[210:211], v[206:207], v[136:137], v[208:209] neg_lo:[0,0,1] neg_hi:[0,0,1]
	v_pk_fma_f32 v[136:137], v[206:207], v[136:137], v[208:209] op_sel_hi:[1,0,1]
	v_pk_mul_f32 v[206:207], v[168:169], v[2:3] op_sel:[1,0] op_sel_hi:[0,0]
	v_pk_fma_f32 v[208:209], v[168:169], v[138:139], v[206:207] neg_lo:[0,0,1] neg_hi:[0,0,1]
	v_pk_fma_f32 v[138:139], v[168:169], v[138:139], v[206:207] op_sel_hi:[1,0,1]
	v_mul_f32_e32 v168, v94, v192
	v_mul_f32_e32 v169, v95, v192
	v_mul_f32_e32 v193, v93, v192
	v_mul_f32_e32 v192, v92, v192
	v_mov_b32_e32 v2, v133
	v_pk_mul_f32 v[206:207], v[192:193], v[2:3] op_sel:[1,0] op_sel_hi:[0,0]
	v_mov_b32_e32 v2, v135
	v_pk_fma_f32 v[220:221], v[192:193], v[132:133], v[206:207] neg_lo:[0,0,1] neg_hi:[0,0,1]
	v_pk_fma_f32 v[192:193], v[192:193], v[132:133], v[206:207] op_sel_hi:[1,0,1]
	v_pk_mul_f32 v[132:133], v[168:169], v[2:3] op_sel:[1,0] op_sel_hi:[0,0]
	v_pk_fma_f32 v[206:207], v[168:169], v[134:135], v[132:133] neg_lo:[0,0,1] neg_hi:[0,0,1]
	v_pk_fma_f32 v[134:135], v[168:169], v[134:135], v[132:133] op_sel_hi:[1,0,1]
	v_lshlrev_b64 v[132:133], 8, v[190:191]
	v_lshl_add_u64 v[132:133], s[94:95], 0, v[132:133]
	v_lshl_add_u64 v[168:169], v[132:133], 0, v[188:189]
	s_mov_b32 s0, 0x949e000
	v_add_co_u32_e32 v136, vcc, s0, v168
	v_cvt_pk_bf16_f32 v132, v210, v137
	v_cvt_pk_bf16_f32 v133, v208, v139
	v_cvt_pk_bf16_f32 v134, v220, v193
	v_cvt_pk_bf16_f32 v135, v206, v135
	v_addc_co_u32_e32 v137, vcc, 0, v169, vcc
	global_store_dwordx4 v[136:137], v[132:135], off offset:1024
	v_mov_b32_e32 v2, v149
	v_ashrrev_i32_e32 v195, 31, v194
	v_mul_f32_e32 v134, v88, v196
	v_mul_f32_e32 v135, v89, v196
	v_mul_f32_e32 v132, v90, v196
	v_mul_f32_e32 v133, v91, v196
	v_pk_mul_f32 v[136:137], v[134:135], v[2:3] op_sel:[1,0] op_sel_hi:[0,0]
	v_mov_b32_e32 v2, v151
	v_pk_fma_f32 v[138:139], v[134:135], v[148:149], v[136:137] neg_lo:[0,0,1] neg_hi:[0,0,1]
	v_pk_fma_f32 v[134:135], v[134:135], v[148:149], v[136:137] op_sel_hi:[1,0,1]
	v_pk_mul_f32 v[136:137], v[132:133], v[2:3] op_sel:[1,0] op_sel_hi:[0,0]
	v_pk_fma_f32 v[148:149], v[132:133], v[150:151], v[136:137] neg_lo:[0,0,1] neg_hi:[0,0,1]
	v_pk_fma_f32 v[132:133], v[132:133], v[150:151], v[136:137] op_sel_hi:[1,0,1]
	v_mul_f32_e32 v150, v84, v196
	v_mul_f32_e32 v151, v85, v196
	v_mov_b32_e32 v2, v141
	v_mul_f32_e32 v136, v86, v196
	v_mul_f32_e32 v137, v87, v196
	v_pk_mul_f32 v[168:169], v[150:151], v[2:3] op_sel:[1,0] op_sel_hi:[0,0]
	v_mov_b32_e32 v2, v143
	v_pk_fma_f32 v[190:191], v[150:151], v[140:141], v[168:169] neg_lo:[0,0,1] neg_hi:[0,0,1]
	v_pk_fma_f32 v[140:141], v[150:151], v[140:141], v[168:169] op_sel_hi:[1,0,1]
	v_pk_mul_f32 v[150:151], v[136:137], v[2:3] op_sel:[1,0] op_sel_hi:[0,0]
	v_pk_fma_f32 v[168:169], v[136:137], v[142:143], v[150:151] neg_lo:[0,0,1] neg_hi:[0,0,1]
	v_pk_fma_f32 v[136:137], v[136:137], v[142:143], v[150:151] op_sel_hi:[1,0,1]
	v_lshlrev_b64 v[142:143], 8, v[194:195]
	v_lshl_add_u64 v[142:143], s[94:95], 0, v[142:143]
	v_lshl_add_u64 v[142:143], v[142:143], 0, v[188:189]
	v_add_co_u32_e32 v136, vcc, s0, v142
	v_cvt_pk_bf16_f32 v132, v138, v135
	v_cvt_pk_bf16_f32 v133, v148, v133
	v_cvt_pk_bf16_f32 v134, v190, v141
	v_cvt_pk_bf16_f32 v135, v168, v137
	v_addc_co_u32_e32 v137, vcc, 0, v143, vcc
	global_store_dwordx4 v[136:137], v[132:135], off offset:1024
	v_mov_b32_e32 v2, v157
	v_mul_f32_e32 v142, v76, v200
	v_mul_f32_e32 v143, v77, v200
	v_mul_f32_e32 v134, v80, v200
	v_mul_f32_e32 v135, v81, v200
	v_mul_f32_e32 v132, v82, v200
	v_mul_f32_e32 v133, v83, v200
	v_pk_mul_f32 v[136:137], v[134:135], v[2:3] op_sel:[1,0] op_sel_hi:[0,0]
	v_mov_b32_e32 v2, v159
	v_pk_fma_f32 v[138:139], v[134:135], v[156:157], v[136:137] neg_lo:[0,0,1] neg_hi:[0,0,1]
	v_pk_fma_f32 v[134:135], v[134:135], v[156:157], v[136:137] op_sel_hi:[1,0,1]
	v_pk_mul_f32 v[136:137], v[132:133], v[2:3] op_sel:[1,0] op_sel_hi:[0,0]
	v_mov_b32_e32 v2, v145
	v_pk_fma_f32 v[140:141], v[132:133], v[158:159], v[136:137] neg_lo:[0,0,1] neg_hi:[0,0,1]
	v_pk_fma_f32 v[132:133], v[132:133], v[158:159], v[136:137] op_sel_hi:[1,0,1]
	v_mul_f32_e32 v136, v78, v200
	v_mul_f32_e32 v137, v79, v200
	v_pk_mul_f32 v[148:149], v[142:143], v[2:3] op_sel:[1,0] op_sel_hi:[0,0]
	v_mov_b32_e32 v2, v147
	v_ashrrev_i32_e32 v199, 31, v198
	v_pk_fma_f32 v[150:151], v[142:143], v[144:145], v[148:149] neg_lo:[0,0,1] neg_hi:[0,0,1]
	v_pk_fma_f32 v[142:143], v[142:143], v[144:145], v[148:149] op_sel_hi:[1,0,1]
	v_pk_mul_f32 v[144:145], v[136:137], v[2:3] op_sel:[1,0] op_sel_hi:[0,0]
	v_pk_fma_f32 v[148:149], v[136:137], v[146:147], v[144:145] neg_lo:[0,0,1] neg_hi:[0,0,1]
	v_pk_fma_f32 v[136:137], v[136:137], v[146:147], v[144:145] op_sel_hi:[1,0,1]
	v_lshlrev_b64 v[144:145], 8, v[198:199]
	v_lshl_add_u64 v[144:145], s[94:95], 0, v[144:145]
	v_lshl_add_u64 v[144:145], v[144:145], 0, v[188:189]
	v_add_co_u32_e32 v136, vcc, s0, v144
	v_cvt_pk_bf16_f32 v132, v138, v135
	v_cvt_pk_bf16_f32 v133, v140, v133
	v_cvt_pk_bf16_f32 v134, v150, v143
	v_cvt_pk_bf16_f32 v135, v148, v137
	v_addc_co_u32_e32 v137, vcc, 0, v145, vcc
	global_store_dwordx4 v[136:137], v[132:135], off offset:1024
	v_mov_b32_e32 v2, v161
	v_mul_f32_e32 v142, v68, v204
	v_mul_f32_e32 v143, v69, v204
	v_mul_f32_e32 v134, v72, v204
	v_mul_f32_e32 v135, v73, v204
	v_mul_f32_e32 v132, v74, v204
	v_mul_f32_e32 v133, v75, v204
	v_pk_mul_f32 v[136:137], v[134:135], v[2:3] op_sel:[1,0] op_sel_hi:[0,0]
	v_mov_b32_e32 v2, v163
	v_pk_fma_f32 v[138:139], v[134:135], v[160:161], v[136:137] neg_lo:[0,0,1] neg_hi:[0,0,1]
	v_pk_fma_f32 v[134:135], v[134:135], v[160:161], v[136:137] op_sel_hi:[1,0,1]
	v_pk_mul_f32 v[136:137], v[132:133], v[2:3] op_sel:[1,0] op_sel_hi:[0,0]
	v_mov_b32_e32 v2, v153
	v_pk_fma_f32 v[140:141], v[132:133], v[162:163], v[136:137] neg_lo:[0,0,1] neg_hi:[0,0,1]
	v_pk_fma_f32 v[132:133], v[132:133], v[162:163], v[136:137] op_sel_hi:[1,0,1]
	v_mul_f32_e32 v136, v70, v204
	v_mul_f32_e32 v137, v71, v204
	v_pk_mul_f32 v[144:145], v[142:143], v[2:3] op_sel:[1,0] op_sel_hi:[0,0]
	v_mov_b32_e32 v2, v155
	v_ashrrev_i32_e32 v203, 31, v202
	v_pk_fma_f32 v[146:147], v[142:143], v[152:153], v[144:145] neg_lo:[0,0,1] neg_hi:[0,0,1]
	v_pk_fma_f32 v[142:143], v[142:143], v[152:153], v[144:145] op_sel_hi:[1,0,1]
	v_pk_mul_f32 v[144:145], v[136:137], v[2:3] op_sel:[1,0] op_sel_hi:[0,0]
	v_pk_fma_f32 v[148:149], v[136:137], v[154:155], v[144:145] neg_lo:[0,0,1] neg_hi:[0,0,1]
	v_pk_fma_f32 v[136:137], v[136:137], v[154:155], v[144:145] op_sel_hi:[1,0,1]
	v_lshlrev_b64 v[144:145], 8, v[202:203]
	v_lshl_add_u64 v[144:145], s[94:95], 0, v[144:145]
	v_lshl_add_u64 v[144:145], v[144:145], 0, v[188:189]
	v_add_co_u32_e32 v136, vcc, 0x949e000, v144
	v_cvt_pk_bf16_f32 v132, v138, v135
	v_cvt_pk_bf16_f32 v133, v140, v133
	v_cvt_pk_bf16_f32 v134, v146, v143
	v_cvt_pk_bf16_f32 v135, v148, v137
	v_addc_co_u32_e32 v137, vcc, 0, v145, vcc
	global_store_dwordx4 v[136:137], v[132:135], off offset:1024

.LBB0_129:
	s_or_b64 exec, exec, s[0:1]
	s_waitcnt vmcnt(0)
	s_and_saveexec_b64 s[0:1], s[38:39]
	v_mov_b32_e32 v210, v141
	v_mov_b32_e32 v206, v143
	v_mov_b32_e32 v198, v133
	v_mov_b32_e32 v214, v135
	v_mov_b32_e32 v218, v149
	v_mov_b32_e32 v216, v151
	v_mov_b32_e32 v204, v137
	v_mov_b32_e32 v222, v139
	v_mov_b32_e32 v226, v157
	v_mov_b32_e32 v224, v159
	v_mov_b32_e32 v212, v145
	v_mov_b32_e32 v228, v147
	v_mov_b32_e32 v232, v161
	v_mov_b32_e32 v230, v163
	v_mov_b32_e32 v220, v153
	v_mov_b32_e32 v2, v155
	s_or_b64 exec, exec, s[0:1]
	v_mul_f32_e32 v168, v128, v188
	v_mul_f32_e32 v169, v129, v188
	v_mul_f32_e32 v236, v130, v188
	v_mul_f32_e32 v237, v131, v188
	v_pk_mul_f32 v[210:211], v[168:169], v[210:211] op_sel:[1,0] op_sel_hi:[0,0]
	v_pk_fma_f32 v[238:239], v[168:169], v[140:141], v[210:211] op_sel_hi:[1,0,1] neg_lo:[0,0,1] neg_hi:[0,0,1]
	v_pk_fma_f32 v[140:141], v[168:169], v[140:141], v[210:211] op_sel_hi:[1,0,1]
	v_pk_mul_f32 v[168:169], v[236:237], v[206:207] op_sel:[1,0] op_sel_hi:[0,0]
	v_pk_fma_f32 v[206:207], v[236:237], v[142:143], v[168:169] op_sel_hi:[1,0,1] neg_lo:[0,0,1] neg_hi:[0,0,1]
	v_pk_fma_f32 v[142:143], v[236:237], v[142:143], v[168:169] op_sel_hi:[1,0,1]
	v_mul_f32_e32 v168, v126, v188
	v_mul_f32_e32 v169, v127, v188
	v_mul_f32_e32 v189, v125, v188
	v_mul_f32_e32 v188, v124, v188
	v_mov_b32_e32 v207, v143
	s_mov_b32 s4, 0x3e000000
	v_pk_mul_f32 v[198:199], v[188:189], v[198:199] op_sel:[1,0] op_sel_hi:[0,0]
	v_or_b32_e32 v234, s74, v178
	v_mul_f32_e32 v142, s4, v206
	v_mul_f32_e32 v143, s4, v207
	v_pk_fma_f32 v[206:207], v[188:189], v[132:133], v[198:199] op_sel_hi:[1,0,1] neg_lo:[0,0,1] neg_hi:[0,0,1]
	v_pk_fma_f32 v[132:133], v[188:189], v[132:133], v[198:199] op_sel_hi:[1,0,1]
	v_pk_mul_f32 v[188:189], v[168:169], v[214:215] op_sel:[1,0] op_sel_hi:[0,0]
	v_ashrrev_i32_e32 v235, 31, v234
	v_pk_fma_f32 v[198:199], v[168:169], v[134:135], v[188:189] op_sel_hi:[1,0,1] neg_lo:[0,0,1] neg_hi:[0,0,1]
	v_pk_fma_f32 v[134:135], v[168:169], v[134:135], v[188:189] op_sel_hi:[1,0,1]
	v_mov_b32_e32 v207, v133
	v_lshlrev_b64 v[132:133], 10, v[190:191]
	v_mov_b32_e32 v239, v141
	v_mov_b32_e32 v199, v135
	v_lshl_add_u64 v[132:133], s[94:95], 0, v[132:133]
	v_lshlrev_b64 v[188:189], 1, v[234:235]
	v_mul_f32_e32 v140, s4, v238
	v_mul_f32_e32 v141, s4, v239
	v_mul_f32_e32 v168, s4, v198
	v_mul_f32_e32 v169, s4, v199
	v_lshl_add_u64 v[198:199], v[132:133], 0, v[188:189]
	s_mov_b32 s0, 0x847e000
	v_mul_f32_e32 v134, s4, v206
	v_mul_f32_e32 v135, s4, v207
	v_cvt_pk_bf16_f32 v132, v140, v141
	v_add_co_u32_e32 v140, vcc, s0, v198
	v_cvt_pk_bf16_f32 v133, v142, v143
	v_cvt_pk_bf16_f32 v134, v134, v135
	v_cvt_pk_bf16_f32 v135, v168, v169
	v_addc_co_u32_e32 v141, vcc, 0, v199, vcc
	global_store_dwordx4 v[140:141], v[132:135], off offset:2048
	v_ashrrev_i32_e32 v193, 31, v192
	v_ashrrev_i32_e32 v195, 31, v194
	v_mul_f32_e32 v134, v120, v196
	v_mul_f32_e32 v135, v121, v196
	v_mul_f32_e32 v132, v122, v196
	v_mul_f32_e32 v133, v123, v196
	v_pk_mul_f32 v[140:141], v[134:135], v[218:219] op_sel:[1,0] op_sel_hi:[0,0]
	v_pk_fma_f32 v[142:143], v[134:135], v[148:149], v[140:141] op_sel_hi:[1,0,1] neg_lo:[0,0,1] neg_hi:[0,0,1]
	v_pk_fma_f32 v[134:135], v[134:135], v[148:149], v[140:141] op_sel_hi:[1,0,1]
	v_pk_mul_f32 v[140:141], v[132:133], v[216:217] op_sel:[1,0] op_sel_hi:[0,0]
	v_pk_fma_f32 v[148:149], v[132:133], v[150:151], v[140:141] op_sel_hi:[1,0,1] neg_lo:[0,0,1] neg_hi:[0,0,1]
	v_pk_fma_f32 v[132:133], v[132:133], v[150:151], v[140:141] op_sel_hi:[1,0,1]
	v_mov_b32_e32 v143, v135
	v_mov_b32_e32 v149, v133
	v_mul_f32_e32 v132, s4, v142
	v_mul_f32_e32 v133, s4, v143
	v_mul_f32_e32 v142, v116, v196
	v_mul_f32_e32 v143, v117, v196
	v_mul_f32_e32 v140, s4, v148
	v_mul_f32_e32 v141, s4, v149
	v_pk_mul_f32 v[148:149], v[142:143], v[204:205] op_sel:[1,0] op_sel_hi:[0,0]
	v_mul_f32_e32 v134, v118, v196
	v_mul_f32_e32 v135, v119, v196
	v_pk_fma_f32 v[150:151], v[142:143], v[136:137], v[148:149] op_sel_hi:[1,0,1] neg_lo:[0,0,1] neg_hi:[0,0,1]
	v_pk_fma_f32 v[136:137], v[142:143], v[136:137], v[148:149] op_sel_hi:[1,0,1]
	v_pk_mul_f32 v[142:143], v[134:135], v[222:223] op_sel:[1,0] op_sel_hi:[0,0]
	v_mov_b32_e32 v151, v137
	v_lshlrev_b64 v[136:137], 10, v[192:193]
	v_pk_fma_f32 v[148:149], v[134:135], v[138:139], v[142:143] op_sel_hi:[1,0,1] neg_lo:[0,0,1] neg_hi:[0,0,1]
	v_pk_fma_f32 v[134:135], v[134:135], v[138:139], v[142:143] op_sel_hi:[1,0,1]
	v_lshl_add_u64 v[136:137], s[94:95], 0, v[136:137]
	v_mov_b32_e32 v149, v135
	v_lshl_add_u64 v[136:137], v[136:137], 0, v[188:189]
	v_mul_f32_e32 v138, s4, v148
	v_mul_f32_e32 v139, s4, v149
	v_mul_f32_e32 v134, s4, v150
	v_mul_f32_e32 v135, s4, v151
	v_add_co_u32_e32 v136, vcc, s0, v136
	v_cvt_pk_bf16_f32 v132, v132, v133
	v_cvt_pk_bf16_f32 v133, v140, v141
	v_cvt_pk_bf16_f32 v134, v134, v135
	v_cvt_pk_bf16_f32 v135, v138, v139
	v_addc_co_u32_e32 v137, vcc, 0, v137, vcc
	global_store_dwordx4 v[136:137], v[132:135], off offset:2048
	v_ashrrev_i32_e32 v201, 31, v200
	s_cmp_eq_u32 s48, 64
	v_mul_f32_e32 v134, v112, v202
	v_mul_f32_e32 v135, v113, v202
	v_mul_f32_e32 v132, v114, v202
	v_mul_f32_e32 v133, v115, v202
	v_pk_mul_f32 v[136:137], v[134:135], v[226:227] op_sel:[1,0] op_sel_hi:[0,0]
	v_pk_fma_f32 v[138:139], v[134:135], v[156:157], v[136:137] op_sel_hi:[1,0,1] neg_lo:[0,0,1] neg_hi:[0,0,1]
	v_pk_fma_f32 v[134:135], v[134:135], v[156:157], v[136:137] op_sel_hi:[1,0,1]
	v_pk_mul_f32 v[136:137], v[132:133], v[224:225] op_sel:[1,0] op_sel_hi:[0,0]
	v_pk_fma_f32 v[140:141], v[132:133], v[158:159], v[136:137] op_sel_hi:[1,0,1] neg_lo:[0,0,1] neg_hi:[0,0,1]
	v_pk_fma_f32 v[132:133], v[132:133], v[158:159], v[136:137] op_sel_hi:[1,0,1]
	v_mov_b32_e32 v139, v135
	v_mov_b32_e32 v141, v133
	v_mul_f32_e32 v132, s4, v138
	v_mul_f32_e32 v133, s4, v139
	v_mul_f32_e32 v138, v108, v202
	v_mul_f32_e32 v139, v109, v202
	v_mul_f32_e32 v136, s4, v140
	v_mul_f32_e32 v137, s4, v141
	v_pk_mul_f32 v[140:141], v[138:139], v[212:213] op_sel:[1,0] op_sel_hi:[0,0]
	v_mul_f32_e32 v134, v110, v202
	v_mul_f32_e32 v135, v111, v202
	v_pk_fma_f32 v[142:143], v[138:139], v[144:145], v[140:141] op_sel_hi:[1,0,1] neg_lo:[0,0,1] neg_hi:[0,0,1]
	v_pk_fma_f32 v[138:139], v[138:139], v[144:145], v[140:141] op_sel_hi:[1,0,1]
	v_pk_mul_f32 v[140:141], v[134:135], v[228:229] op_sel:[1,0] op_sel_hi:[0,0]
	v_mov_b32_e32 v143, v139
	v_lshlrev_b64 v[138:139], 10, v[194:195]
	v_pk_fma_f32 v[144:145], v[134:135], v[146:147], v[140:141] op_sel_hi:[1,0,1] neg_lo:[0,0,1] neg_hi:[0,0,1]
	v_pk_fma_f32 v[134:135], v[134:135], v[146:147], v[140:141] op_sel_hi:[1,0,1]
	v_lshl_add_u64 v[138:139], s[94:95], 0, v[138:139]
	v_mov_b32_e32 v145, v135
	v_lshl_add_u64 v[138:139], v[138:139], 0, v[188:189]
	v_mul_f32_e32 v140, s4, v144
	v_mul_f32_e32 v141, s4, v145
	v_mul_f32_e32 v134, s4, v142
	v_mul_f32_e32 v135, s4, v143
	v_cvt_pk_bf16_f32 v132, v132, v133
	v_cvt_pk_bf16_f32 v133, v136, v137
	v_add_co_u32_e32 v136, vcc, s0, v138
	v_cvt_pk_bf16_f32 v134, v134, v135
	v_cvt_pk_bf16_f32 v135, v140, v141
	v_addc_co_u32_e32 v137, vcc, 0, v139, vcc
	global_store_dwordx4 v[136:137], v[132:135], off offset:2048
	s_nop 1
	v_mul_f32_e32 v134, v104, v208
	v_mul_f32_e32 v135, v105, v208
	v_mul_f32_e32 v132, v106, v208
	v_mul_f32_e32 v133, v107, v208
	v_pk_mul_f32 v[136:137], v[134:135], v[232:233] op_sel:[1,0] op_sel_hi:[0,0]
	v_pk_fma_f32 v[138:139], v[134:135], v[160:161], v[136:137] op_sel_hi:[1,0,1] neg_lo:[0,0,1] neg_hi:[0,0,1]
	v_pk_fma_f32 v[134:135], v[134:135], v[160:161], v[136:137] op_sel_hi:[1,0,1]
	v_pk_mul_f32 v[136:137], v[132:133], v[230:231] op_sel:[1,0] op_sel_hi:[0,0]
	v_pk_fma_f32 v[140:141], v[132:133], v[162:163], v[136:137] op_sel_hi:[1,0,1] neg_lo:[0,0,1] neg_hi:[0,0,1]
	v_pk_fma_f32 v[132:133], v[132:133], v[162:163], v[136:137] op_sel_hi:[1,0,1]
	v_mov_b32_e32 v139, v135
	v_mov_b32_e32 v141, v133
	v_mul_f32_e32 v132, s4, v138
	v_mul_f32_e32 v133, s4, v139
	v_mul_f32_e32 v138, v100, v208
	v_mul_f32_e32 v139, v101, v208
	v_mul_f32_e32 v136, s4, v140
	v_mul_f32_e32 v137, s4, v141
	v_pk_mul_f32 v[140:141], v[138:139], v[220:221] op_sel:[1,0] op_sel_hi:[0,0]
	v_mul_f32_e32 v134, v102, v208
	v_mul_f32_e32 v135, v103, v208
	v_pk_fma_f32 v[142:143], v[138:139], v[152:153], v[140:141] op_sel_hi:[1,0,1] neg_lo:[0,0,1] neg_hi:[0,0,1]
	v_pk_fma_f32 v[138:139], v[138:139], v[152:153], v[140:141] op_sel_hi:[1,0,1]
	v_pk_mul_f32 v[140:141], v[134:135], v[2:3] op_sel:[1,0] op_sel_hi:[0,0]
	v_mov_b32_e32 v143, v139
	v_lshlrev_b64 v[138:139], 10, v[200:201]
	v_pk_fma_f32 v[144:145], v[134:135], v[154:155], v[140:141] op_sel_hi:[1,0,1] neg_lo:[0,0,1] neg_hi:[0,0,1]
	v_pk_fma_f32 v[134:135], v[134:135], v[154:155], v[140:141] op_sel_hi:[1,0,1]
	v_lshl_add_u64 v[138:139], s[94:95], 0, v[138:139]
	v_mov_b32_e32 v145, v135
	v_lshl_add_u64 v[138:139], v[138:139], 0, v[188:189]
	v_mul_f32_e32 v140, s4, v144
	v_mul_f32_e32 v141, s4, v145
	v_mul_f32_e32 v134, s4, v142
	v_mul_f32_e32 v135, s4, v143
	v_cvt_pk_bf16_f32 v132, v132, v133
	v_cvt_pk_bf16_f32 v133, v136, v137
	v_add_co_u32_e32 v136, vcc, 0x847e000, v138
	v_cvt_pk_bf16_f32 v134, v134, v135
	v_cvt_pk_bf16_f32 v135, v140, v141
	v_addc_co_u32_e32 v137, vcc, 0, v139, vcc
	global_store_dwordx4 v[136:137], v[132:135], off offset:2048
	s_cbranch_scc1 .LBB0_147
	v_add_u32_e32 v190, 0x80, v190
	v_ashrrev_i32_e32 v191, 31, v190
	v_lshl_add_u64 v[152:153], v[190:191], 2, s[70:71]
	v_mov_b32_e32 v194, v246
	s_movk_i32 s0, 0x7cf
	v_and_or_b32 v2, v190, s0, 16
	v_cmp_gt_i32_e32 vcc, s20, v190
	v_mov_b32_e32 v200, 0
	v_mov_b32_e32 v132, 1.0
	v_cndmask_b32_e32 v2, v181, v2, vcc
	v_lshlrev_b32_e32 v2, 6, v2
	v_lshl_add_u64 v[136:137], s[84:85], 0, v[2:3]
	v_mov_b32_e32 v140, 1.0
	v_mov_b32_e32 v210, 0
	v_mov_b32_e32 v142, 1.0
	v_mov_b32_e32 v208, 0
	s_and_saveexec_b64 s[0:1], s[38:39]
	s_cbranch_execz .LBB0_132
	v_lshlrev_b32_e32 v2, 2, v170
	v_lshl_add_u64 v[134:135], v[136:137], 0, v[2:3]
	global_load_dwordx4 v[140:143], v[134:135], off

.LBB0_146:
	s_or_b64 exec, exec, s[0:1]
	s_waitcnt vmcnt(0)
	s_and_saveexec_b64 s[0:1], s[38:39]
	v_mov_b32_e32 v210, v141
	v_mov_b32_e32 v208, v143
	v_mov_b32_e32 v200, v133
	v_mov_b32_e32 v216, v135
	v_mov_b32_e32 v220, v149
	v_mov_b32_e32 v218, v151
	v_mov_b32_e32 v206, v137
	v_mov_b32_e32 v224, v139
	v_mov_b32_e32 v228, v157
	v_mov_b32_e32 v226, v159
	v_mov_b32_e32 v214, v145
	v_mov_b32_e32 v230, v147
	v_mov_b32_e32 v234, v161
	v_mov_b32_e32 v232, v163
	v_mov_b32_e32 v222, v153
	v_mov_b32_e32 v2, v155
	s_or_b64 exec, exec, s[0:1]
	v_mul_f32_e32 v168, v98, v194
	v_mul_f32_e32 v169, v99, v194
	v_mul_f32_e32 v236, v96, v194
	v_mul_f32_e32 v237, v97, v194
	v_pk_mul_f32 v[208:209], v[168:169], v[208:209] op_sel:[1,0] op_sel_hi:[0,0]
	v_pk_mul_f32 v[210:211], v[236:237], v[210:211] op_sel:[1,0] op_sel_hi:[0,0]
	v_pk_fma_f32 v[238:239], v[236:237], v[140:141], v[210:211] op_sel_hi:[1,0,1] neg_lo:[0,0,1] neg_hi:[0,0,1]
	v_pk_fma_f32 v[140:141], v[236:237], v[140:141], v[210:211] op_sel_hi:[1,0,1]
	v_pk_fma_f32 v[210:211], v[168:169], v[142:143], v[208:209] op_sel_hi:[1,0,1] neg_lo:[0,0,1] neg_hi:[0,0,1]
	v_pk_fma_f32 v[142:143], v[168:169], v[142:143], v[208:209] op_sel_hi:[1,0,1]
	v_mul_f32_e32 v168, v94, v194
	v_mul_f32_e32 v169, v95, v194
	v_mul_f32_e32 v195, v93, v194
	v_mul_f32_e32 v194, v92, v194
	v_mov_b32_e32 v239, v141
	v_pk_mul_f32 v[200:201], v[194:195], v[200:201] op_sel:[1,0] op_sel_hi:[0,0]
	v_pk_fma_f32 v[208:209], v[194:195], v[132:133], v[200:201] op_sel_hi:[1,0,1] neg_lo:[0,0,1] neg_hi:[0,0,1]
	v_pk_fma_f32 v[132:133], v[194:195], v[132:133], v[200:201] op_sel_hi:[1,0,1]
	v_pk_mul_f32 v[194:195], v[168:169], v[216:217] op_sel:[1,0] op_sel_hi:[0,0]
	v_mov_b32_e32 v209, v133
	v_lshlrev_b64 v[132:133], 10, v[190:191]
	v_pk_fma_f32 v[200:201], v[168:169], v[134:135], v[194:195] op_sel_hi:[1,0,1] neg_lo:[0,0,1] neg_hi:[0,0,1]
	v_pk_fma_f32 v[134:135], v[168:169], v[134:135], v[194:195] op_sel_hi:[1,0,1]
	v_lshl_add_u64 v[132:133], s[94:95], 0, v[132:133]
	v_mov_b32_e32 v211, v143
	v_mul_f32_e32 v140, s4, v238
	v_mul_f32_e32 v141, s4, v239
	v_mov_b32_e32 v201, v135
	v_lshl_add_u64 v[190:191], v[132:133], 0, v[188:189]
	s_mov_b32 s0, 0x847e000
	v_mul_f32_e32 v142, s4, v210
	v_mul_f32_e32 v143, s4, v211
	v_mul_f32_e32 v168, s4, v200
	v_mul_f32_e32 v169, s4, v201
	v_mul_f32_e32 v134, s4, v208
	v_mul_f32_e32 v135, s4, v209
	v_cvt_pk_bf16_f32 v132, v140, v141
	v_add_co_u32_e32 v140, vcc, s0, v190
	v_cvt_pk_bf16_f32 v133, v142, v143
	v_cvt_pk_bf16_f32 v134, v134, v135
	v_cvt_pk_bf16_f32 v135, v168, v169
	v_addc_co_u32_e32 v141, vcc, 0, v191, vcc
	global_store_dwordx4 v[140:141], v[132:135], off offset:2048
	v_ashrrev_i32_e32 v193, 31, v192
	v_ashrrev_i32_e32 v197, 31, v196
	v_mul_f32_e32 v134, v88, v198
	v_mul_f32_e32 v135, v89, v198
	v_mul_f32_e32 v132, v90, v198
	v_mul_f32_e32 v133, v91, v198
	v_pk_mul_f32 v[140:141], v[134:135], v[220:221] op_sel:[1,0] op_sel_hi:[0,0]
	v_pk_fma_f32 v[142:143], v[134:135], v[148:149], v[140:141] op_sel_hi:[1,0,1] neg_lo:[0,0,1] neg_hi:[0,0,1]
	v_pk_fma_f32 v[134:135], v[134:135], v[148:149], v[140:141] op_sel_hi:[1,0,1]
	v_pk_mul_f32 v[140:141], v[132:133], v[218:219] op_sel:[1,0] op_sel_hi:[0,0]
	v_pk_fma_f32 v[148:149], v[132:133], v[150:151], v[140:141] op_sel_hi:[1,0,1] neg_lo:[0,0,1] neg_hi:[0,0,1]
	v_pk_fma_f32 v[132:133], v[132:133], v[150:151], v[140:141] op_sel_hi:[1,0,1]
	v_mov_b32_e32 v143, v135
	v_mov_b32_e32 v149, v133
	v_mul_f32_e32 v132, s4, v142
	v_mul_f32_e32 v133, s4, v143
	v_mul_f32_e32 v142, v84, v198
	v_mul_f32_e32 v143, v85, v198
	v_mul_f32_e32 v140, s4, v148
	v_mul_f32_e32 v141, s4, v149
	v_pk_mul_f32 v[148:149], v[142:143], v[206:207] op_sel:[1,0] op_sel_hi:[0,0]
	v_mul_f32_e32 v134, v86, v198
	v_mul_f32_e32 v135, v87, v198
	v_pk_fma_f32 v[150:151], v[142:143], v[136:137], v[148:149] op_sel_hi:[1,0,1] neg_lo:[0,0,1] neg_hi:[0,0,1]
	v_pk_fma_f32 v[136:137], v[142:143], v[136:137], v[148:149] op_sel_hi:[1,0,1]
	v_pk_mul_f32 v[142:143], v[134:135], v[224:225] op_sel:[1,0] op_sel_hi:[0,0]
	v_mov_b32_e32 v151, v137
	v_lshlrev_b64 v[136:137], 10, v[192:193]
	v_pk_fma_f32 v[148:149], v[134:135], v[138:139], v[142:143] op_sel_hi:[1,0,1] neg_lo:[0,0,1] neg_hi:[0,0,1]
	v_pk_fma_f32 v[134:135], v[134:135], v[138:139], v[142:143] op_sel_hi:[1,0,1]
	v_lshl_add_u64 v[136:137], s[94:95], 0, v[136:137]
	v_mov_b32_e32 v149, v135
	v_lshl_add_u64 v[136:137], v[136:137], 0, v[188:189]
	v_mul_f32_e32 v138, s4, v148
	v_mul_f32_e32 v139, s4, v149
	v_mul_f32_e32 v134, s4, v150
	v_mul_f32_e32 v135, s4, v151
	v_add_co_u32_e32 v136, vcc, s0, v136
	v_cvt_pk_bf16_f32 v132, v132, v133
	v_cvt_pk_bf16_f32 v133, v140, v141
	v_cvt_pk_bf16_f32 v134, v134, v135
	v_cvt_pk_bf16_f32 v135, v138, v139
	v_addc_co_u32_e32 v137, vcc, 0, v137, vcc
	global_store_dwordx4 v[136:137], v[132:135], off offset:2048
	v_ashrrev_i32_e32 v203, 31, v202
	s_nop 0
	v_mul_f32_e32 v134, v80, v204
	v_mul_f32_e32 v135, v81, v204
	v_mul_f32_e32 v132, v82, v204
	v_mul_f32_e32 v133, v83, v204
	v_pk_mul_f32 v[136:137], v[134:135], v[228:229] op_sel:[1,0] op_sel_hi:[0,0]
	v_pk_fma_f32 v[138:139], v[134:135], v[156:157], v[136:137] op_sel_hi:[1,0,1] neg_lo:[0,0,1] neg_hi:[0,0,1]
	v_pk_fma_f32 v[134:135], v[134:135], v[156:157], v[136:137] op_sel_hi:[1,0,1]
	v_pk_mul_f32 v[136:137], v[132:133], v[226:227] op_sel:[1,0] op_sel_hi:[0,0]
	v_pk_fma_f32 v[140:141], v[132:133], v[158:159], v[136:137] op_sel_hi:[1,0,1] neg_lo:[0,0,1] neg_hi:[0,0,1]
	v_pk_fma_f32 v[132:133], v[132:133], v[158:159], v[136:137] op_sel_hi:[1,0,1]
	v_mov_b32_e32 v139, v135
	v_mov_b32_e32 v141, v133
	v_mul_f32_e32 v132, s4, v138
	v_mul_f32_e32 v133, s4, v139
	v_mul_f32_e32 v138, v76, v204
	v_mul_f32_e32 v139, v77, v204
	v_mul_f32_e32 v136, s4, v140
	v_mul_f32_e32 v137, s4, v141
	v_pk_mul_f32 v[140:141], v[138:139], v[214:215] op_sel:[1,0] op_sel_hi:[0,0]
	v_mul_f32_e32 v134, v78, v204
	v_mul_f32_e32 v135, v79, v204
	v_pk_fma_f32 v[142:143], v[138:139], v[144:145], v[140:141] op_sel_hi:[1,0,1] neg_lo:[0,0,1] neg_hi:[0,0,1]
	v_pk_fma_f32 v[138:139], v[138:139], v[144:145], v[140:141] op_sel_hi:[1,0,1]
	v_pk_mul_f32 v[140:141], v[134:135], v[230:231] op_sel:[1,0] op_sel_hi:[0,0]
	v_mov_b32_e32 v143, v139
	v_lshlrev_b64 v[138:139], 10, v[196:197]
	v_pk_fma_f32 v[144:145], v[134:135], v[146:147], v[140:141] op_sel_hi:[1,0,1] neg_lo:[0,0,1] neg_hi:[0,0,1]
	v_pk_fma_f32 v[134:135], v[134:135], v[146:147], v[140:141] op_sel_hi:[1,0,1]
	v_lshl_add_u64 v[138:139], s[94:95], 0, v[138:139]
	v_mov_b32_e32 v145, v135
	v_lshl_add_u64 v[138:139], v[138:139], 0, v[188:189]
	v_mul_f32_e32 v140, s4, v144
	v_mul_f32_e32 v141, s4, v145
	v_mul_f32_e32 v134, s4, v142
	v_mul_f32_e32 v135, s4, v143
	v_cvt_pk_bf16_f32 v132, v132, v133
	v_cvt_pk_bf16_f32 v133, v136, v137
	v_add_co_u32_e32 v136, vcc, s0, v138
	v_cvt_pk_bf16_f32 v134, v134, v135
	v_cvt_pk_bf16_f32 v135, v140, v141
	v_addc_co_u32_e32 v137, vcc, 0, v139, vcc
	global_store_dwordx4 v[136:137], v[132:135], off offset:2048
	s_nop 1
	v_mul_f32_e32 v134, v72, v212
	v_mul_f32_e32 v135, v73, v212
	v_mul_f32_e32 v132, v74, v212
	v_mul_f32_e32 v133, v75, v212
	v_pk_mul_f32 v[136:137], v[134:135], v[234:235] op_sel:[1,0] op_sel_hi:[0,0]
	v_pk_fma_f32 v[138:139], v[134:135], v[160:161], v[136:137] op_sel_hi:[1,0,1] neg_lo:[0,0,1] neg_hi:[0,0,1]
	v_pk_fma_f32 v[134:135], v[134:135], v[160:161], v[136:137] op_sel_hi:[1,0,1]
	v_pk_mul_f32 v[136:137], v[132:133], v[232:233] op_sel:[1,0] op_sel_hi:[0,0]
	v_pk_fma_f32 v[140:141], v[132:133], v[162:163], v[136:137] op_sel_hi:[1,0,1] neg_lo:[0,0,1] neg_hi:[0,0,1]
	v_pk_fma_f32 v[132:133], v[132:133], v[162:163], v[136:137] op_sel_hi:[1,0,1]
	v_mov_b32_e32 v139, v135
	v_mov_b32_e32 v141, v133
	v_mul_f32_e32 v132, s4, v138
	v_mul_f32_e32 v133, s4, v139
	v_mul_f32_e32 v138, v68, v212
	v_mul_f32_e32 v139, v69, v212
	v_mul_f32_e32 v136, s4, v140
	v_mul_f32_e32 v137, s4, v141
	v_pk_mul_f32 v[140:141], v[138:139], v[222:223] op_sel:[1,0] op_sel_hi:[0,0]
	v_mul_f32_e32 v134, v70, v212
	v_mul_f32_e32 v135, v71, v212
	v_pk_fma_f32 v[142:143], v[138:139], v[152:153], v[140:141] op_sel_hi:[1,0,1] neg_lo:[0,0,1] neg_hi:[0,0,1]
	v_pk_fma_f32 v[138:139], v[138:139], v[152:153], v[140:141] op_sel_hi:[1,0,1]
	v_pk_mul_f32 v[140:141], v[134:135], v[2:3] op_sel:[1,0] op_sel_hi:[0,0]
	v_mov_b32_e32 v143, v139
	v_lshlrev_b64 v[138:139], 10, v[202:203]
	v_pk_fma_f32 v[144:145], v[134:135], v[154:155], v[140:141] op_sel_hi:[1,0,1] neg_lo:[0,0,1] neg_hi:[0,0,1]
	v_pk_fma_f32 v[134:135], v[134:135], v[154:155], v[140:141] op_sel_hi:[1,0,1]
	v_lshl_add_u64 v[138:139], s[94:95], 0, v[138:139]
	v_mov_b32_e32 v145, v135
	v_lshl_add_u64 v[138:139], v[138:139], 0, v[188:189]
	v_mul_f32_e32 v140, s4, v144
	v_mul_f32_e32 v141, s4, v145
	v_mul_f32_e32 v134, s4, v142
	v_mul_f32_e32 v135, s4, v143
	v_cvt_pk_bf16_f32 v132, v132, v133
	v_cvt_pk_bf16_f32 v133, v136, v137
	v_add_co_u32_e32 v136, vcc, 0x847e000, v138
	v_cvt_pk_bf16_f32 v134, v134, v135
	v_cvt_pk_bf16_f32 v135, v140, v141
	v_addc_co_u32_e32 v137, vcc, 0, v139, vcc
	global_store_dwordx4 v[136:137], v[132:135], off offset:2048

.LBB0_148:
	s_andn2_b64 vcc, exec, s[0:1]
	s_cbranch_vccnz .LBB0_166
	s_cmp_lt_i32 s2, 2
	s_mov_b64 s[0:1], -1
	s_cbranch_scc1 .LBB0_158
	s_cmp_gt_i32 s2, 2
	s_cbranch_scc0 .LBB0_154
	s_lshl_b32 s0, s48, 8
	v_add_u32_e32 v134, s0, v241
	v_ashrrev_i32_e32 v135, 31, v134
	v_lshl_add_u64 v[146:147], v[134:135], 2, s[70:71]
	v_mov_b32_e32 v148, v164
	v_mov_b32_e32 v144, v165
	v_mov_b32_e32 v140, v166
	v_mov_b32_e32 v2, v167
	v_or_b32_e32 v132, s74, v178
	v_ashrrev_i32_e32 v133, 31, v132
	v_lshlrev_b64 v[132:133], 1, v[132:133]
	s_mov_b32 s0, 0x643f000
	v_or_b32_e32 v142, 16, v134
	v_ashrrev_i32_e32 v143, 31, v142
	v_lshlrev_b64 v[142:143], 11, v[142:143]
	v_lshl_add_u64 v[142:143], s[94:95], 0, v[142:143]
	v_or_b32_e32 v138, 32, v134
	v_ashrrev_i32_e32 v139, 31, v138
	v_lshlrev_b64 v[138:139], 11, v[138:139]
	v_lshl_add_u64 v[138:139], s[94:95], 0, v[138:139]
	v_or_b32_e32 v136, 48, v134
	v_ashrrev_i32_e32 v137, 31, v136
	v_lshlrev_b64 v[136:137], 11, v[136:137]
	v_lshl_add_u64 v[136:137], s[94:95], 0, v[136:137]
	s_cmp_eq_u32 s48, 64
	v_mul_f32_e32 v146, v128, v148
	v_mul_f32_e32 v147, v129, v148
	s_nop 0
	v_mul_f32_e32 v141, 0xbfb8aa3b, v146
	v_exp_f32_e32 v141, v141
	v_mul_f32_e32 v150, v130, v148
	v_mul_f32_e32 v151, v131, v148
	v_add_f32_e32 v141, 1.0, v141
	v_rcp_f32_e32 v152, v141
	v_mul_f32_e32 v141, 0xbfb8aa3b, v147
	v_exp_f32_e32 v141, v141
	s_nop 0
	v_add_f32_e32 v141, 1.0, v141
	v_rcp_f32_e32 v153, v141
	v_mul_f32_e32 v141, 0xbfb8aa3b, v150
	v_exp_f32_e32 v141, v141
	v_mul_f32_e32 v146, v146, v152
	v_mul_f32_e32 v147, v147, v153
	s_nop 0
	v_cvt_pk_bf16_f32 v146, v146, v147
	v_add_f32_e32 v141, 1.0, v141
	v_rcp_f32_e32 v152, v141
	v_mul_f32_e32 v141, 0xbfb8aa3b, v151
	v_exp_f32_e32 v141, v141
	s_nop 0
	v_add_f32_e32 v141, 1.0, v141
	v_rcp_f32_e32 v153, v141
	s_nop 0
	v_mul_f32_e32 v150, v150, v152
	v_mul_f32_e32 v151, v151, v153
	v_mul_f32_e32 v152, v126, v148
	v_mul_f32_e32 v153, v127, v148
	v_mul_f32_e32 v149, v125, v148
	v_mul_f32_e32 v148, v124, v148
	v_cvt_pk_bf16_f32 v147, v150, v151
	v_mul_f32_e32 v141, 0xbfb8aa3b, v148
	v_exp_f32_e32 v141, v141
	s_nop 0
	v_add_f32_e32 v141, 1.0, v141
	v_rcp_f32_e32 v154, v141
	v_mul_f32_e32 v141, 0xbfb8aa3b, v149
	v_exp_f32_e32 v141, v141
	s_nop 0
	v_add_f32_e32 v141, 1.0, v141
	v_rcp_f32_e32 v155, v141
	v_mul_f32_e32 v141, 0xbfb8aa3b, v152
	v_exp_f32_e32 v141, v141
	v_mul_f32_e32 v148, v148, v154
	v_mul_f32_e32 v149, v149, v155
	s_nop 0
	v_cvt_pk_bf16_f32 v148, v148, v149
	v_add_f32_e32 v141, 1.0, v141
	v_rcp_f32_e32 v154, v141
	v_mul_f32_e32 v141, 0xbfb8aa3b, v153
	v_exp_f32_e32 v141, v141
	s_nop 0
	v_add_f32_e32 v141, 1.0, v141
	v_rcp_f32_e32 v155, v141
	s_nop 0
	v_mul_f32_e32 v152, v152, v154
	v_mul_f32_e32 v153, v153, v155
	v_lshlrev_b64 v[154:155], 11, v[134:135]
	v_lshl_add_u64 v[154:155], s[94:95], 0, v[154:155]
	v_lshl_add_u64 v[154:155], v[154:155], 0, v[132:133]
	v_add_co_u32_e32 v150, vcc, s0, v154
	v_cvt_pk_bf16_f32 v149, v152, v153
	s_nop 0
	v_addc_co_u32_e32 v151, vcc, 0, v155, vcc
	global_store_dwordx4 v[150:151], v[146:149], off
	s_nop 1
	v_mul_f32_e32 v146, v120, v144
	v_mul_f32_e32 v147, v121, v144
	v_mul_f32_e32 v148, v122, v144
	v_mul_f32_e32 v149, v123, v144
	v_mul_f32_e32 v135, 0xbfb8aa3b, v146
	v_exp_f32_e32 v135, v135
	s_nop 0
	v_add_f32_e32 v135, 1.0, v135
	v_rcp_f32_e32 v150, v135
	v_mul_f32_e32 v135, 0xbfb8aa3b, v147
	v_exp_f32_e32 v135, v135
	s_nop 0
	v_add_f32_e32 v135, 1.0, v135
	v_rcp_f32_e32 v151, v135
	v_mul_f32_e32 v135, 0xbfb8aa3b, v148
	v_exp_f32_e32 v135, v135
	v_mul_f32_e32 v146, v146, v150
	v_mul_f32_e32 v147, v147, v151
	v_add_f32_e32 v135, 1.0, v135
	v_rcp_f32_e32 v150, v135
	v_mul_f32_e32 v135, 0xbfb8aa3b, v149
	v_exp_f32_e32 v135, v135
	s_nop 0
	v_add_f32_e32 v135, 1.0, v135
	v_rcp_f32_e32 v151, v135
	s_nop 0
	v_mul_f32_e32 v148, v148, v150
	v_mul_f32_e32 v149, v149, v151
	v_mul_f32_e32 v150, v118, v144
	v_mul_f32_e32 v151, v119, v144
	v_mul_f32_e32 v145, v117, v144
	v_mul_f32_e32 v144, v116, v144
	s_nop 0
	v_mul_f32_e32 v135, 0xbfb8aa3b, v144
	v_exp_f32_e32 v135, v135
	s_nop 0
	v_add_f32_e32 v135, 1.0, v135
	v_rcp_f32_e32 v152, v135
	v_mul_f32_e32 v135, 0xbfb8aa3b, v145
	v_exp_f32_e32 v135, v135
	s_nop 0
	v_add_f32_e32 v135, 1.0, v135
	v_rcp_f32_e32 v153, v135
	v_mul_f32_e32 v135, 0xbfb8aa3b, v150
	v_exp_f32_e32 v135, v135
	v_mul_f32_e32 v144, v144, v152
	v_mul_f32_e32 v145, v145, v153
	s_nop 0
	v_cvt_pk_bf16_f32 v144, v144, v145
	v_add_f32_e32 v135, 1.0, v135
	v_rcp_f32_e32 v152, v135
	v_mul_f32_e32 v135, 0xbfb8aa3b, v151
	v_exp_f32_e32 v135, v135
	s_nop 0
	v_add_f32_e32 v135, 1.0, v135
	v_rcp_f32_e32 v153, v135
	s_nop 0
	v_mul_f32_e32 v150, v150, v152
	v_mul_f32_e32 v151, v151, v153
	v_lshl_add_u64 v[152:153], v[142:143], 0, v[132:133]
	v_cvt_pk_bf16_f32 v142, v146, v147
	v_add_co_u32_e32 v146, vcc, s0, v152
	v_cvt_pk_bf16_f32 v143, v148, v149
	v_cvt_pk_bf16_f32 v145, v150, v151
	v_addc_co_u32_e32 v147, vcc, 0, v153, vcc
	global_store_dwordx4 v[146:147], v[142:145], off
	s_nop 1
	v_mul_f32_e32 v144, v112, v140
	v_mul_f32_e32 v145, v113, v140
	v_mul_f32_e32 v142, v114, v140
	v_mul_f32_e32 v143, v115, v140
	v_mul_f32_e32 v135, 0xbfb8aa3b, v144
	v_exp_f32_e32 v135, v135
	s_nop 0
	v_add_f32_e32 v135, 1.0, v135
	v_rcp_f32_e32 v146, v135
	v_mul_f32_e32 v135, 0xbfb8aa3b, v145
	v_exp_f32_e32 v135, v135
	s_nop 0
	v_add_f32_e32 v135, 1.0, v135
	v_rcp_f32_e32 v147, v135
	v_mul_f32_e32 v135, 0xbfb8aa3b, v142
	v_exp_f32_e32 v135, v135
	v_mul_f32_e32 v144, v144, v146
	v_mul_f32_e32 v145, v145, v147
	v_add_f32_e32 v135, 1.0, v135
	v_rcp_f32_e32 v146, v135
	v_mul_f32_e32 v135, 0xbfb8aa3b, v143
	v_exp_f32_e32 v135, v135
	s_nop 0
	v_add_f32_e32 v135, 1.0, v135
	v_rcp_f32_e32 v147, v135
	s_nop 0
	v_mul_f32_e32 v142, v142, v146
	v_mul_f32_e32 v143, v143, v147
	v_mul_f32_e32 v146, v110, v140
	v_mul_f32_e32 v147, v111, v140
	v_mul_f32_e32 v141, v109, v140
	v_mul_f32_e32 v140, v108, v140
	s_nop 0
	v_mul_f32_e32 v135, 0xbfb8aa3b, v140
	v_exp_f32_e32 v135, v135
	s_nop 0
	v_add_f32_e32 v135, 1.0, v135
	v_rcp_f32_e32 v148, v135
	v_mul_f32_e32 v135, 0xbfb8aa3b, v141
	v_exp_f32_e32 v135, v135
	s_nop 0
	v_add_f32_e32 v135, 1.0, v135
	v_rcp_f32_e32 v149, v135
	v_mul_f32_e32 v135, 0xbfb8aa3b, v146
	v_exp_f32_e32 v135, v135
	v_mul_f32_e32 v140, v140, v148
	v_mul_f32_e32 v141, v141, v149
	s_nop 0
	v_cvt_pk_bf16_f32 v140, v140, v141
	v_add_f32_e32 v135, 1.0, v135
	v_rcp_f32_e32 v148, v135
	v_mul_f32_e32 v135, 0xbfb8aa3b, v147
	v_exp_f32_e32 v135, v135
	s_nop 0
	v_add_f32_e32 v135, 1.0, v135
	v_rcp_f32_e32 v149, v135
	s_nop 0
	v_mul_f32_e32 v146, v146, v148
	v_mul_f32_e32 v147, v147, v149
	v_lshl_add_u64 v[148:149], v[138:139], 0, v[132:133]
	v_cvt_pk_bf16_f32 v139, v142, v143
	v_add_co_u32_e32 v142, vcc, s0, v148
	v_cvt_pk_bf16_f32 v138, v144, v145
	v_cvt_pk_bf16_f32 v141, v146, v147
	v_addc_co_u32_e32 v143, vcc, 0, v149, vcc
	global_store_dwordx4 v[142:143], v[138:141], off
	v_mul_f32_e32 v144, v100, v2
	v_mul_f32_e32 v145, v101, v2
	s_nop 0
	v_mul_f32_e32 v140, v104, v2
	v_mul_f32_e32 v141, v105, v2
	v_mul_f32_e32 v138, v106, v2
	v_mul_f32_e32 v139, v107, v2
	v_mul_f32_e32 v135, 0xbfb8aa3b, v140
	v_exp_f32_e32 v135, v135
	s_nop 0
	v_add_f32_e32 v135, 1.0, v135
	v_rcp_f32_e32 v142, v135
	v_mul_f32_e32 v135, 0xbfb8aa3b, v141
	v_exp_f32_e32 v135, v135
	s_nop 0
	v_add_f32_e32 v135, 1.0, v135
	v_rcp_f32_e32 v143, v135
	v_mul_f32_e32 v135, 0xbfb8aa3b, v138
	v_exp_f32_e32 v135, v135
	v_mul_f32_e32 v140, v140, v142
	v_mul_f32_e32 v141, v141, v143
	v_add_f32_e32 v135, 1.0, v135
	v_rcp_f32_e32 v142, v135
	v_mul_f32_e32 v135, 0xbfb8aa3b, v139
	v_exp_f32_e32 v135, v135
	s_nop 0
	v_add_f32_e32 v135, 1.0, v135
	v_rcp_f32_e32 v143, v135
	s_nop 0
	v_mul_f32_e32 v138, v138, v142
	v_mul_f32_e32 v139, v139, v143
	v_mul_f32_e32 v142, v102, v2
	v_mul_f32_e32 v143, v103, v2
	v_mul_f32_e32 v2, 0xbfb8aa3b, v144
	v_exp_f32_e32 v2, v2
	s_nop 0
	v_add_f32_e32 v2, 1.0, v2
	v_rcp_f32_e32 v146, v2
	v_mul_f32_e32 v2, 0xbfb8aa3b, v145
	v_exp_f32_e32 v2, v2
	s_nop 0
	v_add_f32_e32 v2, 1.0, v2
	v_rcp_f32_e32 v147, v2
	v_mul_f32_e32 v2, 0xbfb8aa3b, v142
	v_exp_f32_e32 v2, v2
	v_mul_f32_e32 v144, v144, v146
	v_mul_f32_e32 v145, v145, v147
	v_add_f32_e32 v2, 1.0, v2
	v_rcp_f32_e32 v146, v2
	v_mul_f32_e32 v2, 0xbfb8aa3b, v143
	v_exp_f32_e32 v2, v2
	s_nop 0
	v_add_f32_e32 v2, 1.0, v2
	v_rcp_f32_e32 v147, v2
	s_nop 0
	v_mul_f32_e32 v142, v142, v146
	v_mul_f32_e32 v143, v143, v147
	v_lshl_add_u64 v[146:147], v[136:137], 0, v[132:133]
	v_cvt_pk_bf16_f32 v136, v140, v141
	v_add_co_u32_e32 v140, vcc, 0x643f000, v146
	v_cvt_pk_bf16_f32 v137, v138, v139
	v_cvt_pk_bf16_f32 v138, v144, v145
	v_cvt_pk_bf16_f32 v139, v142, v143
	v_addc_co_u32_e32 v141, vcc, 0, v147, vcc
	global_store_dwordx4 v[140:141], v[136:139], off
	s_cbranch_scc1 .LBB0_153
	v_add_u32_e32 v142, 0x80, v134
	v_ashrrev_i32_e32 v143, 31, v142
	v_lshl_add_u64 v[144:145], v[142:143], 2, s[70:71]
	v_mov_b32_e32 v148, v246
	v_mov_b32_e32 v146, v247
	v_mov_b32_e32 v138, v248
	v_mov_b32_e32 v2, v249
	v_lshlrev_b64 v[142:143], 11, v[142:143]
	v_lshl_add_u64 v[142:143], s[94:95], 0, v[142:143]
	v_add_u32_e32 v140, 0x90, v134
	v_ashrrev_i32_e32 v141, 31, v140
	v_lshlrev_b64 v[140:141], 11, v[140:141]
	v_lshl_add_u64 v[140:141], s[94:95], 0, v[140:141]
	v_add_u32_e32 v136, 0xa0, v134
	v_ashrrev_i32_e32 v137, 31, v136
	v_lshlrev_b64 v[136:137], 11, v[136:137]
	v_lshl_add_u64 v[136:137], s[94:95], 0, v[136:137]
	v_add_u32_e32 v134, 0xb0, v134
	v_ashrrev_i32_e32 v135, 31, v134
	v_lshlrev_b64 v[134:135], 11, v[134:135]
	v_lshl_add_u64 v[134:135], s[94:95], 0, v[134:135]
	v_mul_f32_e32 v150, v96, v148
	v_mul_f32_e32 v151, v97, v148
	s_nop 0
	v_mul_f32_e32 v139, 0xbfb8aa3b, v150
	v_exp_f32_e32 v139, v139
	v_mul_f32_e32 v144, v98, v148
	v_mul_f32_e32 v145, v99, v148
	v_add_f32_e32 v139, 1.0, v139
	v_rcp_f32_e32 v152, v139
	v_mul_f32_e32 v139, 0xbfb8aa3b, v151
	v_exp_f32_e32 v139, v139
	s_nop 0
	v_add_f32_e32 v139, 1.0, v139
	v_rcp_f32_e32 v153, v139
	v_mul_f32_e32 v139, 0xbfb8aa3b, v144
	v_exp_f32_e32 v139, v139
	v_mul_f32_e32 v150, v150, v152
	v_mul_f32_e32 v151, v151, v153
	v_add_f32_e32 v139, 1.0, v139
	v_rcp_f32_e32 v152, v139
	v_mul_f32_e32 v139, 0xbfb8aa3b, v145
	v_exp_f32_e32 v139, v139
	s_nop 0
	v_add_f32_e32 v139, 1.0, v139
	v_rcp_f32_e32 v153, v139
	s_nop 0
	v_mul_f32_e32 v144, v144, v152
	v_mul_f32_e32 v145, v145, v153
	v_mul_f32_e32 v152, v94, v148
	v_mul_f32_e32 v153, v95, v148
	v_mul_f32_e32 v149, v93, v148
	v_mul_f32_e32 v148, v92, v148
	s_nop 0
	v_mul_f32_e32 v139, 0xbfb8aa3b, v148
	v_exp_f32_e32 v139, v139
	s_nop 0
	v_add_f32_e32 v139, 1.0, v139
	v_rcp_f32_e32 v154, v139
	v_mul_f32_e32 v139, 0xbfb8aa3b, v149
	v_exp_f32_e32 v139, v139
	s_nop 0
	v_add_f32_e32 v139, 1.0, v139
	v_rcp_f32_e32 v155, v139
	v_mul_f32_e32 v139, 0xbfb8aa3b, v152
	v_exp_f32_e32 v139, v139
	v_mul_f32_e32 v148, v148, v154
	v_mul_f32_e32 v149, v149, v155
	v_add_f32_e32 v139, 1.0, v139
	v_rcp_f32_e32 v154, v139
	v_mul_f32_e32 v139, 0xbfb8aa3b, v153
	v_exp_f32_e32 v139, v139
	s_nop 0
	v_add_f32_e32 v139, 1.0, v139
	v_rcp_f32_e32 v155, v139
	s_nop 0
	v_mul_f32_e32 v152, v152, v154
	v_mul_f32_e32 v153, v153, v155
	v_lshl_add_u64 v[154:155], v[142:143], 0, v[132:133]
	v_cvt_pk_bf16_f32 v143, v144, v145
	v_cvt_pk_bf16_f32 v144, v148, v149
	v_add_co_u32_e32 v148, vcc, s0, v154
	v_cvt_pk_bf16_f32 v142, v150, v151
	v_cvt_pk_bf16_f32 v145, v152, v153
	v_addc_co_u32_e32 v149, vcc, 0, v155, vcc
	global_store_dwordx4 v[148:149], v[142:145], off
	s_nop 1
	v_mul_f32_e32 v142, v88, v146
	v_mul_f32_e32 v143, v89, v146
	v_mul_f32_e32 v144, v90, v146
	v_mul_f32_e32 v145, v91, v146
	v_mul_f32_e32 v139, 0xbfb8aa3b, v142
	v_exp_f32_e32 v139, v139
	s_nop 0
	v_add_f32_e32 v139, 1.0, v139
	v_rcp_f32_e32 v148, v139
	v_mul_f32_e32 v139, 0xbfb8aa3b, v143
	v_exp_f32_e32 v139, v139
	s_nop 0
	v_add_f32_e32 v139, 1.0, v139
	v_rcp_f32_e32 v149, v139
	v_mul_f32_e32 v139, 0xbfb8aa3b, v144
	v_exp_f32_e32 v139, v139
	v_mul_f32_e32 v142, v142, v148
	v_mul_f32_e32 v143, v143, v149
	v_add_f32_e32 v139, 1.0, v139
	v_rcp_f32_e32 v148, v139
	v_mul_f32_e32 v139, 0xbfb8aa3b, v145
	v_exp_f32_e32 v139, v139
	s_nop 0
	v_add_f32_e32 v139, 1.0, v139
	v_rcp_f32_e32 v149, v139
	s_nop 0
	v_mul_f32_e32 v144, v144, v148
	v_mul_f32_e32 v145, v145, v149
	v_mul_f32_e32 v148, v86, v146
	v_mul_f32_e32 v149, v87, v146
	v_mul_f32_e32 v147, v85, v146
	v_mul_f32_e32 v146, v84, v146
	s_nop 0
	v_mul_f32_e32 v139, 0xbfb8aa3b, v146
	v_exp_f32_e32 v139, v139
	s_nop 0
	v_add_f32_e32 v139, 1.0, v139
	v_rcp_f32_e32 v150, v139
	v_mul_f32_e32 v139, 0xbfb8aa3b, v147
	v_exp_f32_e32 v139, v139
	s_nop 0
	v_add_f32_e32 v139, 1.0, v139
	v_rcp_f32_e32 v151, v139
	v_mul_f32_e32 v139, 0xbfb8aa3b, v148
	v_exp_f32_e32 v139, v139
	v_mul_f32_e32 v146, v146, v150
	v_mul_f32_e32 v147, v147, v151
	v_add_f32_e32 v139, 1.0, v139
	v_rcp_f32_e32 v150, v139
	v_mul_f32_e32 v139, 0xbfb8aa3b, v149
	v_exp_f32_e32 v139, v139
	s_nop 0
	v_add_f32_e32 v139, 1.0, v139
	v_rcp_f32_e32 v151, v139
	s_nop 0
	v_mul_f32_e32 v148, v148, v150
	v_mul_f32_e32 v149, v149, v151
	v_lshl_add_u64 v[150:151], v[140:141], 0, v[132:133]
	v_cvt_pk_bf16_f32 v141, v144, v145
	v_add_co_u32_e32 v144, vcc, s0, v150
	v_cvt_pk_bf16_f32 v140, v142, v143
	v_cvt_pk_bf16_f32 v142, v146, v147
	v_cvt_pk_bf16_f32 v143, v148, v149
	v_addc_co_u32_e32 v145, vcc, 0, v151, vcc
	global_store_dwordx4 v[144:145], v[140:143], off
	s_nop 1
	v_mul_f32_e32 v142, v80, v138
	v_mul_f32_e32 v143, v81, v138
	v_mul_f32_e32 v140, v82, v138
	v_mul_f32_e32 v141, v83, v138
	v_mul_f32_e32 v139, 0xbfb8aa3b, v142
	v_exp_f32_e32 v139, v139
	s_nop 0
	v_add_f32_e32 v139, 1.0, v139
	v_rcp_f32_e32 v144, v139
	v_mul_f32_e32 v139, 0xbfb8aa3b, v143
	v_exp_f32_e32 v139, v139
	s_nop 0
	v_add_f32_e32 v139, 1.0, v139
	v_rcp_f32_e32 v145, v139
	v_mul_f32_e32 v139, 0xbfb8aa3b, v140
	v_exp_f32_e32 v139, v139
	v_mul_f32_e32 v142, v142, v144
	v_mul_f32_e32 v143, v143, v145
	v_add_f32_e32 v139, 1.0, v139
	v_rcp_f32_e32 v144, v139
	v_mul_f32_e32 v139, 0xbfb8aa3b, v141
	v_exp_f32_e32 v139, v139
	s_nop 0
	v_add_f32_e32 v139, 1.0, v139
	v_rcp_f32_e32 v145, v139
	s_nop 0
	v_mul_f32_e32 v140, v140, v144
	v_mul_f32_e32 v141, v141, v145
	v_mul_f32_e32 v144, v78, v138
	v_mul_f32_e32 v145, v79, v138
	v_mul_f32_e32 v139, v77, v138
	v_mul_f32_e32 v138, v76, v138
	s_nop 0
	v_mul_f32_e32 v146, 0xbfb8aa3b, v138
	v_mul_f32_e32 v147, 0xbfb8aa3b, v139
	v_exp_f32_e32 v146, v146
	v_exp_f32_e32 v147, v147
	v_add_f32_e32 v146, 1.0, v146
	v_add_f32_e32 v147, 1.0, v147
	v_rcp_f32_e32 v146, v146
	v_rcp_f32_e32 v147, v147
	s_nop 0
	v_mul_f32_e32 v138, v138, v146
	v_mul_f32_e32 v139, v139, v147
	v_mul_f32_e32 v146, 0xbfb8aa3b, v144
	v_mul_f32_e32 v147, 0xbfb8aa3b, v145
	v_exp_f32_e32 v146, v146
	v_exp_f32_e32 v147, v147
	v_cvt_pk_bf16_f32 v138, v138, v139
	v_add_f32_e32 v146, 1.0, v146
	v_add_f32_e32 v147, 1.0, v147
	v_rcp_f32_e32 v146, v146
	v_rcp_f32_e32 v147, v147
	s_nop 0
	v_mul_f32_e32 v144, v144, v146
	v_mul_f32_e32 v145, v145, v147
	v_lshl_add_u64 v[146:147], v[136:137], 0, v[132:133]
	v_cvt_pk_bf16_f32 v137, v140, v141
	v_add_co_u32_e32 v140, vcc, s0, v146
	v_cvt_pk_bf16_f32 v136, v142, v143
	v_cvt_pk_bf16_f32 v139, v144, v145
	v_addc_co_u32_e32 v141, vcc, 0, v147, vcc
	global_store_dwordx4 v[140:141], v[136:139], off
	v_mul_f32_e32 v142, v68, v2
	v_mul_f32_e32 v143, v69, v2
	s_nop 0
	v_mul_f32_e32 v138, v72, v2
	v_mul_f32_e32 v139, v73, v2
	v_mul_f32_e32 v136, v74, v2
	v_mul_f32_e32 v137, v75, v2
	v_mul_f32_e32 v140, 0xbfb8aa3b, v138
	v_mul_f32_e32 v141, 0xbfb8aa3b, v139
	v_exp_f32_e32 v140, v140
	v_exp_f32_e32 v141, v141
	v_add_f32_e32 v140, 1.0, v140
	v_add_f32_e32 v141, 1.0, v141
	v_rcp_f32_e32 v140, v140
	v_rcp_f32_e32 v141, v141
	s_nop 0
	v_mul_f32_e32 v138, v138, v140
	v_mul_f32_e32 v139, v139, v141
	v_mul_f32_e32 v140, 0xbfb8aa3b, v136
	v_mul_f32_e32 v141, 0xbfb8aa3b, v137
	v_exp_f32_e32 v140, v140
	v_exp_f32_e32 v141, v141
	v_add_f32_e32 v140, 1.0, v140
	v_add_f32_e32 v141, 1.0, v141
	v_rcp_f32_e32 v140, v140
	v_rcp_f32_e32 v141, v141
	s_nop 0
	v_mul_f32_e32 v136, v136, v140
	v_mul_f32_e32 v137, v137, v141
	v_mul_f32_e32 v140, v70, v2
	v_mul_f32_e32 v141, v71, v2
	v_mul_f32_e32 v2, 0xbfb8aa3b, v142
	v_exp_f32_e32 v2, v2
	s_nop 0
	v_add_f32_e32 v2, 1.0, v2
	v_rcp_f32_e32 v144, v2
	v_mul_f32_e32 v2, 0xbfb8aa3b, v143
	v_exp_f32_e32 v2, v2
	s_nop 0
	v_add_f32_e32 v2, 1.0, v2
	v_rcp_f32_e32 v145, v2
	v_mul_f32_e32 v2, 0xbfb8aa3b, v140
	v_exp_f32_e32 v2, v2
	v_mul_f32_e32 v142, v142, v144
	v_mul_f32_e32 v143, v143, v145
	v_add_f32_e32 v2, 1.0, v2
	v_rcp_f32_e32 v144, v2
	v_mul_f32_e32 v2, 0xbfb8aa3b, v141
	v_exp_f32_e32 v2, v2
	s_nop 0
	v_add_f32_e32 v2, 1.0, v2
	v_rcp_f32_e32 v145, v2
	s_nop 0
	v_mul_f32_e32 v140, v140, v144
	v_mul_f32_e32 v141, v141, v145
	v_lshl_add_u64 v[144:145], v[134:135], 0, v[132:133]
	v_cvt_pk_bf16_f32 v133, v136, v137
	v_add_co_u32_e32 v136, vcc, 0x643f000, v144
	v_cvt_pk_bf16_f32 v132, v138, v139
	v_cvt_pk_bf16_f32 v134, v142, v143
	v_cvt_pk_bf16_f32 v135, v140, v141
	v_addc_co_u32_e32 v137, vcc, 0, v145, vcc
	global_store_dwordx4 v[136:137], v[132:135], off

.LBB0_163:
	s_andn2_b64 vcc, exec, s[0:1]
	s_cbranch_vccnz .LBB0_166
	s_lshl_b32 s0, s48, 8
	v_add_u32_e32 v156, s0, v241
	s_movk_i32 s0, 0x7cf
	v_cmp_gt_i32_e32 vcc, s20, v156
	v_and_or_b32 v2, v156, s0, 16
	v_ashrrev_i32_e32 v157, 31, v156
	v_cndmask_b32_e32 v2, v181, v2, vcc
	v_lshl_add_u64 v[140:141], v[156:157], 2, s[70:71]
	v_lshlrev_b32_e32 v2, 8, v2
	v_mov_b32_e32 v204, v164
	v_lshl_add_u64 v[132:133], v[182:183], 0, v[2:3]
	global_load_dwordx4 v[196:199], v[132:133], off offset:16
	global_load_dwordx4 v[200:203], v[132:133], off
	s_movk_i32 s0, 0x7df
	v_or_b32_e32 v158, 16, v156
	v_bitop3_b32 v2, v156, s0, 16 bitop3:0xc8
	v_cmp_gt_i32_e32 vcc, s20, v158
	v_add_u32_e32 v2, 16, v2
	v_mov_b32_e32 v188, v165
	v_cndmask_b32_e32 v2, v181, v2, vcc
	v_lshlrev_b32_e32 v2, 8, v2
	v_lshl_add_u64 v[132:133], v[182:183], 0, v[2:3]
	global_load_dwordx4 v[144:147], v[132:133], off offset:16
	global_load_dwordx4 v[152:155], v[132:133], off
	v_or_b32_e32 v160, 32, v156
	s_movk_i32 s0, 0x7ef
	v_cmp_gt_i32_e32 vcc, s20, v160
	v_and_or_b32 v2, v160, s0, 16
	v_mov_b32_e32 v190, v166
	v_cndmask_b32_e32 v2, v181, v2, vcc
	v_lshlrev_b32_e32 v2, 8, v2
	v_lshl_add_u64 v[136:137], v[182:183], 0, v[2:3]
	global_load_dwordx4 v[132:135], v[136:137], off offset:16
	s_nop 0
	global_load_dwordx4 v[136:139], v[136:137], off
	s_movk_i32 s0, 0x7ff
	v_or_b32_e32 v162, 48, v156
	v_bitop3_b32 v2, v156, s0, 48 bitop3:0xc8
	v_cmp_gt_i32_e32 vcc, s20, v162
	v_add_u32_e32 v2, 16, v2
	v_mov_b32_e32 v192, v167
	v_cndmask_b32_e32 v2, v181, v2, vcc
	v_lshlrev_b32_e32 v2, 8, v2
	v_lshl_add_u64 v[148:149], v[182:183], 0, v[2:3]
	global_load_dwordx4 v[140:143], v[148:149], off offset:16
	s_nop 0
	global_load_dwordx4 v[148:151], v[148:149], off
	v_or_b32_e32 v194, s74, v178
	v_ashrrev_i32_e32 v195, 31, v194
	s_mov_b32 s0, 0x3e000000
	v_ashrrev_i32_e32 v159, 31, v158
	v_ashrrev_i32_e32 v161, 31, v160
	v_ashrrev_i32_e32 v163, 31, v162
	s_cmp_eq_u32 s48, 64
	s_waitcnt vmcnt(0)
	v_mul_f32_e32 v128, v128, v204
	v_mul_f32_e32 v129, v129, v204
	v_mul_f32_e32 v130, v130, v204
	v_mul_f32_e32 v131, v131, v204
	v_pk_mul_f32 v[206:207], v[200:201], v[128:129] op_sel:[1,1] op_sel_hi:[1,0]
	v_mov_b32_e32 v2, v203
	v_pk_fma_f32 v[208:209], v[200:201], v[128:129], v[206:207] op_sel_hi:[0,1,1] neg_lo:[0,0,1] neg_hi:[0,0,1]
	v_pk_fma_f32 v[128:129], v[200:201], v[128:129], v[206:207] op_sel_hi:[0,1,1]
	v_pk_mul_f32 v[200:201], v[2:3], v[130:131] op_sel:[0,1] op_sel_hi:[0,0]
	v_mul_f32_e32 v124, v124, v204
	v_mul_f32_e32 v125, v125, v204
	v_pk_fma_f32 v[206:207], v[202:203], v[130:131], v[200:201] op_sel_hi:[0,1,1] neg_lo:[0,0,1] neg_hi:[0,0,1]
	v_pk_fma_f32 v[130:131], v[202:203], v[130:131], v[200:201] op_sel_hi:[0,1,1]
	v_mul_f32_e32 v126, v126, v204
	v_mul_f32_e32 v127, v127, v204
	v_pk_mul_f32 v[200:201], v[196:197], v[124:125] op_sel:[1,1] op_sel_hi:[1,0]
	v_mov_b32_e32 v2, v199
	v_pk_fma_f32 v[202:203], v[196:197], v[124:125], v[200:201] op_sel_hi:[0,1,1] neg_lo:[0,0,1] neg_hi:[0,0,1]
	v_pk_fma_f32 v[124:125], v[196:197], v[124:125], v[200:201] op_sel_hi:[0,1,1]
	v_pk_mul_f32 v[196:197], v[2:3], v[126:127] op_sel:[0,1] op_sel_hi:[0,0]
	v_pk_fma_f32 v[200:201], v[198:199], v[126:127], v[196:197] op_sel_hi:[0,1,1] neg_lo:[0,0,1] neg_hi:[0,0,1]
	v_pk_fma_f32 v[126:127], v[198:199], v[126:127], v[196:197] op_sel_hi:[0,1,1]
	v_mov_b32_e32 v207, v131
	v_mov_b32_e32 v209, v129
	v_mov_b32_e32 v201, v127
	v_mov_b32_e32 v203, v125
	v_lshlrev_b64 v[124:125], 10, v[156:157]
	v_mul_f32_e32 v130, s0, v206
	v_mul_f32_e32 v131, s0, v207
	v_mul_f32_e32 v128, s0, v208
	v_mul_f32_e32 v129, s0, v209
	v_mul_f32_e32 v196, s0, v200
	v_mul_f32_e32 v197, s0, v201
	v_mul_f32_e32 v198, s0, v202
	v_mul_f32_e32 v199, s0, v203
	v_lshl_add_u64 v[126:127], s[94:95], 0, v[124:125]
	v_lshlrev_b64 v[124:125], 1, v[194:195]
	v_lshl_add_u64 v[194:195], v[126:127], 0, v[124:125]
	v_cvt_pk_bf16_f32 v126, v128, v129
	v_cvt_pk_bf16_f32 v127, v130, v131
	v_cvt_pk_bf16_f32 v128, v198, v199
	v_cvt_pk_bf16_f32 v129, v196, v197
	v_mul_f32_e32 v120, v120, v188
	v_mul_f32_e32 v121, v121, v188
	global_store_dwordx4 v[194:195], v[126:129], off
	v_mul_f32_e32 v122, v122, v188
	v_mul_f32_e32 v123, v123, v188
	v_mov_b32_e32 v2, v155
	v_pk_mul_f32 v[126:127], v[152:153], v[120:121] op_sel:[1,1] op_sel_hi:[1,0]
	v_mul_f32_e32 v116, v116, v188
	v_mul_f32_e32 v117, v117, v188
	v_pk_fma_f32 v[128:129], v[152:153], v[120:121], v[126:127] op_sel_hi:[0,1,1] neg_lo:[0,0,1] neg_hi:[0,0,1]
	v_pk_fma_f32 v[120:121], v[152:153], v[120:121], v[126:127] op_sel_hi:[0,1,1]
	v_pk_mul_f32 v[126:127], v[2:3], v[122:123] op_sel:[0,1] op_sel_hi:[0,0]
	v_pk_fma_f32 v[130:131], v[154:155], v[122:123], v[126:127] op_sel_hi:[0,1,1] neg_lo:[0,0,1] neg_hi:[0,0,1]
	v_pk_fma_f32 v[122:123], v[154:155], v[122:123], v[126:127] op_sel_hi:[0,1,1]
	v_mov_b32_e32 v129, v121
	v_mul_f32_e32 v118, v118, v188
	v_mul_f32_e32 v119, v119, v188
	v_pk_mul_f32 v[126:127], v[144:145], v[116:117] op_sel:[1,1] op_sel_hi:[1,0]
	v_mov_b32_e32 v2, v147
	v_mov_b32_e32 v131, v123
	v_mul_f32_e32 v120, s0, v128
	v_mul_f32_e32 v121, s0, v129
	v_pk_fma_f32 v[128:129], v[144:145], v[116:117], v[126:127] op_sel_hi:[0,1,1] neg_lo:[0,0,1] neg_hi:[0,0,1]
	v_pk_fma_f32 v[116:117], v[144:145], v[116:117], v[126:127] op_sel_hi:[0,1,1]
	v_pk_mul_f32 v[126:127], v[2:3], v[118:119] op_sel:[0,1] op_sel_hi:[0,0]
	v_mul_f32_e32 v122, s0, v130
	v_mul_f32_e32 v123, s0, v131
	v_pk_fma_f32 v[130:131], v[146:147], v[118:119], v[126:127] op_sel_hi:[0,1,1] neg_lo:[0,0,1] neg_hi:[0,0,1]
	v_pk_fma_f32 v[118:119], v[146:147], v[118:119], v[126:127] op_sel_hi:[0,1,1]
	v_mov_b32_e32 v131, v119
	v_mov_b32_e32 v129, v117
	v_lshlrev_b64 v[116:117], 10, v[158:159]
	v_mul_f32_e32 v126, s0, v130
	v_mul_f32_e32 v127, s0, v131
	v_mul_f32_e32 v118, s0, v128
	v_mul_f32_e32 v119, s0, v129
	v_lshl_add_u64 v[116:117], s[94:95], 0, v[116:117]
	v_lshl_add_u64 v[128:129], v[116:117], 0, v[124:125]
	v_cvt_pk_bf16_f32 v116, v120, v121
	v_cvt_pk_bf16_f32 v117, v122, v123
	v_cvt_pk_bf16_f32 v118, v118, v119
	v_cvt_pk_bf16_f32 v119, v126, v127
	v_mul_f32_e32 v112, v112, v190
	v_mul_f32_e32 v113, v113, v190
	global_store_dwordx4 v[128:129], v[116:119], off
	v_mul_f32_e32 v114, v114, v190
	v_mul_f32_e32 v115, v115, v190
	v_mov_b32_e32 v2, v139
	v_pk_mul_f32 v[116:117], v[136:137], v[112:113] op_sel:[1,1] op_sel_hi:[1,0]
	v_mul_f32_e32 v108, v108, v190
	v_mul_f32_e32 v109, v109, v190
	v_pk_fma_f32 v[118:119], v[136:137], v[112:113], v[116:117] op_sel_hi:[0,1,1] neg_lo:[0,0,1] neg_hi:[0,0,1]
	v_pk_fma_f32 v[112:113], v[136:137], v[112:113], v[116:117] op_sel_hi:[0,1,1]
	v_pk_mul_f32 v[116:117], v[2:3], v[114:115] op_sel:[0,1] op_sel_hi:[0,0]
	v_pk_fma_f32 v[120:121], v[138:139], v[114:115], v[116:117] op_sel_hi:[0,1,1] neg_lo:[0,0,1] neg_hi:[0,0,1]
	v_pk_fma_f32 v[114:115], v[138:139], v[114:115], v[116:117] op_sel_hi:[0,1,1]
	v_mov_b32_e32 v119, v113
	v_mul_f32_e32 v110, v110, v190
	v_mul_f32_e32 v111, v111, v190
	v_pk_mul_f32 v[116:117], v[132:133], v[108:109] op_sel:[1,1] op_sel_hi:[1,0]
	v_mov_b32_e32 v2, v135
	v_mov_b32_e32 v121, v115
	v_mul_f32_e32 v112, s0, v118
	v_mul_f32_e32 v113, s0, v119
	v_pk_fma_f32 v[118:119], v[132:133], v[108:109], v[116:117] op_sel_hi:[0,1,1] neg_lo:[0,0,1] neg_hi:[0,0,1]
	v_pk_fma_f32 v[108:109], v[132:133], v[108:109], v[116:117] op_sel_hi:[0,1,1]
	v_pk_mul_f32 v[116:117], v[2:3], v[110:111] op_sel:[0,1] op_sel_hi:[0,0]
	v_mul_f32_e32 v114, s0, v120
	v_mul_f32_e32 v115, s0, v121
	v_pk_fma_f32 v[120:121], v[134:135], v[110:111], v[116:117] op_sel_hi:[0,1,1] neg_lo:[0,0,1] neg_hi:[0,0,1]
	v_pk_fma_f32 v[110:111], v[134:135], v[110:111], v[116:117] op_sel_hi:[0,1,1]
	v_mov_b32_e32 v121, v111
	v_mov_b32_e32 v119, v109
	v_lshlrev_b64 v[108:109], 10, v[160:161]
	v_mul_f32_e32 v116, s0, v120
	v_mul_f32_e32 v117, s0, v121
	v_mul_f32_e32 v110, s0, v118
	v_mul_f32_e32 v111, s0, v119
	v_lshl_add_u64 v[108:109], s[94:95], 0, v[108:109]
	v_lshl_add_u64 v[118:119], v[108:109], 0, v[124:125]
	v_cvt_pk_bf16_f32 v108, v112, v113
	v_cvt_pk_bf16_f32 v109, v114, v115
	v_cvt_pk_bf16_f32 v110, v110, v111
	v_cvt_pk_bf16_f32 v111, v116, v117
	v_mul_f32_e32 v104, v104, v192
	v_mul_f32_e32 v105, v105, v192
	global_store_dwordx4 v[118:119], v[108:111], off
	v_mul_f32_e32 v106, v106, v192
	v_mul_f32_e32 v107, v107, v192
	v_mov_b32_e32 v2, v151
	v_pk_mul_f32 v[108:109], v[148:149], v[104:105] op_sel:[1,1] op_sel_hi:[1,0]
	v_mul_f32_e32 v100, v100, v192
	v_mul_f32_e32 v101, v101, v192
	v_pk_fma_f32 v[110:111], v[148:149], v[104:105], v[108:109] op_sel_hi:[0,1,1] neg_lo:[0,0,1] neg_hi:[0,0,1]
	v_pk_fma_f32 v[104:105], v[148:149], v[104:105], v[108:109] op_sel_hi:[0,1,1]
	v_pk_mul_f32 v[108:109], v[2:3], v[106:107] op_sel:[0,1] op_sel_hi:[0,0]
	v_pk_fma_f32 v[112:113], v[150:151], v[106:107], v[108:109] op_sel_hi:[0,1,1] neg_lo:[0,0,1] neg_hi:[0,0,1]
	v_pk_fma_f32 v[106:107], v[150:151], v[106:107], v[108:109] op_sel_hi:[0,1,1]
	v_mov_b32_e32 v111, v105
	v_mul_f32_e32 v102, v102, v192
	v_mul_f32_e32 v103, v103, v192
	v_pk_mul_f32 v[108:109], v[140:141], v[100:101] op_sel:[1,1] op_sel_hi:[1,0]
	v_mov_b32_e32 v2, v143
	v_mov_b32_e32 v113, v107
	v_mul_f32_e32 v104, s0, v110
	v_mul_f32_e32 v105, s0, v111
	v_pk_fma_f32 v[110:111], v[140:141], v[100:101], v[108:109] op_sel_hi:[0,1,1] neg_lo:[0,0,1] neg_hi:[0,0,1]
	v_pk_fma_f32 v[100:101], v[140:141], v[100:101], v[108:109] op_sel_hi:[0,1,1]
	v_pk_mul_f32 v[108:109], v[2:3], v[102:103] op_sel:[0,1] op_sel_hi:[0,0]
	v_mul_f32_e32 v106, s0, v112
	v_mul_f32_e32 v107, s0, v113
	v_pk_fma_f32 v[112:113], v[142:143], v[102:103], v[108:109] op_sel_hi:[0,1,1] neg_lo:[0,0,1] neg_hi:[0,0,1]
	v_pk_fma_f32 v[102:103], v[142:143], v[102:103], v[108:109] op_sel_hi:[0,1,1]
	v_mov_b32_e32 v113, v103
	v_mov_b32_e32 v111, v101
	v_lshlrev_b64 v[100:101], 10, v[162:163]
	v_mul_f32_e32 v108, s0, v112
	v_mul_f32_e32 v109, s0, v113
	v_mul_f32_e32 v102, s0, v110
	v_mul_f32_e32 v103, s0, v111
	v_lshl_add_u64 v[100:101], s[94:95], 0, v[100:101]
	v_lshl_add_u64 v[110:111], v[100:101], 0, v[124:125]
	v_cvt_pk_bf16_f32 v100, v104, v105
	v_cvt_pk_bf16_f32 v101, v106, v107
	v_cvt_pk_bf16_f32 v102, v102, v103
	v_cvt_pk_bf16_f32 v103, v108, v109
	global_store_dwordx4 v[110:111], v[100:103], off
	s_cbranch_scc1 .LBB0_166
	v_add_u32_e32 v138, 0x80, v156
	s_movk_i32 s0, 0x7cf
	v_cmp_gt_i32_e32 vcc, s20, v138
	v_and_or_b32 v2, v138, s0, 16
	v_ashrrev_i32_e32 v139, 31, v138
	v_cndmask_b32_e32 v2, v181, v2, vcc
	v_lshl_add_u64 v[112:113], v[138:139], 2, s[70:71]
	v_lshlrev_b32_e32 v2, 8, v2
	v_mov_b32_e32 v148, v246
	v_lshl_add_u64 v[100:101], v[182:183], 0, v[2:3]
	global_load_dwordx4 v[140:143], v[100:101], off offset:16
	global_load_dwordx4 v[144:147], v[100:101], off
	v_add_u32_e32 v126, 0x90, v156
	v_and_b32_e32 v2, 0x7df, v126
	v_cmp_gt_i32_e32 vcc, s20, v126
	v_add_u32_e32 v2, 16, v2
	v_mov_b32_e32 v136, v247
	v_cndmask_b32_e32 v2, v181, v2, vcc
	v_lshlrev_b32_e32 v2, 8, v2
	v_lshl_add_u64 v[100:101], v[182:183], 0, v[2:3]
	global_load_dwordx4 v[108:111], v[100:101], off offset:16
	global_load_dwordx4 v[120:123], v[100:101], off
	v_add_u32_e32 v128, 0xa0, v156
	s_movk_i32 s0, 0x7ef
	v_cmp_gt_i32_e32 vcc, s20, v128
	v_and_or_b32 v2, v128, s0, 16
	v_mov_b32_e32 v132, v248
	v_cndmask_b32_e32 v2, v181, v2, vcc
	v_lshlrev_b32_e32 v2, 8, v2
	v_lshl_add_u64 v[104:105], v[182:183], 0, v[2:3]
	global_load_dwordx4 v[100:103], v[104:105], off offset:16
	s_nop 0
	global_load_dwordx4 v[104:107], v[104:105], off
	v_add_u32_e32 v130, 0xb0, v156
	v_and_b32_e32 v2, 0x7ff, v130
	v_cmp_gt_i32_e32 vcc, s20, v130
	v_add_u32_e32 v2, 16, v2
	v_mov_b32_e32 v134, v249
	v_cndmask_b32_e32 v2, v181, v2, vcc
	v_lshlrev_b32_e32 v2, 8, v2
	v_lshl_add_u64 v[116:117], v[182:183], 0, v[2:3]
	global_load_dwordx4 v[112:115], v[116:117], off offset:16
	s_nop 0
	global_load_dwordx4 v[116:119], v[116:117], off
	s_mov_b32 s0, 0x3e000000
	v_ashrrev_i32_e32 v127, 31, v126
	v_ashrrev_i32_e32 v129, 31, v128
	v_ashrrev_i32_e32 v131, 31, v130
	s_waitcnt vmcnt(0)
	v_mul_f32_e32 v96, v96, v148
	v_mul_f32_e32 v97, v97, v148
	v_mul_f32_e32 v98, v98, v148
	v_mul_f32_e32 v99, v99, v148
	v_pk_mul_f32 v[150:151], v[144:145], v[96:97] op_sel:[1,1] op_sel_hi:[1,0]
	v_mov_b32_e32 v2, v147
	v_pk_fma_f32 v[152:153], v[144:145], v[96:97], v[150:151] op_sel_hi:[0,1,1] neg_lo:[0,0,1] neg_hi:[0,0,1]
	v_pk_fma_f32 v[96:97], v[144:145], v[96:97], v[150:151] op_sel_hi:[0,1,1]
	v_pk_mul_f32 v[144:145], v[2:3], v[98:99] op_sel:[0,1] op_sel_hi:[0,0]
	v_mul_f32_e32 v92, v92, v148
	v_mul_f32_e32 v93, v93, v148
	v_pk_fma_f32 v[150:151], v[146:147], v[98:99], v[144:145] op_sel_hi:[0,1,1] neg_lo:[0,0,1] neg_hi:[0,0,1]
	v_pk_fma_f32 v[98:99], v[146:147], v[98:99], v[144:145] op_sel_hi:[0,1,1]
	v_mul_f32_e32 v94, v94, v148
	v_mul_f32_e32 v95, v95, v148
	v_pk_mul_f32 v[144:145], v[140:141], v[92:93] op_sel:[1,1] op_sel_hi:[1,0]
	v_mov_b32_e32 v2, v143
	v_pk_fma_f32 v[146:147], v[140:141], v[92:93], v[144:145] op_sel_hi:[0,1,1] neg_lo:[0,0,1] neg_hi:[0,0,1]
	v_pk_fma_f32 v[92:93], v[140:141], v[92:93], v[144:145] op_sel_hi:[0,1,1]
	v_pk_mul_f32 v[140:141], v[2:3], v[94:95] op_sel:[0,1] op_sel_hi:[0,0]
	v_pk_fma_f32 v[144:145], v[142:143], v[94:95], v[140:141] op_sel_hi:[0,1,1] neg_lo:[0,0,1] neg_hi:[0,0,1]
	v_pk_fma_f32 v[94:95], v[142:143], v[94:95], v[140:141] op_sel_hi:[0,1,1]
	v_mov_b32_e32 v151, v99
	v_mov_b32_e32 v153, v97
	v_mov_b32_e32 v145, v95
	v_mov_b32_e32 v147, v93
	v_lshlrev_b64 v[92:93], 10, v[138:139]
	v_mul_f32_e32 v98, s0, v150
	v_mul_f32_e32 v99, s0, v151
	v_mul_f32_e32 v96, s0, v152
	v_mul_f32_e32 v97, s0, v153
	v_mul_f32_e32 v140, s0, v144
	v_mul_f32_e32 v141, s0, v145
	v_mul_f32_e32 v94, s0, v146
	v_mul_f32_e32 v95, s0, v147
	v_lshl_add_u64 v[92:93], s[94:95], 0, v[92:93]
	v_lshl_add_u64 v[138:139], v[92:93], 0, v[124:125]
	v_cvt_pk_bf16_f32 v92, v96, v97
	v_cvt_pk_bf16_f32 v93, v98, v99
	v_cvt_pk_bf16_f32 v94, v94, v95
	v_cvt_pk_bf16_f32 v95, v140, v141
	v_mul_f32_e32 v88, v88, v136
	v_mul_f32_e32 v89, v89, v136
	global_store_dwordx4 v[138:139], v[92:95], off
	v_mul_f32_e32 v90, v90, v136
	v_mul_f32_e32 v91, v91, v136
	v_mov_b32_e32 v2, v123
	v_pk_mul_f32 v[92:93], v[120:121], v[88:89] op_sel:[1,1] op_sel_hi:[1,0]
	v_mul_f32_e32 v84, v84, v136
	v_mul_f32_e32 v85, v85, v136
	v_pk_fma_f32 v[94:95], v[120:121], v[88:89], v[92:93] op_sel_hi:[0,1,1] neg_lo:[0,0,1] neg_hi:[0,0,1]
	v_pk_fma_f32 v[88:89], v[120:121], v[88:89], v[92:93] op_sel_hi:[0,1,1]
	v_pk_mul_f32 v[92:93], v[2:3], v[90:91] op_sel:[0,1] op_sel_hi:[0,0]
	v_pk_fma_f32 v[96:97], v[122:123], v[90:91], v[92:93] op_sel_hi:[0,1,1] neg_lo:[0,0,1] neg_hi:[0,0,1]
	v_pk_fma_f32 v[90:91], v[122:123], v[90:91], v[92:93] op_sel_hi:[0,1,1]
	v_mov_b32_e32 v95, v89
	v_mul_f32_e32 v86, v86, v136
	v_mul_f32_e32 v87, v87, v136
	v_pk_mul_f32 v[92:93], v[108:109], v[84:85] op_sel:[1,1] op_sel_hi:[1,0]
	v_mov_b32_e32 v2, v111
	v_mov_b32_e32 v97, v91
	v_mul_f32_e32 v88, s0, v94
	v_mul_f32_e32 v89, s0, v95
	v_pk_fma_f32 v[94:95], v[108:109], v[84:85], v[92:93] op_sel_hi:[0,1,1] neg_lo:[0,0,1] neg_hi:[0,0,1]
	v_pk_fma_f32 v[84:85], v[108:109], v[84:85], v[92:93] op_sel_hi:[0,1,1]
	v_pk_mul_f32 v[92:93], v[2:3], v[86:87] op_sel:[0,1] op_sel_hi:[0,0]
	v_mul_f32_e32 v90, s0, v96
	v_mul_f32_e32 v91, s0, v97
	v_pk_fma_f32 v[96:97], v[110:111], v[86:87], v[92:93] op_sel_hi:[0,1,1] neg_lo:[0,0,1] neg_hi:[0,0,1]
	v_pk_fma_f32 v[86:87], v[110:111], v[86:87], v[92:93] op_sel_hi:[0,1,1]
	v_mov_b32_e32 v97, v87
	v_mov_b32_e32 v95, v85
	v_lshlrev_b64 v[84:85], 10, v[126:127]
	v_mul_f32_e32 v92, s0, v96
	v_mul_f32_e32 v93, s0, v97
	v_mul_f32_e32 v86, s0, v94
	v_mul_f32_e32 v87, s0, v95
	v_lshl_add_u64 v[84:85], s[94:95], 0, v[84:85]
	v_lshl_add_u64 v[94:95], v[84:85], 0, v[124:125]
	v_cvt_pk_bf16_f32 v84, v88, v89
	v_cvt_pk_bf16_f32 v85, v90, v91
	v_cvt_pk_bf16_f32 v86, v86, v87
	v_cvt_pk_bf16_f32 v87, v92, v93
	v_mul_f32_e32 v80, v80, v132
	v_mul_f32_e32 v81, v81, v132
	global_store_dwordx4 v[94:95], v[84:87], off
	v_mul_f32_e32 v82, v82, v132
	v_mul_f32_e32 v83, v83, v132
	v_mov_b32_e32 v2, v107
	v_pk_mul_f32 v[84:85], v[104:105], v[80:81] op_sel:[1,1] op_sel_hi:[1,0]
	v_mul_f32_e32 v76, v76, v132
	v_mul_f32_e32 v77, v77, v132
	v_pk_fma_f32 v[86:87], v[104:105], v[80:81], v[84:85] op_sel_hi:[0,1,1] neg_lo:[0,0,1] neg_hi:[0,0,1]
	v_pk_fma_f32 v[80:81], v[104:105], v[80:81], v[84:85] op_sel_hi:[0,1,1]
	v_pk_mul_f32 v[84:85], v[2:3], v[82:83] op_sel:[0,1] op_sel_hi:[0,0]
	v_pk_fma_f32 v[88:89], v[106:107], v[82:83], v[84:85] op_sel_hi:[0,1,1] neg_lo:[0,0,1] neg_hi:[0,0,1]
	v_pk_fma_f32 v[82:83], v[106:107], v[82:83], v[84:85] op_sel_hi:[0,1,1]
	v_mov_b32_e32 v87, v81
	v_mul_f32_e32 v78, v78, v132
	v_mul_f32_e32 v79, v79, v132
	v_pk_mul_f32 v[84:85], v[100:101], v[76:77] op_sel:[1,1] op_sel_hi:[1,0]
	v_mov_b32_e32 v2, v103
	v_mov_b32_e32 v89, v83
	v_mul_f32_e32 v80, s0, v86
	v_mul_f32_e32 v81, s0, v87
	v_pk_fma_f32 v[86:87], v[100:101], v[76:77], v[84:85] op_sel_hi:[0,1,1] neg_lo:[0,0,1] neg_hi:[0,0,1]
	v_pk_fma_f32 v[76:77], v[100:101], v[76:77], v[84:85] op_sel_hi:[0,1,1]
	v_pk_mul_f32 v[84:85], v[2:3], v[78:79] op_sel:[0,1] op_sel_hi:[0,0]
	v_mul_f32_e32 v82, s0, v88
	v_mul_f32_e32 v83, s0, v89
	v_pk_fma_f32 v[88:89], v[102:103], v[78:79], v[84:85] op_sel_hi:[0,1,1] neg_lo:[0,0,1] neg_hi:[0,0,1]
	v_pk_fma_f32 v[78:79], v[102:103], v[78:79], v[84:85] op_sel_hi:[0,1,1]
	v_mov_b32_e32 v89, v79
	v_mov_b32_e32 v87, v77
	v_lshlrev_b64 v[76:77], 10, v[128:129]
	v_mul_f32_e32 v84, s0, v88
	v_mul_f32_e32 v85, s0, v89
	v_mul_f32_e32 v78, s0, v86
	v_mul_f32_e32 v79, s0, v87
	v_lshl_add_u64 v[76:77], s[94:95], 0, v[76:77]
	v_lshl_add_u64 v[86:87], v[76:77], 0, v[124:125]
	v_cvt_pk_bf16_f32 v76, v80, v81
	v_cvt_pk_bf16_f32 v77, v82, v83
	v_cvt_pk_bf16_f32 v78, v78, v79
	v_cvt_pk_bf16_f32 v79, v84, v85
	v_mul_f32_e32 v72, v72, v134
	v_mul_f32_e32 v73, v73, v134
	global_store_dwordx4 v[86:87], v[76:79], off
	v_mul_f32_e32 v74, v74, v134
	v_mul_f32_e32 v75, v75, v134
	v_mov_b32_e32 v2, v119
	v_pk_mul_f32 v[76:77], v[116:117], v[72:73] op_sel:[1,1] op_sel_hi:[1,0]
	v_mul_f32_e32 v68, v68, v134
	v_mul_f32_e32 v69, v69, v134
	v_pk_fma_f32 v[78:79], v[116:117], v[72:73], v[76:77] op_sel_hi:[0,1,1] neg_lo:[0,0,1] neg_hi:[0,0,1]
	v_pk_fma_f32 v[72:73], v[116:117], v[72:73], v[76:77] op_sel_hi:[0,1,1]
	v_pk_mul_f32 v[76:77], v[2:3], v[74:75] op_sel:[0,1] op_sel_hi:[0,0]
	v_pk_fma_f32 v[80:81], v[118:119], v[74:75], v[76:77] op_sel_hi:[0,1,1] neg_lo:[0,0,1] neg_hi:[0,0,1]
	v_pk_fma_f32 v[74:75], v[118:119], v[74:75], v[76:77] op_sel_hi:[0,1,1]
	v_mov_b32_e32 v79, v73
	v_mul_f32_e32 v70, v70, v134
	v_mul_f32_e32 v71, v71, v134
	v_pk_mul_f32 v[76:77], v[112:113], v[68:69] op_sel:[1,1] op_sel_hi:[1,0]
	v_mov_b32_e32 v2, v115
	v_mov_b32_e32 v81, v75
	v_mul_f32_e32 v72, s0, v78
	v_mul_f32_e32 v73, s0, v79
	v_pk_fma_f32 v[78:79], v[112:113], v[68:69], v[76:77] op_sel_hi:[0,1,1] neg_lo:[0,0,1] neg_hi:[0,0,1]
	v_pk_fma_f32 v[68:69], v[112:113], v[68:69], v[76:77] op_sel_hi:[0,1,1]
	v_pk_mul_f32 v[76:77], v[2:3], v[70:71] op_sel:[0,1] op_sel_hi:[0,0]
	v_mul_f32_e32 v74, s0, v80
	v_mul_f32_e32 v75, s0, v81
	v_pk_fma_f32 v[80:81], v[114:115], v[70:71], v[76:77] op_sel_hi:[0,1,1] neg_lo:[0,0,1] neg_hi:[0,0,1]
	v_pk_fma_f32 v[70:71], v[114:115], v[70:71], v[76:77] op_sel_hi:[0,1,1]
	v_mov_b32_e32 v81, v71
	v_mov_b32_e32 v79, v69
	v_lshlrev_b64 v[68:69], 10, v[130:131]
	v_mul_f32_e32 v76, s0, v80
	v_mul_f32_e32 v77, s0, v81
	v_mul_f32_e32 v70, s0, v78
	v_mul_f32_e32 v71, s0, v79
	v_lshl_add_u64 v[68:69], s[94:95], 0, v[68:69]
	v_lshl_add_u64 v[78:79], v[68:69], 0, v[124:125]
	v_cvt_pk_bf16_f32 v68, v72, v73
	v_cvt_pk_bf16_f32 v69, v74, v75
	v_cvt_pk_bf16_f32 v70, v70, v71
	v_cvt_pk_bf16_f32 v71, v76, v77
	global_store_dwordx4 v[78:79], v[68:71], off

.Lsec78_b:
	s_lshl_b32 s2, s48, 8
	v_add_u32_e32 v70, s2, v241
	v_ashrrev_i32_e32 v71, 31, v70
	v_lshl_add_u64 v[68:69], v[70:71], 2, s[70:71]
	v_mov_b32_e32 v82, v164
	v_mov_b32_e32 v80, v165
	v_mov_b32_e32 v76, v166
	v_mov_b32_e32 v2, v167
	s_ashr_i32 s75, s74, 31
	s_mov_b32 s2, 0x9ce6000
	s_cmp_eq_u32 s17, 8
	s_cselect_b32 s2, 0xbd25800, s2
	v_or_b32_e32 v78, 16, v70
	v_ashrrev_i32_e32 v79, 31, v78
	v_lshlrev_b64 v[78:79], 11, v[78:79]
	v_lshl_add_u64 v[78:79], s[94:95], 0, v[78:79]
	v_or_b32_e32 v74, 32, v70
	v_ashrrev_i32_e32 v75, 31, v74
	v_lshlrev_b64 v[74:75], 11, v[74:75]
	v_lshl_add_u64 v[74:75], s[94:95], 0, v[74:75]
	v_or_b32_e32 v72, 48, v70
	v_ashrrev_i32_e32 v73, 31, v72
	v_lshlrev_b64 v[72:73], 11, v[72:73]
	v_lshl_add_u64 v[72:73], s[94:95], 0, v[72:73]
	s_cmp_eq_u32 s48, 64
	v_mul_f32_e32 v68, v66, v82
	v_mul_f32_e32 v69, v67, v82
	s_nop 0
	v_mul_f32_e32 v68, 0xbfb8aa3b, v68
	v_exp_f32_e32 v68, v68
	v_mul_f32_e32 v84, v64, v82
	v_mul_f32_e32 v85, v65, v82
	v_add_f32_e32 v68, 1.0, v68
	v_mul_f32_e32 v77, 0xbfb8aa3b, v84
	v_rcp_f32_e32 v84, v68
	v_mul_f32_e32 v68, 0xbfb8aa3b, v69
	v_exp_f32_e32 v68, v68
	v_mul_f32_e32 v81, 0xbfb8aa3b, v85
	v_exp_f32_e32 v77, v77
	v_exp_f32_e32 v81, v81
	v_add_f32_e32 v68, 1.0, v68
	v_rcp_f32_e32 v85, v68
	v_mul_f32_e32 v68, v62, v82
	v_mul_f32_e32 v69, v63, v82
	v_mul_f32_e32 v83, v61, v82
	v_mul_f32_e32 v82, v60, v82
	v_mul_f32_e32 v68, 0xbfb8aa3b, v68
	v_mul_f32_e32 v82, 0xbfb8aa3b, v82
	v_exp_f32_e32 v68, v68
	v_exp_f32_e32 v82, v82
	v_add_f32_e32 v77, 1.0, v77
	v_add_f32_e32 v81, 1.0, v81
	v_add_f32_e32 v68, 1.0, v68
	v_add_f32_e32 v82, 1.0, v82
	v_rcp_f32_e32 v90, v68
	v_mul_f32_e32 v68, 0xbfb8aa3b, v69
	v_rcp_f32_e32 v88, v82
	v_mul_f32_e32 v82, 0xbfb8aa3b, v83
	v_exp_f32_e32 v68, v68
	v_exp_f32_e32 v82, v82
	v_rcp_f32_e32 v77, v77
	v_rcp_f32_e32 v81, v81
	v_add_f32_e32 v68, 1.0, v68
	v_add_f32_e32 v82, 1.0, v82
	v_rcp_f32_e32 v91, v68
	v_lshlrev_b64 v[68:69], 11, v[70:71]
	v_rcp_f32_e32 v89, v82
	v_lshl_add_u64 v[82:83], s[94:95], 0, v[68:69]
	v_lshl_add_u64 v[68:69], s[74:75], 0, v[178:179]
	v_lshlrev_b64 v[68:69], 1, v[68:69]
	v_lshl_add_u64 v[86:87], v[82:83], 0, v[68:69]
	v_add_co_u32_e32 v86, vcc, s2, v86
	v_cvt_pk_bf16_f32 v82, v77, v81
	v_cvt_pk_bf16_f32 v83, v84, v85
	v_cvt_pk_bf16_f32 v84, v88, v89
	v_cvt_pk_bf16_f32 v85, v90, v91
	v_addc_co_u32_e32 v87, vcc, 0, v87, vcc
	global_store_dwordx4 v[86:87], v[82:85], off offset:768
	s_nop 1
	v_mul_f32_e32 v82, v58, v80
	v_mul_f32_e32 v83, v59, v80
	v_mul_f32_e32 v84, v56, v80
	v_mul_f32_e32 v85, v57, v80
	v_mul_f32_e32 v81, 0xbfb8aa3b, v82
	v_exp_f32_e32 v81, v81
	v_mul_f32_e32 v71, 0xbfb8aa3b, v84
	v_mul_f32_e32 v77, 0xbfb8aa3b, v85
	v_exp_f32_e32 v71, v71
	v_add_f32_e32 v81, 1.0, v81
	v_rcp_f32_e32 v84, v81
	v_mul_f32_e32 v81, 0xbfb8aa3b, v83
	v_exp_f32_e32 v81, v81
	v_exp_f32_e32 v77, v77
	v_add_f32_e32 v71, 1.0, v71
	v_rcp_f32_e32 v71, v71
	v_add_f32_e32 v81, 1.0, v81
	v_mul_f32_e32 v82, v54, v80
	v_mul_f32_e32 v83, v55, v80
	v_rcp_f32_e32 v85, v81
	v_mul_f32_e32 v82, 0xbfb8aa3b, v82
	v_exp_f32_e32 v82, v82
	v_mul_f32_e32 v81, v53, v80
	v_mul_f32_e32 v80, v52, v80
	v_add_f32_e32 v77, 1.0, v77
	v_mul_f32_e32 v80, 0xbfb8aa3b, v80
	v_add_f32_e32 v82, 1.0, v82
	v_mul_f32_e32 v81, 0xbfb8aa3b, v81
	v_rcp_f32_e32 v86, v82
	v_mul_f32_e32 v82, 0xbfb8aa3b, v83
	v_exp_f32_e32 v80, v80
	v_exp_f32_e32 v81, v81
	v_exp_f32_e32 v82, v82
	v_rcp_f32_e32 v77, v77
	v_add_f32_e32 v80, 1.0, v80
	v_add_f32_e32 v81, 1.0, v81
	v_add_f32_e32 v82, 1.0, v82
	v_rcp_f32_e32 v80, v80
	v_rcp_f32_e32 v81, v81
	v_rcp_f32_e32 v87, v82
	v_lshl_add_u64 v[82:83], v[78:79], 0, v[68:69]
	v_add_co_u32_e32 v82, vcc, s2, v82
	v_cvt_pk_bf16_f32 v78, v71, v77
	v_cvt_pk_bf16_f32 v79, v84, v85
	v_cvt_pk_bf16_f32 v80, v80, v81
	v_cvt_pk_bf16_f32 v81, v86, v87
	v_addc_co_u32_e32 v83, vcc, 0, v83, vcc
	global_store_dwordx4 v[82:83], v[78:81], off offset:768
	s_nop 1
	v_mul_f32_e32 v80, v48, v76
	v_mul_f32_e32 v81, v49, v76
	v_mul_f32_e32 v78, v50, v76
	v_mul_f32_e32 v79, v51, v76
	v_mul_f32_e32 v77, 0xbfb8aa3b, v81
	v_exp_f32_e32 v77, v77
	v_mul_f32_e32 v71, 0xbfb8aa3b, v80
	v_exp_f32_e32 v71, v71
	v_add_f32_e32 v77, 1.0, v77
	v_rcp_f32_e32 v80, v77
	v_mul_f32_e32 v77, 0xbfb8aa3b, v78
	v_exp_f32_e32 v77, v77
	v_add_f32_e32 v71, 1.0, v71
	v_rcp_f32_e32 v71, v71
	v_add_f32_e32 v77, 1.0, v77
	v_rcp_f32_e32 v81, v77
	v_mul_f32_e32 v77, 0xbfb8aa3b, v79
	v_exp_f32_e32 v77, v77
	s_nop 0
	v_add_f32_e32 v77, 1.0, v77
	v_mul_f32_e32 v78, v46, v76
	v_mul_f32_e32 v79, v47, v76
	v_rcp_f32_e32 v82, v77
	v_mul_f32_e32 v78, 0xbfb8aa3b, v78
	v_exp_f32_e32 v78, v78
	v_mul_f32_e32 v77, v45, v76
	v_mul_f32_e32 v76, v44, v76
	v_add_f32_e32 v78, 1.0, v78
	v_mul_f32_e32 v76, 0xbfb8aa3b, v76
	v_mul_f32_e32 v77, 0xbfb8aa3b, v77
	v_rcp_f32_e32 v83, v78
	v_mul_f32_e32 v78, 0xbfb8aa3b, v79
	v_exp_f32_e32 v76, v76
	v_exp_f32_e32 v77, v77
	v_exp_f32_e32 v78, v78
	v_add_f32_e32 v76, 1.0, v76
	v_add_f32_e32 v77, 1.0, v77
	v_add_f32_e32 v78, 1.0, v78
	v_rcp_f32_e32 v76, v76
	v_rcp_f32_e32 v77, v77
	v_rcp_f32_e32 v84, v78
	v_lshl_add_u64 v[78:79], v[74:75], 0, v[68:69]
	v_add_co_u32_e32 v78, vcc, s2, v78
	v_cvt_pk_bf16_f32 v74, v71, v80
	v_cvt_pk_bf16_f32 v75, v81, v82
	v_cvt_pk_bf16_f32 v76, v76, v77
	v_cvt_pk_bf16_f32 v77, v83, v84
	v_addc_co_u32_e32 v79, vcc, 0, v79, vcc
	global_store_dwordx4 v[78:79], v[74:77], off offset:768
	s_nop 1
	v_mul_f32_e32 v74, v42, v2
	v_mul_f32_e32 v75, v43, v2
	v_mul_f32_e32 v76, v40, v2
	v_mul_f32_e32 v77, v41, v2
	v_mul_f32_e32 v74, 0xbfb8aa3b, v74
	v_exp_f32_e32 v74, v74
	v_mul_f32_e32 v71, 0xbfb8aa3b, v76
	v_mul_f32_e32 v76, 0xbfb8aa3b, v77
	v_exp_f32_e32 v76, v76
	v_add_f32_e32 v74, 1.0, v74
	v_rcp_f32_e32 v79, v74
	v_mul_f32_e32 v74, 0xbfb8aa3b, v75
	v_exp_f32_e32 v74, v74
	v_add_f32_e32 v76, 1.0, v76
	v_rcp_f32_e32 v78, v76
	v_mul_f32_e32 v76, v36, v2
	v_mul_f32_e32 v77, v37, v2
	v_add_f32_e32 v74, 1.0, v74
	v_rcp_f32_e32 v80, v74
	v_mul_f32_e32 v74, v38, v2
	v_mul_f32_e32 v75, v39, v2
	v_mul_f32_e32 v2, 0xbfb8aa3b, v76
	v_mul_f32_e32 v74, 0xbfb8aa3b, v74
	v_exp_f32_e32 v74, v74
	v_mul_f32_e32 v76, 0xbfb8aa3b, v77
	v_exp_f32_e32 v71, v71
	v_exp_f32_e32 v2, v2
	v_add_f32_e32 v74, 1.0, v74
	v_rcp_f32_e32 v82, v74
	v_mul_f32_e32 v74, 0xbfb8aa3b, v75
	v_exp_f32_e32 v76, v76
	v_exp_f32_e32 v74, v74
	v_add_f32_e32 v71, 1.0, v71
	v_add_f32_e32 v2, 1.0, v2
	v_add_f32_e32 v76, 1.0, v76
	v_add_f32_e32 v74, 1.0, v74
	v_rcp_f32_e32 v71, v71
	v_rcp_f32_e32 v2, v2
	v_rcp_f32_e32 v81, v76
	v_rcp_f32_e32 v75, v74
	v_lshl_add_u64 v[76:77], v[72:73], 0, v[68:69]
	v_add_co_u32_e32 v76, vcc, s2, v76
	v_cvt_pk_bf16_f32 v72, v71, v78
	v_cvt_pk_bf16_f32 v73, v79, v80
	v_cvt_pk_bf16_f32 v74, v2, v81
	v_cvt_pk_bf16_f32 v75, v82, v75
	v_addc_co_u32_e32 v77, vcc, 0, v77, vcc
	global_store_dwordx4 v[76:77], v[72:75], off offset:768
	s_cbranch_scc1 .LBB0_176
	v_add_u32_e32 v80, 0x80, v70
	v_ashrrev_i32_e32 v81, 31, v80
	v_lshl_add_u64 v[82:83], v[80:81], 2, s[70:71]
	v_mov_b32_e32 v84, v246
	v_mov_b32_e32 v78, v247
	v_mov_b32_e32 v74, v248
	v_mov_b32_e32 v2, v249
	v_lshlrev_b64 v[80:81], 11, v[80:81]
	v_lshl_add_u64 v[80:81], s[94:95], 0, v[80:81]
	v_add_u32_e32 v76, 0x90, v70
	v_ashrrev_i32_e32 v77, 31, v76
	v_lshlrev_b64 v[76:77], 11, v[76:77]
	v_lshl_add_u64 v[76:77], s[94:95], 0, v[76:77]
	v_add_u32_e32 v72, 0xa0, v70
	v_ashrrev_i32_e32 v73, 31, v72
	v_lshlrev_b64 v[72:73], 11, v[72:73]
	v_lshl_add_u64 v[72:73], s[94:95], 0, v[72:73]
	v_add_u32_e32 v70, 0xb0, v70
	v_ashrrev_i32_e32 v71, 31, v70
	v_lshlrev_b64 v[70:71], 11, v[70:71]
	v_lshl_add_u64 v[70:71], s[94:95], 0, v[70:71]
	v_mul_f32_e32 v82, v34, v84
	v_mul_f32_e32 v83, v35, v84
	s_nop 0
	v_mul_f32_e32 v82, 0xbfb8aa3b, v82
	v_exp_f32_e32 v82, v82
	v_mul_f32_e32 v86, v32, v84
	v_mul_f32_e32 v87, v33, v84
	v_add_f32_e32 v82, 1.0, v82
	v_mul_f32_e32 v75, 0xbfb8aa3b, v86
	v_rcp_f32_e32 v86, v82
	v_mul_f32_e32 v82, 0xbfb8aa3b, v83
	v_exp_f32_e32 v82, v82
	v_mul_f32_e32 v79, 0xbfb8aa3b, v87
	v_exp_f32_e32 v75, v75
	v_exp_f32_e32 v79, v79
	v_add_f32_e32 v82, 1.0, v82
	v_rcp_f32_e32 v87, v82
	v_mul_f32_e32 v82, v30, v84
	v_mul_f32_e32 v83, v31, v84
	v_mul_f32_e32 v85, v29, v84
	v_mul_f32_e32 v84, v28, v84
	v_mul_f32_e32 v82, 0xbfb8aa3b, v82
	v_mul_f32_e32 v84, 0xbfb8aa3b, v84
	v_exp_f32_e32 v84, v84
	v_exp_f32_e32 v82, v82
	v_add_f32_e32 v75, 1.0, v75
	v_add_f32_e32 v79, 1.0, v79
	v_add_f32_e32 v84, 1.0, v84
	v_add_f32_e32 v82, 1.0, v82
	v_rcp_f32_e32 v88, v84
	v_mul_f32_e32 v84, 0xbfb8aa3b, v85
	v_rcp_f32_e32 v90, v82
	v_mul_f32_e32 v82, 0xbfb8aa3b, v83
	v_exp_f32_e32 v84, v84
	v_exp_f32_e32 v82, v82
	v_rcp_f32_e32 v75, v75
	v_rcp_f32_e32 v79, v79
	v_add_f32_e32 v84, 1.0, v84
	v_add_f32_e32 v82, 1.0, v82
	v_rcp_f32_e32 v89, v84
	v_rcp_f32_e32 v83, v82
	v_lshl_add_u64 v[84:85], v[80:81], 0, v[68:69]
	v_add_co_u32_e32 v84, vcc, s2, v84
	v_cvt_pk_bf16_f32 v80, v75, v79
	v_cvt_pk_bf16_f32 v81, v86, v87
	v_cvt_pk_bf16_f32 v82, v88, v89
	v_cvt_pk_bf16_f32 v83, v90, v83
	v_addc_co_u32_e32 v85, vcc, 0, v85, vcc
	global_store_dwordx4 v[84:85], v[80:83], off offset:768
	s_nop 1
	v_mul_f32_e32 v82, v24, v78
	v_mul_f32_e32 v83, v25, v78
	v_mul_f32_e32 v80, v26, v78
	v_mul_f32_e32 v81, v27, v78
	v_mul_f32_e32 v79, 0xbfb8aa3b, v83
	v_exp_f32_e32 v79, v79
	v_mul_f32_e32 v75, 0xbfb8aa3b, v82
	v_exp_f32_e32 v75, v75
	v_add_f32_e32 v79, 1.0, v79
	v_rcp_f32_e32 v82, v79
	v_mul_f32_e32 v79, 0xbfb8aa3b, v80
	v_exp_f32_e32 v79, v79
	v_add_f32_e32 v75, 1.0, v75
	v_rcp_f32_e32 v75, v75
	v_add_f32_e32 v79, 1.0, v79
	v_rcp_f32_e32 v83, v79
	v_mul_f32_e32 v79, 0xbfb8aa3b, v81
	v_exp_f32_e32 v79, v79
	s_nop 0
	v_add_f32_e32 v79, 1.0, v79
	v_mul_f32_e32 v80, v22, v78
	v_mul_f32_e32 v81, v23, v78
	v_rcp_f32_e32 v84, v79
	v_mul_f32_e32 v80, 0xbfb8aa3b, v80
	v_exp_f32_e32 v80, v80
	v_mul_f32_e32 v79, v21, v78
	v_mul_f32_e32 v78, v20, v78
	v_add_f32_e32 v80, 1.0, v80
	v_mul_f32_e32 v78, 0xbfb8aa3b, v78
	v_mul_f32_e32 v79, 0xbfb8aa3b, v79
	v_rcp_f32_e32 v85, v80
	v_mul_f32_e32 v80, 0xbfb8aa3b, v81
	v_exp_f32_e32 v78, v78
	v_exp_f32_e32 v79, v79
	v_exp_f32_e32 v80, v80
	v_add_f32_e32 v78, 1.0, v78
	v_add_f32_e32 v79, 1.0, v79
	v_add_f32_e32 v80, 1.0, v80
	v_rcp_f32_e32 v78, v78
	v_rcp_f32_e32 v79, v79
	v_rcp_f32_e32 v86, v80
	v_lshl_add_u64 v[80:81], v[76:77], 0, v[68:69]
	v_add_co_u32_e32 v80, vcc, s2, v80
	v_cvt_pk_bf16_f32 v76, v75, v82
	v_cvt_pk_bf16_f32 v77, v83, v84
	v_cvt_pk_bf16_f32 v78, v78, v79
	v_cvt_pk_bf16_f32 v79, v85, v86
	v_addc_co_u32_e32 v81, vcc, 0, v81, vcc
	global_store_dwordx4 v[80:81], v[76:79], off offset:768
	s_nop 1
	v_mul_f32_e32 v78, v16, v74
	v_mul_f32_e32 v79, v17, v74
	v_mul_f32_e32 v76, v18, v74
	v_mul_f32_e32 v77, v19, v74
	v_mul_f32_e32 v75, 0xbfb8aa3b, v78
	v_exp_f32_e32 v75, v75
	s_nop 0
	v_add_f32_e32 v75, 1.0, v75
	v_rcp_f32_e32 v78, v75
	v_mul_f32_e32 v75, 0xbfb8aa3b, v79
	v_exp_f32_e32 v75, v75
	s_nop 0
	v_add_f32_e32 v75, 1.0, v75
	v_rcp_f32_e32 v79, v75
	v_mul_f32_e32 v75, 0xbfb8aa3b, v76
	v_exp_f32_e32 v75, v75
	s_nop 0
	v_add_f32_e32 v75, 1.0, v75
	v_rcp_f32_e32 v80, v75
	v_mul_f32_e32 v75, 0xbfb8aa3b, v77
	v_exp_f32_e32 v75, v75
	s_nop 0
	v_add_f32_e32 v75, 1.0, v75
	v_mul_f32_e32 v76, v14, v74
	v_mul_f32_e32 v77, v15, v74
	v_rcp_f32_e32 v81, v75
	v_mul_f32_e32 v76, 0xbfb8aa3b, v76
	v_exp_f32_e32 v76, v76
	v_mul_f32_e32 v75, v13, v74
	v_mul_f32_e32 v74, v12, v74
	v_add_f32_e32 v76, 1.0, v76
	v_mul_f32_e32 v74, 0xbfb8aa3b, v74
	v_mul_f32_e32 v75, 0xbfb8aa3b, v75
	v_rcp_f32_e32 v82, v76
	v_mul_f32_e32 v76, 0xbfb8aa3b, v77
	v_exp_f32_e32 v74, v74
	v_exp_f32_e32 v75, v75
	v_exp_f32_e32 v76, v76
	v_add_f32_e32 v74, 1.0, v74
	v_add_f32_e32 v75, 1.0, v75
	v_add_f32_e32 v76, 1.0, v76
	v_rcp_f32_e32 v74, v74
	v_rcp_f32_e32 v75, v75
	v_rcp_f32_e32 v83, v76
	v_lshl_add_u64 v[76:77], v[72:73], 0, v[68:69]
	v_add_co_u32_e32 v76, vcc, s2, v76
	v_cvt_pk_bf16_f32 v72, v78, v79
	v_cvt_pk_bf16_f32 v73, v80, v81
	v_cvt_pk_bf16_f32 v74, v74, v75
	v_cvt_pk_bf16_f32 v75, v82, v83
	v_addc_co_u32_e32 v77, vcc, 0, v77, vcc
	global_store_dwordx4 v[76:77], v[72:75], off offset:768
	s_nop 1
	v_mul_f32_e32 v72, v10, v2
	v_mul_f32_e32 v73, v11, v2
	v_mul_f32_e32 v74, v8, v2
	v_mul_f32_e32 v75, v9, v2
	v_mul_f32_e32 v72, 0xbfb8aa3b, v72
	v_exp_f32_e32 v72, v72
	v_mul_f32_e32 v74, 0xbfb8aa3b, v74
	v_exp_f32_e32 v74, v74
	v_add_f32_e32 v72, 1.0, v72
	v_rcp_f32_e32 v78, v72
	v_mul_f32_e32 v72, 0xbfb8aa3b, v73
	v_exp_f32_e32 v72, v72
	v_add_f32_e32 v74, 1.0, v74
	v_rcp_f32_e32 v76, v74
	v_mul_f32_e32 v74, 0xbfb8aa3b, v75
	v_add_f32_e32 v72, 1.0, v72
	v_rcp_f32_e32 v79, v72
	v_mul_f32_e32 v72, v6, v2
	v_mul_f32_e32 v73, v7, v2
	v_exp_f32_e32 v74, v74
	v_mul_f32_e32 v72, 0xbfb8aa3b, v72
	v_exp_f32_e32 v72, v72
	v_add_f32_e32 v74, 1.0, v74
	v_rcp_f32_e32 v77, v74
	v_mul_f32_e32 v74, v4, v2
	v_mul_f32_e32 v75, v5, v2
	v_add_f32_e32 v72, 1.0, v72
	v_mul_f32_e32 v2, 0xbfb8aa3b, v74
	v_mul_f32_e32 v74, 0xbfb8aa3b, v75
	v_rcp_f32_e32 v75, v72
	v_mul_f32_e32 v72, 0xbfb8aa3b, v73
	v_exp_f32_e32 v2, v2
	v_exp_f32_e32 v74, v74
	v_exp_f32_e32 v72, v72
	v_add_f32_e32 v2, 1.0, v2
	v_add_f32_e32 v74, 1.0, v74
	v_add_f32_e32 v72, 1.0, v72
	v_rcp_f32_e32 v2, v2
	v_rcp_f32_e32 v74, v74
	v_rcp_f32_e32 v80, v72
	v_lshl_add_u64 v[72:73], v[70:71], 0, v[68:69]
	v_add_co_u32_e32 v72, vcc, s2, v72
	v_cvt_pk_bf16_f32 v68, v76, v77
	v_cvt_pk_bf16_f32 v69, v78, v79
	v_cvt_pk_bf16_f32 v70, v2, v74
	v_cvt_pk_bf16_f32 v71, v75, v80
	v_addc_co_u32_e32 v73, vcc, 0, v73, vcc
	global_store_dwordx4 v[72:73], v[68:71], off offset:768

.LBB0_178:
	s_and_b64 vcc, exec, s[4:5]
	s_cbranch_vccz .LBB0_181
	s_lshl_b32 s4, s48, 8
	s_add_i32 s4, s4, s31
	v_or_b32_e32 v70, s4, v181
	v_ashrrev_i32_e32 v71, 31, v70
	v_lshl_add_u64 v[78:79], v[70:71], 2, s[70:71]
	v_mov_b32_e32 v80, v164
	v_mov_b32_e32 v82, v165
	v_mov_b32_e32 v74, v166
	v_mov_b32_e32 v72, v167
	s_or_b32 s5, s16, s49
	v_or_b32_e32 v2, s5, v242
	s_add_i32 s20, s5, 0xfffff180
	s_add_i32 s21, s4, 0xffffc000
	s_movk_i32 s36, 0x4000
	v_bitop3_b32 v76, s5, 56, v242 bitop3:0xc8
	s_ashr_i32 s5, s20, 6
	v_add_u32_e32 v2, 0xfffff184, v2
	s_ashr_i32 s20, s4, 11
	v_bitop3_b32 v71, s4, v250, v181 bitop3:0xc8
	s_lshr_b32 s21, s21, 4
	v_ashrrev_i32_e32 v75, 6, v2
	v_add_u32_e32 v2, 0x80, v71
	v_mov_b32_e32 v71, s20
	v_mov_b32_e32 v81, s21
	v_cmp_gt_i32_e32 vcc, s36, v70
	v_mov_b64_e32 v[68:69], s[92:93]
	v_or_b32_e32 v73, 4, v76
	v_cndmask_b32_e32 v78, v81, v71, vcc
	v_lshlrev_b32_e32 v79, 1, v78
	v_add_u32_e32 v78, s5, v79
	v_add_u32_e32 v84, v79, v75
	v_ashrrev_i32_e32 v79, 31, v78
	v_lshlrev_b64 v[78:79], 6, v[78:79]
	v_or_b32_e32 v78, v78, v76
	v_cndmask_b32_e32 v2, v244, v2, vcc
	v_ashrrev_i32_e32 v85, 31, v84
	v_mad_u64_u32 v[86:87], s[20:21], v78, s89, v[68:69]
	v_lshlrev_b32_e32 v2, 1, v2
	v_lshlrev_b64 v[84:85], 6, v[84:85]
	v_mad_i32_i24 v87, v79, s89, v87
	v_or_b32_e32 v81, v84, v73
	v_lshl_add_u64 v[78:79], v[86:87], 0, v[2:3]
	s_movk_i32 s40, 0x1000
	v_mad_u64_u32 v[88:89], s[20:21], v81, s89, v[68:69]
	v_add_co_u32_e32 v86, vcc, s40, v78
	v_mad_i32_i24 v89, v85, s89, v89
	s_nop 0
	v_addc_co_u32_e32 v87, vcc, 0, v79, vcc
	s_movk_i32 s37, 0x2000
	v_lshl_add_u64 v[84:85], v[88:89], 0, v[2:3]
	v_add_co_u32_e32 v88, vcc, s37, v78
	s_movk_i32 s41, 0x3000
	s_nop 0
	v_addc_co_u32_e32 v89, vcc, 0, v79, vcc
	v_add_co_u32_e32 v90, vcc, s41, v78
	s_movk_i32 s20, 0x7df
	s_nop 0
	v_addc_co_u32_e32 v91, vcc, 0, v79, vcc
	v_add_co_u32_e32 v92, vcc, s40, v84
	v_or_b32_e32 v77, 16, v70
	s_nop 0
	v_addc_co_u32_e32 v93, vcc, 0, v85, vcc
	v_add_co_u32_e32 v94, vcc, s37, v84
	v_or_b32_e32 v102, 32, v70
	s_nop 0
	v_addc_co_u32_e32 v95, vcc, 0, v85, vcc
	v_or_b32_e32 v103, 48, v70
	v_mul_f32_e32 v98, v64, v80
	v_mul_f32_e32 v99, v65, v80
	v_mul_f32_e32 v96, v66, v80
	v_mul_f32_e32 v97, v67, v80
	v_mul_f32_e32 v100, v62, v80
	v_mul_f32_e32 v101, v63, v80
	v_mul_f32_e32 v81, v61, v80
	v_mul_f32_e32 v80, v60, v80
	v_cvt_pk_bf16_f32 v2, v98, s0
	v_cvt_pk_bf16_f32 v83, v99, s0
	v_cvt_pk_bf16_f32 v96, v96, s0
	v_cvt_pk_bf16_f32 v97, v97, s0
	v_cvt_pk_bf16_f32 v80, v80, s0
	v_cvt_pk_bf16_f32 v81, v81, s0
	v_cvt_pk_bf16_f32 v98, v100, s0
	global_store_short v[78:79], v2, off
	global_store_short v[86:87], v83, off offset:256
	global_store_short v[88:89], v96, off offset:512
	global_store_short v[90:91], v97, off offset:768
	global_store_short v[84:85], v80, off
	global_store_short v[92:93], v81, off offset:256
	global_store_short v[94:95], v98, off offset:512
	v_add_co_u32_e32 v78, vcc, s41, v84
	v_bitop3_b32 v2, v70, s20, 16 bitop3:0xc8
	s_add_i32 s20, s4, 0xffffc010
	v_cvt_pk_bf16_f32 v99, v101, s0
	v_addc_co_u32_e32 v79, vcc, 0, v85, vcc
	s_lshr_b32 s20, s20, 4
	global_store_short v[78:79], v99, off offset:768
	v_mul_f32_e32 v78, v58, v82
	v_mul_f32_e32 v79, v59, v82
	v_mul_f32_e32 v80, v56, v82
	v_mul_f32_e32 v81, v57, v82
	v_mov_b32_e32 v83, s20
	v_cmp_gt_i32_e32 vcc, s36, v77
	v_add_u32_e32 v2, 0x80, v2
	v_cvt_pk_bf16_f32 v80, v80, s0
	v_cndmask_b32_e32 v77, v83, v71, vcc
	v_lshlrev_b32_e32 v77, 1, v77
	v_add_u32_e32 v84, s5, v77
	v_ashrrev_i32_e32 v85, 31, v84
	v_lshlrev_b64 v[84:85], 6, v[84:85]
	v_or_b32_e32 v83, v84, v76
	v_cndmask_b32_e32 v2, v244, v2, vcc
	v_mad_u64_u32 v[86:87], s[20:21], v83, s89, v[68:69]
	v_mad_i32_i24 v87, v85, s89, v87
	v_lshlrev_b32_e32 v2, 1, v2
	v_lshl_add_u64 v[84:85], v[86:87], 0, v[2:3]
	global_store_short v[84:85], v80, off
	v_add_co_u32_e32 v80, vcc, s40, v84
	v_cvt_pk_bf16_f32 v83, v81, s0
	s_nop 0
	v_addc_co_u32_e32 v81, vcc, 0, v85, vcc
	global_store_short v[80:81], v83, off offset:256
	v_add_co_u32_e32 v80, vcc, s37, v84
	v_cvt_pk_bf16_f32 v78, v78, s0
	s_nop 0
	v_addc_co_u32_e32 v81, vcc, 0, v85, vcc
	global_store_short v[80:81], v78, off offset:512
	v_add_co_u32_e32 v78, vcc, s41, v84
	v_cvt_pk_bf16_f32 v80, v79, s0
	s_nop 0
	v_addc_co_u32_e32 v79, vcc, 0, v85, vcc
	global_store_short v[78:79], v80, off offset:768
	v_mul_f32_e32 v78, v54, v82
	v_mul_f32_e32 v79, v55, v82
	v_mul_f32_e32 v80, v52, v82
	v_mul_f32_e32 v81, v53, v82
	v_add_u32_e32 v82, v77, v75
	v_ashrrev_i32_e32 v83, 31, v82
	v_lshlrev_b64 v[82:83], 6, v[82:83]
	v_or_b32_e32 v77, v82, v73
	v_mad_u64_u32 v[84:85], s[20:21], v77, s89, v[68:69]
	v_mad_i32_i24 v85, v83, s89, v85
	v_lshl_add_u64 v[82:83], v[84:85], 0, v[2:3]
	v_cvt_pk_bf16_f32 v2, v80, s0
	v_add_co_u32_e32 v80, vcc, s40, v82
	global_store_short v[82:83], v2, off
	v_cvt_pk_bf16_f32 v2, v81, s0
	v_addc_co_u32_e32 v81, vcc, 0, v83, vcc
	global_store_short v[80:81], v2, off offset:256
	v_add_co_u32_e32 v80, vcc, s37, v82
	v_cvt_pk_bf16_f32 v2, v78, s0
	s_nop 0
	v_addc_co_u32_e32 v81, vcc, 0, v83, vcc
	v_add_co_u32_e32 v78, vcc, s41, v82
	global_store_short v[80:81], v2, off offset:512
	v_cvt_pk_bf16_f32 v2, v79, s0
	v_addc_co_u32_e32 v79, vcc, 0, v83, vcc
	s_movk_i32 s20, 0x7ef
	global_store_short v[78:79], v2, off offset:768
	v_bitop3_b32 v2, v70, s20, 32 bitop3:0xc8
	s_add_i32 s20, s4, 0xffffc020
	s_lshr_b32 s20, s20, 4
	v_mov_b32_e32 v77, s20
	v_cmp_gt_i32_e32 vcc, s36, v102
	v_add_u32_e32 v2, 0x80, v2
	v_mul_f32_e32 v80, v48, v74
	v_mul_f32_e32 v81, v49, v74
	v_cndmask_b32_e32 v77, v77, v71, vcc
	v_lshlrev_b32_e32 v77, 1, v77
	v_add_u32_e32 v82, s5, v77
	v_ashrrev_i32_e32 v83, 31, v82
	v_lshlrev_b64 v[82:83], 6, v[82:83]
	v_or_b32_e32 v82, v82, v76
	v_cndmask_b32_e32 v2, v244, v2, vcc
	v_mad_u64_u32 v[84:85], s[20:21], v82, s89, v[68:69]
	v_mad_i32_i24 v85, v83, s89, v85
	v_lshlrev_b32_e32 v2, 1, v2
	v_lshl_add_u64 v[82:83], v[84:85], 0, v[2:3]
	v_cvt_pk_bf16_f32 v80, v80, s0
	global_store_short v[82:83], v80, off
	v_add_co_u32_e32 v80, vcc, s40, v82
	v_cvt_pk_bf16_f32 v84, v81, s0
	s_nop 0
	v_addc_co_u32_e32 v81, vcc, 0, v83, vcc
	v_mul_f32_e32 v78, v50, v74
	v_mul_f32_e32 v79, v51, v74
	global_store_short v[80:81], v84, off offset:256
	v_add_co_u32_e32 v80, vcc, s37, v82
	v_cvt_pk_bf16_f32 v78, v78, s0
	s_nop 0
	v_addc_co_u32_e32 v81, vcc, 0, v83, vcc
	global_store_short v[80:81], v78, off offset:512
	v_add_co_u32_e32 v78, vcc, s41, v82
	v_add_u32_e32 v82, v77, v75
	v_cvt_pk_bf16_f32 v80, v79, s0
	v_addc_co_u32_e32 v79, vcc, 0, v83, vcc
	v_ashrrev_i32_e32 v83, 31, v82
	v_lshlrev_b64 v[82:83], 6, v[82:83]
	global_store_short v[78:79], v80, off offset:768
	v_mul_f32_e32 v78, v46, v74
	v_mul_f32_e32 v79, v47, v74
	v_mul_f32_e32 v80, v44, v74
	v_mul_f32_e32 v81, v45, v74
	v_or_b32_e32 v74, v82, v73
	v_mad_u64_u32 v[84:85], s[20:21], v74, s89, v[68:69]
	v_mad_i32_i24 v85, v83, s89, v85
	v_lshl_add_u64 v[82:83], v[84:85], 0, v[2:3]
	v_cvt_pk_bf16_f32 v2, v80, s0
	v_add_co_u32_e32 v80, vcc, s40, v82
	global_store_short v[82:83], v2, off
	v_cvt_pk_bf16_f32 v2, v81, s0
	v_addc_co_u32_e32 v81, vcc, 0, v83, vcc
	global_store_short v[80:81], v2, off offset:256
	v_add_co_u32_e32 v80, vcc, s37, v82
	v_cvt_pk_bf16_f32 v2, v78, s0
	s_nop 0
	v_addc_co_u32_e32 v81, vcc, 0, v83, vcc
	v_add_co_u32_e32 v78, vcc, s41, v82
	global_store_short v[80:81], v2, off offset:512
	v_cvt_pk_bf16_f32 v2, v79, s0
	v_addc_co_u32_e32 v79, vcc, 0, v83, vcc
	s_movk_i32 s20, 0x7ff
	global_store_short v[78:79], v2, off offset:768
	v_bitop3_b32 v2, v70, s20, 48 bitop3:0xc8
	s_add_i32 s20, s4, 0xffffc030
	s_lshr_b32 s20, s20, 4
	v_mov_b32_e32 v70, s20
	v_cmp_gt_i32_e32 vcc, s36, v103
	v_add_u32_e32 v2, 0x80, v2
	v_mul_f32_e32 v80, v40, v72
	v_mul_f32_e32 v81, v41, v72
	v_cndmask_b32_e32 v70, v70, v71, vcc
	v_lshlrev_b32_e32 v74, 1, v70
	v_add_u32_e32 v70, s5, v74
	v_ashrrev_i32_e32 v71, 31, v70
	v_lshlrev_b64 v[70:71], 6, v[70:71]
	v_or_b32_e32 v70, v70, v76
	v_cndmask_b32_e32 v2, v244, v2, vcc
	v_mad_u64_u32 v[82:83], s[20:21], v70, s89, v[68:69]
	v_mad_i32_i24 v83, v71, s89, v83
	v_lshlrev_b32_e32 v2, 1, v2
	v_lshl_add_u64 v[70:71], v[82:83], 0, v[2:3]
	v_cvt_pk_bf16_f32 v77, v80, s0
	v_add_co_u32_e32 v80, vcc, s40, v70
	global_store_short v[70:71], v77, off
	v_cvt_pk_bf16_f32 v77, v81, s0
	v_addc_co_u32_e32 v81, vcc, 0, v71, vcc
	v_mul_f32_e32 v78, v42, v72
	v_mul_f32_e32 v79, v43, v72
	global_store_short v[80:81], v77, off offset:256
	v_add_co_u32_e32 v80, vcc, s37, v70
	v_cvt_pk_bf16_f32 v77, v78, s0
	s_nop 0
	v_addc_co_u32_e32 v81, vcc, 0, v71, vcc
	global_store_short v[80:81], v77, off offset:512
	v_add_u32_e32 v80, v74, v75
	v_add_co_u32_e32 v70, vcc, s41, v70
	v_ashrrev_i32_e32 v81, 31, v80
	v_cvt_pk_bf16_f32 v77, v79, s0
	v_addc_co_u32_e32 v71, vcc, 0, v71, vcc
	v_lshlrev_b64 v[80:81], 6, v[80:81]
	global_store_short v[70:71], v77, off offset:768
	v_mul_f32_e32 v70, v38, v72
	v_mul_f32_e32 v71, v39, v72
	v_mul_f32_e32 v78, v36, v72
	v_mul_f32_e32 v79, v37, v72
	v_or_b32_e32 v72, v80, v73
	v_mad_u64_u32 v[68:69], s[20:21], v72, s89, v[68:69]
	v_mad_i32_i24 v69, v81, s89, v69
	v_lshl_add_u64 v[68:69], v[68:69], 0, v[2:3]
	v_cvt_pk_bf16_f32 v2, v78, s0
	v_add_co_u32_e32 v78, vcc, 0x1000, v68
	global_store_short v[68:69], v2, off
	v_cvt_pk_bf16_f32 v2, v79, s0
	v_addc_co_u32_e32 v79, vcc, 0, v69, vcc
	global_store_short v[78:79], v2, off offset:256
	v_add_co_u32_e32 v78, vcc, 0x2000, v68
	v_cvt_pk_bf16_f32 v2, v70, s0
	s_nop 0
	v_addc_co_u32_e32 v79, vcc, 0, v69, vcc
	v_add_co_u32_e32 v68, vcc, 0x3000, v68
	s_movk_i32 s20, 0x4000
	global_store_short v[78:79], v2, off offset:512
	v_cvt_pk_bf16_f32 v2, v71, s0
	v_addc_co_u32_e32 v69, vcc, 0, v69, vcc
	s_cmp_eq_u32 s48, 64
	global_store_short v[68:69], v2, off offset:768
	s_cbranch_scc1 .LBB0_181
	s_add_i32 s20, s4, 0x80
	v_or_b32_e32 v70, s20, v181
	v_ashrrev_i32_e32 v71, 31, v70
	v_lshl_add_u64 v[78:79], v[70:71], 2, s[70:71]
	v_mov_b32_e32 v74, v246
	v_mov_b32_e32 v80, v247
	s_add_i32 s21, s4, 0xffffc080
	s_movk_i32 s37, 0x4000
	s_ashr_i32 s36, s20, 11
	v_bitop3_b32 v2, s20, v250, v181 bitop3:0xc8
	s_lshr_b32 s20, s21, 4
	v_mov_b32_e32 v72, s20
	v_mov_b32_e32 v111, s36
	v_cmp_gt_i32_e32 vcc, s37, v70
	v_mov_b64_e32 v[68:69], s[92:93]
	v_add_u32_e32 v2, 0x80, v2
	v_cndmask_b32_e32 v83, v72, v111, vcc
	v_mov_b32_e32 v82, v248
	v_mov_b32_e32 v72, v249
	v_lshlrev_b32_e32 v79, 1, v83
	v_add_u32_e32 v78, s5, v79
	v_add_u32_e32 v84, v79, v75
	v_ashrrev_i32_e32 v79, 31, v78
	v_lshlrev_b64 v[78:79], 6, v[78:79]
	s_movk_i32 s20, 0x7df
	v_or_b32_e32 v78, v78, v76
	v_bitop3_b32 v81, v70, s20, 16 bitop3:0xc8
	v_cndmask_b32_e32 v2, v244, v2, vcc
	v_ashrrev_i32_e32 v85, 31, v84
	v_mad_u64_u32 v[86:87], s[20:21], v78, s89, v[68:69]
	v_lshlrev_b32_e32 v2, 1, v2
	v_lshlrev_b64 v[84:85], 6, v[84:85]
	v_mad_i32_i24 v87, v79, s89, v87
	v_or_b32_e32 v83, v84, v73
	v_lshl_add_u64 v[78:79], v[86:87], 0, v[2:3]
	v_mad_u64_u32 v[88:89], s[20:21], v83, s89, v[68:69]
	v_add_co_u32_e32 v86, vcc, s40, v78
	v_mad_i32_i24 v89, v85, s89, v89
	s_nop 0
	v_addc_co_u32_e32 v87, vcc, 0, v79, vcc
	s_movk_i32 s36, 0x2000
	v_lshl_add_u64 v[84:85], v[88:89], 0, v[2:3]
	v_add_co_u32_e32 v88, vcc, s36, v78
	s_add_i32 s20, s4, 0xffffc090
	s_nop 0
	v_addc_co_u32_e32 v89, vcc, 0, v79, vcc
	v_add_co_u32_e32 v90, vcc, s41, v78
	v_or_b32_e32 v71, 16, v70
	s_nop 0
	v_addc_co_u32_e32 v91, vcc, 0, v79, vcc
	v_add_co_u32_e32 v92, vcc, s40, v84
	s_lshr_b32 s20, s20, 4
	s_nop 0
	v_addc_co_u32_e32 v93, vcc, 0, v85, vcc
	v_add_co_u32_e32 v94, vcc, s36, v84
	v_or_b32_e32 v77, 32, v70
	s_nop 0
	v_addc_co_u32_e32 v95, vcc, 0, v85, vcc
	v_add_co_u32_e32 v96, vcc, s41, v84
	v_or_b32_e32 v110, 48, v70
	s_nop 0
	v_addc_co_u32_e32 v97, vcc, 0, v85, vcc
	v_cmp_gt_i32_e32 vcc, s37, v71
	v_mul_f32_e32 v100, v32, v74
	v_mul_f32_e32 v101, v33, v74
	v_mul_f32_e32 v98, v34, v74
	v_mul_f32_e32 v99, v35, v74
	v_mul_f32_e32 v102, v30, v74
	v_mul_f32_e32 v103, v31, v74
	v_mul_f32_e32 v104, v28, v74
	v_mul_f32_e32 v105, v29, v74
	v_cvt_pk_bf16_f32 v2, v100, s0
	v_cvt_pk_bf16_f32 v74, v101, s0
	v_cvt_pk_bf16_f32 v83, v98, s0
	v_cvt_pk_bf16_f32 v98, v99, s0
	v_cvt_pk_bf16_f32 v99, v104, s0
	v_cvt_pk_bf16_f32 v100, v105, s0
	v_cvt_pk_bf16_f32 v101, v102, s0
	v_cvt_pk_bf16_f32 v102, v103, s0
	global_store_short v[78:79], v2, off
	global_store_short v[86:87], v74, off offset:256
	global_store_short v[88:89], v83, off offset:512
	global_store_short v[90:91], v98, off offset:768
	global_store_short v[84:85], v99, off
	global_store_short v[92:93], v100, off offset:256
	global_store_short v[94:95], v101, off offset:512
	global_store_short v[96:97], v102, off offset:768
	v_mov_b32_e32 v74, s20
	v_cndmask_b32_e32 v71, v74, v111, vcc
	v_lshlrev_b32_e32 v71, 1, v71
	v_add_u32_e32 v78, s5, v71
	v_ashrrev_i32_e32 v79, 31, v78
	v_lshlrev_b64 v[78:79], 6, v[78:79]
	v_add_u32_e32 v2, 0x80, v81
	v_or_b32_e32 v74, v78, v76
	v_cndmask_b32_e32 v2, v244, v2, vcc
	v_mad_u64_u32 v[84:85], s[20:21], v74, s89, v[68:69]
	v_mad_i32_i24 v85, v79, s89, v85
	v_lshlrev_b32_e32 v2, 1, v2
	v_mul_f32_e32 v108, v24, v80
	v_mul_f32_e32 v109, v25, v80
	v_lshl_add_u64 v[78:79], v[84:85], 0, v[2:3]
	v_cvt_pk_bf16_f32 v74, v108, s0
	v_add_co_u32_e32 v84, vcc, s40, v78
	global_store_short v[78:79], v74, off
	v_cvt_pk_bf16_f32 v74, v109, s0
	v_addc_co_u32_e32 v85, vcc, 0, v79, vcc
	v_mul_f32_e32 v106, v26, v80
	v_mul_f32_e32 v107, v27, v80
	global_store_short v[84:85], v74, off offset:256
	v_add_co_u32_e32 v84, vcc, s36, v78
	v_cvt_pk_bf16_f32 v74, v106, s0
	s_nop 0
	v_addc_co_u32_e32 v85, vcc, 0, v79, vcc
	global_store_short v[84:85], v74, off offset:512
	v_add_u32_e32 v84, v71, v75
	v_ashrrev_i32_e32 v85, 31, v84
	v_lshlrev_b64 v[84:85], 6, v[84:85]
	v_or_b32_e32 v71, v84, v73
	v_add_co_u32_e32 v78, vcc, s41, v78
	v_mad_u64_u32 v[86:87], s[20:21], v71, s89, v[68:69]
	v_cvt_pk_bf16_f32 v74, v107, s0
	v_addc_co_u32_e32 v79, vcc, 0, v79, vcc
	v_mad_i32_i24 v87, v85, s89, v87
	global_store_short v[78:79], v74, off offset:768
	v_mul_f32_e32 v78, v22, v80
	v_mul_f32_e32 v79, v23, v80
	v_mul_f32_e32 v81, v21, v80
	v_mul_f32_e32 v80, v20, v80
	v_lshl_add_u64 v[84:85], v[86:87], 0, v[2:3]
	v_cvt_pk_bf16_f32 v2, v80, s0
	v_add_co_u32_e32 v80, vcc, s40, v84
	global_store_short v[84:85], v2, off
	v_cvt_pk_bf16_f32 v2, v81, s0
	v_addc_co_u32_e32 v81, vcc, 0, v85, vcc
	global_store_short v[80:81], v2, off offset:256
	v_add_co_u32_e32 v80, vcc, s36, v84
	v_cvt_pk_bf16_f32 v2, v78, s0
	s_nop 0
	v_addc_co_u32_e32 v81, vcc, 0, v85, vcc
	v_add_co_u32_e32 v78, vcc, s41, v84
	global_store_short v[80:81], v2, off offset:512
	v_cvt_pk_bf16_f32 v2, v79, s0
	v_addc_co_u32_e32 v79, vcc, 0, v85, vcc
	s_movk_i32 s20, 0x7ef
	global_store_short v[78:79], v2, off offset:768
	v_bitop3_b32 v2, v70, s20, 32 bitop3:0xc8
	s_add_i32 s20, s4, 0xffffc0a0
	s_lshr_b32 s20, s20, 4
	v_mov_b32_e32 v71, s20
	v_cmp_gt_i32_e32 vcc, s37, v77
	v_add_u32_e32 v2, 0x80, v2
	v_mul_f32_e32 v80, v16, v82
	v_mul_f32_e32 v81, v17, v82
	v_cndmask_b32_e32 v71, v71, v111, vcc
	v_lshlrev_b32_e32 v71, 1, v71
	v_add_u32_e32 v84, s5, v71
	v_ashrrev_i32_e32 v85, 31, v84
	v_lshlrev_b64 v[84:85], 6, v[84:85]
	v_or_b32_e32 v74, v84, v76
	v_cndmask_b32_e32 v2, v244, v2, vcc
	v_mad_u64_u32 v[86:87], s[20:21], v74, s89, v[68:69]
	v_mad_i32_i24 v87, v85, s89, v87
	v_lshlrev_b32_e32 v2, 1, v2
	v_lshl_add_u64 v[84:85], v[86:87], 0, v[2:3]
	v_cvt_pk_bf16_f32 v74, v80, s0
	v_add_co_u32_e32 v80, vcc, s40, v84
	global_store_short v[84:85], v74, off
	v_cvt_pk_bf16_f32 v74, v81, s0
	v_addc_co_u32_e32 v81, vcc, 0, v85, vcc
	global_store_short v[80:81], v74, off offset:256
	v_add_co_u32_e32 v80, vcc, s36, v84
	v_mul_f32_e32 v78, v18, v82
	v_mul_f32_e32 v79, v19, v82
	s_nop 0
	v_addc_co_u32_e32 v81, vcc, 0, v85, vcc
	v_cvt_pk_bf16_f32 v74, v78, s0
	v_add_co_u32_e32 v78, vcc, s41, v84
	global_store_short v[80:81], v74, off offset:512
	v_cvt_pk_bf16_f32 v74, v79, s0
	v_addc_co_u32_e32 v79, vcc, 0, v85, vcc
	global_store_short v[78:79], v74, off offset:768
	v_mul_f32_e32 v78, v14, v82
	v_mul_f32_e32 v79, v15, v82
	v_mul_f32_e32 v80, v12, v82
	v_mul_f32_e32 v81, v13, v82
	v_add_u32_e32 v82, v71, v75
	v_ashrrev_i32_e32 v83, 31, v82
	v_lshlrev_b64 v[82:83], 6, v[82:83]
	v_or_b32_e32 v71, v82, v73
	v_mad_u64_u32 v[84:85], s[20:21], v71, s89, v[68:69]
	v_mad_i32_i24 v85, v83, s89, v85
	v_lshl_add_u64 v[82:83], v[84:85], 0, v[2:3]
	v_cvt_pk_bf16_f32 v2, v80, s0
	v_add_co_u32_e32 v80, vcc, s40, v82
	global_store_short v[82:83], v2, off
	v_cvt_pk_bf16_f32 v2, v81, s0
	v_addc_co_u32_e32 v81, vcc, 0, v83, vcc
	global_store_short v[80:81], v2, off offset:256
	v_add_co_u32_e32 v80, vcc, s36, v82
	v_cvt_pk_bf16_f32 v2, v78, s0
	s_nop 0
	v_addc_co_u32_e32 v81, vcc, 0, v83, vcc
	v_add_co_u32_e32 v78, vcc, s41, v82
	s_addk_i32 s4, 0xc0b0
	s_movk_i32 s20, 0x4000
	global_store_short v[80:81], v2, off offset:512
	v_cvt_pk_bf16_f32 v2, v79, s0
	v_addc_co_u32_e32 v79, vcc, 0, v83, vcc
	s_movk_i32 s21, 0x7ff
	s_lshr_b32 s4, s4, 4
	global_store_short v[78:79], v2, off offset:768
	v_bitop3_b32 v2, v70, s21, 48 bitop3:0xc8
	v_mov_b32_e32 v70, s4
	v_cmp_gt_i32_e32 vcc, s20, v110
	v_add_u32_e32 v2, 0x80, v2
	v_mul_f32_e32 v80, v8, v72
	v_mul_f32_e32 v81, v9, v72
	v_cndmask_b32_e32 v70, v70, v111, vcc
	v_lshlrev_b32_e32 v74, 1, v70
	v_add_u32_e32 v70, s5, v74
	v_ashrrev_i32_e32 v71, 31, v70
	v_lshlrev_b64 v[70:71], 6, v[70:71]
	v_or_b32_e32 v70, v70, v76
	v_cndmask_b32_e32 v2, v244, v2, vcc
	v_mad_u64_u32 v[76:77], s[4:5], v70, s89, v[68:69]
	v_mad_i32_i24 v77, v71, s89, v77
	v_lshlrev_b32_e32 v2, 1, v2
	v_lshl_add_u64 v[70:71], v[76:77], 0, v[2:3]
	v_cvt_pk_bf16_f32 v76, v80, s0
	global_store_short v[70:71], v76, off
	v_add_co_u32_e32 v76, vcc, s40, v70
	v_cvt_pk_bf16_f32 v80, v81, s0
	s_nop 0
	v_addc_co_u32_e32 v77, vcc, 0, v71, vcc
	global_store_short v[76:77], v80, off offset:256
	v_add_co_u32_e32 v76, vcc, s36, v70
	v_mul_f32_e32 v78, v10, v72
	v_mul_f32_e32 v79, v11, v72
	s_nop 0
	v_addc_co_u32_e32 v77, vcc, 0, v71, vcc
	v_add_u32_e32 v74, v74, v75
	v_cvt_pk_bf16_f32 v78, v78, s0
	v_add_co_u32_e32 v70, vcc, s41, v70
	v_ashrrev_i32_e32 v75, 31, v74
	global_store_short v[76:77], v78, off offset:512
	v_cvt_pk_bf16_f32 v76, v79, s0
	v_addc_co_u32_e32 v71, vcc, 0, v71, vcc
	v_lshlrev_b64 v[74:75], 6, v[74:75]
	global_store_short v[70:71], v76, off offset:768
	v_mul_f32_e32 v70, v6, v72
	v_mul_f32_e32 v71, v7, v72
	v_mul_f32_e32 v76, v4, v72
	v_mul_f32_e32 v77, v5, v72
	v_or_b32_e32 v72, v74, v73
	v_mad_u64_u32 v[68:69], s[4:5], v72, s89, v[68:69]
	v_mad_i32_i24 v69, v75, s89, v69
	v_lshl_add_u64 v[68:69], v[68:69], 0, v[2:3]
	v_cvt_pk_bf16_f32 v2, v76, s0
	v_add_co_u32_e32 v72, vcc, 0x1000, v68
	global_store_short v[68:69], v2, off
	v_cvt_pk_bf16_f32 v2, v77, s0
	v_addc_co_u32_e32 v73, vcc, 0, v69, vcc
	global_store_short v[72:73], v2, off offset:256
	v_add_co_u32_e32 v72, vcc, 0x2000, v68
	v_cvt_pk_bf16_f32 v2, v70, s0
	s_nop 0
	v_addc_co_u32_e32 v73, vcc, 0, v69, vcc
	v_add_co_u32_e32 v68, vcc, 0x3000, v68
	global_store_short v[72:73], v2, off offset:512
	v_cvt_pk_bf16_f32 v2, v71, s0
	v_addc_co_u32_e32 v69, vcc, 0, v69, vcc
	global_store_short v[68:69], v2, off offset:768

.LBB0_207:
	s_or_b64 exec, exec, s[2:3]
	s_waitcnt vmcnt(0)
	s_and_saveexec_b64 s[2:3], s[38:39]
	v_mov_b32_e32 v126, v81
	v_mov_b32_e32 v124, v83
	v_mov_b32_e32 v114, v69
	v_mov_b32_e32 v128, v71
	v_mov_b32_e32 v132, v85
	v_mov_b32_e32 v130, v87
	v_mov_b32_e32 v118, v73
	v_mov_b32_e32 v134, v75
	v_mov_b32_e32 v138, v93
	v_mov_b32_e32 v136, v95
	v_mov_b32_e32 v122, v77
	v_mov_b32_e32 v140, v79
	v_mov_b32_e32 v144, v97
	v_mov_b32_e32 v142, v99
	v_mov_b32_e32 v2, v89
	v_mov_b32_e32 v146, v91
	s_or_b64 exec, exec, s[2:3]
	v_mul_f32_e32 v148, v66, v102
	v_mul_f32_e32 v149, v67, v102
	v_mul_f32_e32 v150, v64, v102
	v_mul_f32_e32 v151, v65, v102
	v_pk_mul_f32 v[124:125], v[148:149], v[124:125] op_sel:[1,0] op_sel_hi:[0,0]
	v_pk_mul_f32 v[126:127], v[150:151], v[126:127] op_sel:[1,0] op_sel_hi:[0,0]
	v_pk_fma_f32 v[152:153], v[150:151], v[80:81], v[126:127] op_sel_hi:[1,0,1] neg_lo:[0,0,1] neg_hi:[0,0,1]
	v_pk_fma_f32 v[80:81], v[150:151], v[80:81], v[126:127] op_sel_hi:[1,0,1]
	v_pk_fma_f32 v[126:127], v[148:149], v[82:83], v[124:125] op_sel_hi:[1,0,1] neg_lo:[0,0,1] neg_hi:[0,0,1]
	v_pk_fma_f32 v[82:83], v[148:149], v[82:83], v[124:125] op_sel_hi:[1,0,1]
	v_mul_f32_e32 v124, v62, v102
	v_mul_f32_e32 v125, v63, v102
	v_mul_f32_e32 v103, v61, v102
	v_mul_f32_e32 v102, v60, v102
	v_mov_b32_e32 v127, v83
	s_mov_b32 s4, 0x3e000000
	v_pk_mul_f32 v[114:115], v[102:103], v[114:115] op_sel:[1,0] op_sel_hi:[0,0]
	v_mul_f32_e32 v82, s4, v126
	v_mul_f32_e32 v83, s4, v127
	v_pk_fma_f32 v[126:127], v[102:103], v[68:69], v[114:115] op_sel_hi:[1,0,1] neg_lo:[0,0,1] neg_hi:[0,0,1]
	v_pk_fma_f32 v[68:69], v[102:103], v[68:69], v[114:115] op_sel_hi:[1,0,1]
	v_pk_mul_f32 v[102:103], v[124:125], v[128:129] op_sel:[1,0] op_sel_hi:[0,0]
	s_ashr_i32 s75, s74, 31
	v_pk_fma_f32 v[114:115], v[124:125], v[70:71], v[102:103] op_sel_hi:[1,0,1] neg_lo:[0,0,1] neg_hi:[0,0,1]
	v_pk_fma_f32 v[70:71], v[124:125], v[70:71], v[102:103] op_sel_hi:[1,0,1]
	v_mov_b32_e32 v127, v69
	v_lshlrev_b64 v[68:69], 10, v[104:105]
	v_lshl_add_u64 v[102:103], s[74:75], 0, v[178:179]
	v_mov_b32_e32 v153, v81
	v_lshl_add_u64 v[68:69], s[94:95], 0, v[68:69]
	v_lshlrev_b64 v[102:103], 1, v[102:103]
	v_mul_f32_e32 v80, s4, v152
	v_mul_f32_e32 v81, s4, v153
	v_mov_b32_e32 v115, v71
	v_lshl_add_u64 v[124:125], v[68:69], 0, v[102:103]
	s_mov_b32 s2, 0x847e000
	v_mul_f32_e32 v114, s4, v114
	v_mul_f32_e32 v115, s4, v115
	v_mul_f32_e32 v70, s4, v126
	v_mul_f32_e32 v71, s4, v127
	v_cvt_pk_bf16_f32 v68, v80, v81
	v_add_co_u32_e32 v80, vcc, s2, v124
	v_cvt_pk_bf16_f32 v69, v82, v83
	v_cvt_pk_bf16_f32 v70, v70, v71
	v_cvt_pk_bf16_f32 v71, v114, v115
	v_addc_co_u32_e32 v81, vcc, 0, v125, vcc
	global_store_dwordx4 v[80:81], v[68:71], off offset:2304
	v_ashrrev_i32_e32 v107, 31, v106
	v_ashrrev_i32_e32 v109, 31, v108
	v_mul_f32_e32 v70, v56, v110
	v_mul_f32_e32 v71, v57, v110
	v_mul_f32_e32 v68, v58, v110
	v_mul_f32_e32 v69, v59, v110
	v_pk_mul_f32 v[80:81], v[70:71], v[132:133] op_sel:[1,0] op_sel_hi:[0,0]
	v_pk_fma_f32 v[82:83], v[70:71], v[84:85], v[80:81] op_sel_hi:[1,0,1] neg_lo:[0,0,1] neg_hi:[0,0,1]
	v_pk_fma_f32 v[70:71], v[70:71], v[84:85], v[80:81] op_sel_hi:[1,0,1]
	v_pk_mul_f32 v[80:81], v[68:69], v[130:131] op_sel:[1,0] op_sel_hi:[0,0]
	v_pk_fma_f32 v[84:85], v[68:69], v[86:87], v[80:81] op_sel_hi:[1,0,1] neg_lo:[0,0,1] neg_hi:[0,0,1]
	v_pk_fma_f32 v[68:69], v[68:69], v[86:87], v[80:81] op_sel_hi:[1,0,1]
	v_mov_b32_e32 v83, v71
	v_mov_b32_e32 v85, v69
	v_mul_f32_e32 v68, s4, v82
	v_mul_f32_e32 v69, s4, v83
	v_mul_f32_e32 v82, v52, v110
	v_mul_f32_e32 v83, v53, v110
	v_mul_f32_e32 v80, s4, v84
	v_mul_f32_e32 v81, s4, v85
	v_pk_mul_f32 v[84:85], v[82:83], v[118:119] op_sel:[1,0] op_sel_hi:[0,0]
	v_mul_f32_e32 v70, v54, v110
	v_mul_f32_e32 v71, v55, v110
	v_pk_fma_f32 v[86:87], v[82:83], v[72:73], v[84:85] op_sel_hi:[1,0,1] neg_lo:[0,0,1] neg_hi:[0,0,1]
	v_pk_fma_f32 v[72:73], v[82:83], v[72:73], v[84:85] op_sel_hi:[1,0,1]
	v_pk_mul_f32 v[82:83], v[70:71], v[134:135] op_sel:[1,0] op_sel_hi:[0,0]
	v_mov_b32_e32 v87, v73
	v_lshlrev_b64 v[72:73], 10, v[106:107]
	v_pk_fma_f32 v[84:85], v[70:71], v[74:75], v[82:83] op_sel_hi:[1,0,1] neg_lo:[0,0,1] neg_hi:[0,0,1]
	v_pk_fma_f32 v[70:71], v[70:71], v[74:75], v[82:83] op_sel_hi:[1,0,1]
	v_lshl_add_u64 v[72:73], s[94:95], 0, v[72:73]
	v_mov_b32_e32 v85, v71
	v_lshl_add_u64 v[72:73], v[72:73], 0, v[102:103]
	v_mul_f32_e32 v74, s4, v84
	v_mul_f32_e32 v75, s4, v85
	v_mul_f32_e32 v70, s4, v86
	v_mul_f32_e32 v71, s4, v87
	v_add_co_u32_e32 v72, vcc, s2, v72
	v_cvt_pk_bf16_f32 v68, v68, v69
	v_cvt_pk_bf16_f32 v69, v80, v81
	v_cvt_pk_bf16_f32 v70, v70, v71
	v_cvt_pk_bf16_f32 v71, v74, v75
	v_addc_co_u32_e32 v73, vcc, 0, v73, vcc
	global_store_dwordx4 v[72:73], v[68:71], off offset:2304
	v_ashrrev_i32_e32 v113, 31, v112
	s_cmp_eq_u32 s48, 64
	v_mul_f32_e32 v70, v48, v116
	v_mul_f32_e32 v71, v49, v116
	v_mul_f32_e32 v68, v50, v116
	v_mul_f32_e32 v69, v51, v116
	v_pk_mul_f32 v[72:73], v[70:71], v[138:139] op_sel:[1,0] op_sel_hi:[0,0]
	v_pk_fma_f32 v[74:75], v[70:71], v[92:93], v[72:73] op_sel_hi:[1,0,1] neg_lo:[0,0,1] neg_hi:[0,0,1]
	v_pk_fma_f32 v[70:71], v[70:71], v[92:93], v[72:73] op_sel_hi:[1,0,1]
	v_pk_mul_f32 v[72:73], v[68:69], v[136:137] op_sel:[1,0] op_sel_hi:[0,0]
	v_pk_fma_f32 v[80:81], v[68:69], v[94:95], v[72:73] op_sel_hi:[1,0,1] neg_lo:[0,0,1] neg_hi:[0,0,1]
	v_pk_fma_f32 v[68:69], v[68:69], v[94:95], v[72:73] op_sel_hi:[1,0,1]
	v_mov_b32_e32 v75, v71
	v_mov_b32_e32 v81, v69
	v_mul_f32_e32 v68, s4, v74
	v_mul_f32_e32 v69, s4, v75
	v_mul_f32_e32 v74, v44, v116
	v_mul_f32_e32 v75, v45, v116
	v_mul_f32_e32 v72, s4, v80
	v_mul_f32_e32 v73, s4, v81
	v_pk_mul_f32 v[80:81], v[74:75], v[122:123] op_sel:[1,0] op_sel_hi:[0,0]
	v_mul_f32_e32 v70, v46, v116
	v_mul_f32_e32 v71, v47, v116
	v_pk_fma_f32 v[82:83], v[74:75], v[76:77], v[80:81] op_sel_hi:[1,0,1] neg_lo:[0,0,1] neg_hi:[0,0,1]
	v_pk_fma_f32 v[74:75], v[74:75], v[76:77], v[80:81] op_sel_hi:[1,0,1]
	v_pk_mul_f32 v[76:77], v[70:71], v[140:141] op_sel:[1,0] op_sel_hi:[0,0]
	v_mov_b32_e32 v83, v75
	v_lshlrev_b64 v[74:75], 10, v[108:109]
	v_pk_fma_f32 v[80:81], v[70:71], v[78:79], v[76:77] op_sel_hi:[1,0,1] neg_lo:[0,0,1] neg_hi:[0,0,1]
	v_pk_fma_f32 v[70:71], v[70:71], v[78:79], v[76:77] op_sel_hi:[1,0,1]
	v_lshl_add_u64 v[74:75], s[94:95], 0, v[74:75]
	v_mov_b32_e32 v81, v71
	v_lshl_add_u64 v[74:75], v[74:75], 0, v[102:103]
	v_mul_f32_e32 v76, s4, v80
	v_mul_f32_e32 v77, s4, v81
	v_mul_f32_e32 v70, s4, v82
	v_mul_f32_e32 v71, s4, v83
	v_cvt_pk_bf16_f32 v68, v68, v69
	v_cvt_pk_bf16_f32 v69, v72, v73
	v_add_co_u32_e32 v72, vcc, s2, v74
	v_cvt_pk_bf16_f32 v70, v70, v71
	v_cvt_pk_bf16_f32 v71, v76, v77
	v_addc_co_u32_e32 v73, vcc, 0, v75, vcc
	global_store_dwordx4 v[72:73], v[68:71], off offset:2304
	s_nop 1
	v_mul_f32_e32 v70, v40, v120
	v_mul_f32_e32 v71, v41, v120
	v_mul_f32_e32 v68, v42, v120
	v_mul_f32_e32 v69, v43, v120
	v_pk_mul_f32 v[72:73], v[70:71], v[144:145] op_sel:[1,0] op_sel_hi:[0,0]
	v_pk_fma_f32 v[74:75], v[70:71], v[96:97], v[72:73] op_sel_hi:[1,0,1] neg_lo:[0,0,1] neg_hi:[0,0,1]
	v_pk_fma_f32 v[70:71], v[70:71], v[96:97], v[72:73] op_sel_hi:[1,0,1]
	v_pk_mul_f32 v[72:73], v[68:69], v[142:143] op_sel:[1,0] op_sel_hi:[0,0]
	v_pk_fma_f32 v[76:77], v[68:69], v[98:99], v[72:73] op_sel_hi:[1,0,1] neg_lo:[0,0,1] neg_hi:[0,0,1]
	v_pk_fma_f32 v[68:69], v[68:69], v[98:99], v[72:73] op_sel_hi:[1,0,1]
	v_mov_b32_e32 v75, v71
	v_mov_b32_e32 v77, v69
	v_mul_f32_e32 v68, s4, v74
	v_mul_f32_e32 v69, s4, v75
	v_mul_f32_e32 v74, v36, v120
	v_mul_f32_e32 v75, v37, v120
	v_mul_f32_e32 v72, s4, v76
	v_mul_f32_e32 v73, s4, v77
	v_pk_mul_f32 v[76:77], v[74:75], v[2:3] op_sel:[1,0] op_sel_hi:[0,0]
	v_mul_f32_e32 v70, v38, v120
	v_mul_f32_e32 v71, v39, v120
	v_pk_fma_f32 v[78:79], v[74:75], v[88:89], v[76:77] op_sel_hi:[1,0,1] neg_lo:[0,0,1] neg_hi:[0,0,1]
	v_pk_fma_f32 v[74:75], v[74:75], v[88:89], v[76:77] op_sel_hi:[1,0,1]
	v_pk_mul_f32 v[76:77], v[70:71], v[146:147] op_sel:[1,0] op_sel_hi:[0,0]
	v_mov_b32_e32 v79, v75
	v_lshlrev_b64 v[74:75], 10, v[112:113]
	v_pk_fma_f32 v[80:81], v[70:71], v[90:91], v[76:77] op_sel_hi:[1,0,1] neg_lo:[0,0,1] neg_hi:[0,0,1]
	v_pk_fma_f32 v[70:71], v[70:71], v[90:91], v[76:77] op_sel_hi:[1,0,1]
	v_lshl_add_u64 v[74:75], s[94:95], 0, v[74:75]
	v_mov_b32_e32 v81, v71
	v_lshl_add_u64 v[74:75], v[74:75], 0, v[102:103]
	v_mul_f32_e32 v76, s4, v80
	v_mul_f32_e32 v77, s4, v81
	v_mul_f32_e32 v70, s4, v78
	v_mul_f32_e32 v71, s4, v79
	v_cvt_pk_bf16_f32 v68, v68, v69
	v_cvt_pk_bf16_f32 v69, v72, v73
	v_add_co_u32_e32 v72, vcc, 0x847e000, v74
	v_cvt_pk_bf16_f32 v70, v70, v71
	v_cvt_pk_bf16_f32 v71, v76, v77
	v_addc_co_u32_e32 v73, vcc, 0, v75, vcc
	global_store_dwordx4 v[72:73], v[68:71], off offset:2304
	s_cbranch_scc1 .LBB0_225
	v_add_u32_e32 v104, 0x80, v104
	v_ashrrev_i32_e32 v105, 31, v104
	v_lshl_add_u64 v[88:89], v[104:105], 2, s[70:71]
	v_mov_b32_e32 v108, v246
	s_movk_i32 s2, 0x7cf
	v_and_or_b32 v2, v104, s2, 16
	v_cmp_gt_i32_e32 vcc, s20, v104
	v_mov_b32_e32 v114, 0
	v_mov_b32_e32 v68, 1.0
	v_cndmask_b32_e32 v2, v181, v2, vcc
	v_lshlrev_b32_e32 v2, 6, v2
	v_lshl_add_u64 v[72:73], s[84:85], 0, v[2:3]
	v_mov_b32_e32 v76, 1.0
	v_mov_b32_e32 v126, 0
	v_mov_b32_e32 v78, 1.0
	v_mov_b32_e32 v124, 0
	s_and_saveexec_b64 s[2:3], s[38:39]
	s_cbranch_execz .LBB0_210
	v_mov_b32_e32 v101, v3
	v_lshl_add_u64 v[70:71], v[72:73], 0, v[100:101]
	global_load_dwordx4 v[76:79], v[70:71], off

.LBB0_224:
	s_or_b64 exec, exec, s[2:3]
	s_waitcnt vmcnt(0)
	s_and_saveexec_b64 s[2:3], s[38:39]
	v_mov_b32_e32 v126, v77
	v_mov_b32_e32 v124, v79
	v_mov_b32_e32 v114, v69
	v_mov_b32_e32 v130, v71
	v_mov_b32_e32 v134, v85
	v_mov_b32_e32 v132, v87
	v_mov_b32_e32 v120, v73
	v_mov_b32_e32 v136, v75
	v_mov_b32_e32 v140, v93
	v_mov_b32_e32 v138, v95
	v_mov_b32_e32 v128, v81
	v_mov_b32_e32 v142, v83
	v_mov_b32_e32 v146, v97
	v_mov_b32_e32 v144, v99
	v_mov_b32_e32 v2, v89
	v_mov_b32_e32 v148, v91
	s_or_b64 exec, exec, s[2:3]
	v_mul_f32_e32 v100, v34, v108
	v_mul_f32_e32 v101, v35, v108
	v_mul_f32_e32 v150, v32, v108
	v_mul_f32_e32 v151, v33, v108
	v_pk_mul_f32 v[124:125], v[100:101], v[124:125] op_sel:[1,0] op_sel_hi:[0,0]
	v_pk_mul_f32 v[126:127], v[150:151], v[126:127] op_sel:[1,0] op_sel_hi:[0,0]
	v_pk_fma_f32 v[152:153], v[150:151], v[76:77], v[126:127] op_sel_hi:[1,0,1] neg_lo:[0,0,1] neg_hi:[0,0,1]
	v_pk_fma_f32 v[76:77], v[150:151], v[76:77], v[126:127] op_sel_hi:[1,0,1]
	v_pk_fma_f32 v[126:127], v[100:101], v[78:79], v[124:125] op_sel_hi:[1,0,1] neg_lo:[0,0,1] neg_hi:[0,0,1]
	v_pk_fma_f32 v[78:79], v[100:101], v[78:79], v[124:125] op_sel_hi:[1,0,1]
	v_mul_f32_e32 v100, v30, v108
	v_mul_f32_e32 v101, v31, v108
	v_mul_f32_e32 v109, v29, v108
	v_mul_f32_e32 v108, v28, v108
	v_mov_b32_e32 v153, v77
	v_pk_mul_f32 v[114:115], v[108:109], v[114:115] op_sel:[1,0] op_sel_hi:[0,0]
	v_pk_fma_f32 v[124:125], v[108:109], v[68:69], v[114:115] op_sel_hi:[1,0,1] neg_lo:[0,0,1] neg_hi:[0,0,1]
	v_pk_fma_f32 v[68:69], v[108:109], v[68:69], v[114:115] op_sel_hi:[1,0,1]
	v_pk_mul_f32 v[108:109], v[100:101], v[130:131] op_sel:[1,0] op_sel_hi:[0,0]
	v_mov_b32_e32 v125, v69
	v_lshlrev_b64 v[68:69], 10, v[104:105]
	v_pk_fma_f32 v[114:115], v[100:101], v[70:71], v[108:109] op_sel_hi:[1,0,1] neg_lo:[0,0,1] neg_hi:[0,0,1]
	v_pk_fma_f32 v[70:71], v[100:101], v[70:71], v[108:109] op_sel_hi:[1,0,1]
	v_lshl_add_u64 v[68:69], s[94:95], 0, v[68:69]
	v_mov_b32_e32 v127, v79
	v_mul_f32_e32 v76, s4, v152
	v_mul_f32_e32 v77, s4, v153
	v_mov_b32_e32 v115, v71
	v_lshl_add_u64 v[104:105], v[68:69], 0, v[102:103]
	s_mov_b32 s2, 0x847e000
	v_mul_f32_e32 v78, s4, v126
	v_mul_f32_e32 v79, s4, v127
	v_mul_f32_e32 v100, s4, v114
	v_mul_f32_e32 v101, s4, v115
	v_mul_f32_e32 v70, s4, v124
	v_mul_f32_e32 v71, s4, v125
	v_cvt_pk_bf16_f32 v68, v76, v77
	v_add_co_u32_e32 v76, vcc, s2, v104
	v_cvt_pk_bf16_f32 v69, v78, v79
	v_cvt_pk_bf16_f32 v70, v70, v71
	v_cvt_pk_bf16_f32 v71, v100, v101
	v_addc_co_u32_e32 v77, vcc, 0, v105, vcc
	global_store_dwordx4 v[76:77], v[68:71], off offset:2304
	v_ashrrev_i32_e32 v107, 31, v106
	v_ashrrev_i32_e32 v111, 31, v110
	v_mul_f32_e32 v70, v24, v112
	v_mul_f32_e32 v71, v25, v112
	v_mul_f32_e32 v68, v26, v112
	v_mul_f32_e32 v69, v27, v112
	v_pk_mul_f32 v[76:77], v[70:71], v[134:135] op_sel:[1,0] op_sel_hi:[0,0]
	v_pk_fma_f32 v[78:79], v[70:71], v[84:85], v[76:77] op_sel_hi:[1,0,1] neg_lo:[0,0,1] neg_hi:[0,0,1]
	v_pk_fma_f32 v[70:71], v[70:71], v[84:85], v[76:77] op_sel_hi:[1,0,1]
	v_pk_mul_f32 v[76:77], v[68:69], v[132:133] op_sel:[1,0] op_sel_hi:[0,0]
	v_pk_fma_f32 v[84:85], v[68:69], v[86:87], v[76:77] op_sel_hi:[1,0,1] neg_lo:[0,0,1] neg_hi:[0,0,1]
	v_pk_fma_f32 v[68:69], v[68:69], v[86:87], v[76:77] op_sel_hi:[1,0,1]
	v_mov_b32_e32 v79, v71
	v_mov_b32_e32 v85, v69
	v_mul_f32_e32 v68, s4, v78
	v_mul_f32_e32 v69, s4, v79
	v_mul_f32_e32 v78, v20, v112
	v_mul_f32_e32 v79, v21, v112
	v_mul_f32_e32 v76, s4, v84
	v_mul_f32_e32 v77, s4, v85
	v_pk_mul_f32 v[84:85], v[78:79], v[120:121] op_sel:[1,0] op_sel_hi:[0,0]
	v_mul_f32_e32 v70, v22, v112
	v_mul_f32_e32 v71, v23, v112
	v_pk_fma_f32 v[86:87], v[78:79], v[72:73], v[84:85] op_sel_hi:[1,0,1] neg_lo:[0,0,1] neg_hi:[0,0,1]
	v_pk_fma_f32 v[72:73], v[78:79], v[72:73], v[84:85] op_sel_hi:[1,0,1]
	v_pk_mul_f32 v[78:79], v[70:71], v[136:137] op_sel:[1,0] op_sel_hi:[0,0]
	v_mov_b32_e32 v87, v73
	v_lshlrev_b64 v[72:73], 10, v[106:107]
	v_pk_fma_f32 v[84:85], v[70:71], v[74:75], v[78:79] op_sel_hi:[1,0,1] neg_lo:[0,0,1] neg_hi:[0,0,1]
	v_pk_fma_f32 v[70:71], v[70:71], v[74:75], v[78:79] op_sel_hi:[1,0,1]
	v_lshl_add_u64 v[72:73], s[94:95], 0, v[72:73]
	v_mov_b32_e32 v85, v71
	v_lshl_add_u64 v[72:73], v[72:73], 0, v[102:103]
	v_mul_f32_e32 v74, s4, v84
	v_mul_f32_e32 v75, s4, v85
	v_mul_f32_e32 v70, s4, v86
	v_mul_f32_e32 v71, s4, v87
	v_add_co_u32_e32 v72, vcc, s2, v72
	v_cvt_pk_bf16_f32 v68, v68, v69
	v_cvt_pk_bf16_f32 v69, v76, v77
	v_cvt_pk_bf16_f32 v70, v70, v71
	v_cvt_pk_bf16_f32 v71, v74, v75
	v_addc_co_u32_e32 v73, vcc, 0, v73, vcc
	global_store_dwordx4 v[72:73], v[68:71], off offset:2304
	v_ashrrev_i32_e32 v117, 31, v116
	s_nop 0
	v_mul_f32_e32 v70, v16, v118
	v_mul_f32_e32 v71, v17, v118
	v_mul_f32_e32 v68, v18, v118
	v_mul_f32_e32 v69, v19, v118
	v_pk_mul_f32 v[72:73], v[70:71], v[140:141] op_sel:[1,0] op_sel_hi:[0,0]
	v_pk_fma_f32 v[74:75], v[70:71], v[92:93], v[72:73] op_sel_hi:[1,0,1] neg_lo:[0,0,1] neg_hi:[0,0,1]
	v_pk_fma_f32 v[70:71], v[70:71], v[92:93], v[72:73] op_sel_hi:[1,0,1]
	v_pk_mul_f32 v[72:73], v[68:69], v[138:139] op_sel:[1,0] op_sel_hi:[0,0]
	v_pk_fma_f32 v[76:77], v[68:69], v[94:95], v[72:73] op_sel_hi:[1,0,1] neg_lo:[0,0,1] neg_hi:[0,0,1]
	v_pk_fma_f32 v[68:69], v[68:69], v[94:95], v[72:73] op_sel_hi:[1,0,1]
	v_mov_b32_e32 v75, v71
	v_mov_b32_e32 v77, v69
	v_mul_f32_e32 v68, s4, v74
	v_mul_f32_e32 v69, s4, v75
	v_mul_f32_e32 v74, v12, v118
	v_mul_f32_e32 v75, v13, v118
	v_mul_f32_e32 v72, s4, v76
	v_mul_f32_e32 v73, s4, v77
	v_pk_mul_f32 v[76:77], v[74:75], v[128:129] op_sel:[1,0] op_sel_hi:[0,0]
	v_mul_f32_e32 v70, v14, v118
	v_mul_f32_e32 v71, v15, v118
	v_pk_fma_f32 v[78:79], v[74:75], v[80:81], v[76:77] op_sel_hi:[1,0,1] neg_lo:[0,0,1] neg_hi:[0,0,1]
	v_pk_fma_f32 v[74:75], v[74:75], v[80:81], v[76:77] op_sel_hi:[1,0,1]
	v_pk_mul_f32 v[76:77], v[70:71], v[142:143] op_sel:[1,0] op_sel_hi:[0,0]
	v_mov_b32_e32 v79, v75
	v_lshlrev_b64 v[74:75], 10, v[110:111]
	v_pk_fma_f32 v[80:81], v[70:71], v[82:83], v[76:77] op_sel_hi:[1,0,1] neg_lo:[0,0,1] neg_hi:[0,0,1]
	v_pk_fma_f32 v[70:71], v[70:71], v[82:83], v[76:77] op_sel_hi:[1,0,1]
	v_lshl_add_u64 v[74:75], s[94:95], 0, v[74:75]
	v_mov_b32_e32 v81, v71
	v_lshl_add_u64 v[74:75], v[74:75], 0, v[102:103]
	v_mul_f32_e32 v76, s4, v80
	v_mul_f32_e32 v77, s4, v81
	v_mul_f32_e32 v70, s4, v78
	v_mul_f32_e32 v71, s4, v79
	v_cvt_pk_bf16_f32 v68, v68, v69
	v_cvt_pk_bf16_f32 v69, v72, v73
	v_add_co_u32_e32 v72, vcc, s2, v74
	v_cvt_pk_bf16_f32 v70, v70, v71
	v_cvt_pk_bf16_f32 v71, v76, v77
	v_addc_co_u32_e32 v73, vcc, 0, v75, vcc
	global_store_dwordx4 v[72:73], v[68:71], off offset:2304
	s_nop 1
	v_mul_f32_e32 v70, v8, v122
	v_mul_f32_e32 v71, v9, v122
	v_mul_f32_e32 v68, v10, v122
	v_mul_f32_e32 v69, v11, v122
	v_pk_mul_f32 v[72:73], v[70:71], v[146:147] op_sel:[1,0] op_sel_hi:[0,0]
	v_pk_fma_f32 v[74:75], v[70:71], v[96:97], v[72:73] op_sel_hi:[1,0,1] neg_lo:[0,0,1] neg_hi:[0,0,1]
	v_pk_fma_f32 v[70:71], v[70:71], v[96:97], v[72:73] op_sel_hi:[1,0,1]
	v_pk_mul_f32 v[72:73], v[68:69], v[144:145] op_sel:[1,0] op_sel_hi:[0,0]
	v_pk_fma_f32 v[76:77], v[68:69], v[98:99], v[72:73] op_sel_hi:[1,0,1] neg_lo:[0,0,1] neg_hi:[0,0,1]
	v_pk_fma_f32 v[68:69], v[68:69], v[98:99], v[72:73] op_sel_hi:[1,0,1]
	v_mov_b32_e32 v75, v71
	v_mov_b32_e32 v77, v69
	v_mul_f32_e32 v68, s4, v74
	v_mul_f32_e32 v69, s4, v75
	v_mul_f32_e32 v74, v4, v122
	v_mul_f32_e32 v75, v5, v122
	v_mul_f32_e32 v72, s4, v76
	v_mul_f32_e32 v73, s4, v77
	v_pk_mul_f32 v[76:77], v[74:75], v[2:3] op_sel:[1,0] op_sel_hi:[0,0]
	v_mul_f32_e32 v70, v6, v122
	v_mul_f32_e32 v71, v7, v122
	v_pk_fma_f32 v[78:79], v[74:75], v[88:89], v[76:77] op_sel_hi:[1,0,1] neg_lo:[0,0,1] neg_hi:[0,0,1]
	v_pk_fma_f32 v[74:75], v[74:75], v[88:89], v[76:77] op_sel_hi:[1,0,1]
	v_pk_mul_f32 v[76:77], v[70:71], v[148:149] op_sel:[1,0] op_sel_hi:[0,0]
	v_mov_b32_e32 v79, v75
	v_lshlrev_b64 v[74:75], 10, v[116:117]
	v_pk_fma_f32 v[80:81], v[70:71], v[90:91], v[76:77] op_sel_hi:[1,0,1] neg_lo:[0,0,1] neg_hi:[0,0,1]
	v_pk_fma_f32 v[70:71], v[70:71], v[90:91], v[76:77] op_sel_hi:[1,0,1]
	v_lshl_add_u64 v[74:75], s[94:95], 0, v[74:75]
	v_mov_b32_e32 v81, v71
	v_lshl_add_u64 v[74:75], v[74:75], 0, v[102:103]
	v_mul_f32_e32 v76, s4, v80
	v_mul_f32_e32 v77, s4, v81
	v_mul_f32_e32 v70, s4, v78
	v_mul_f32_e32 v71, s4, v79
	v_cvt_pk_bf16_f32 v68, v68, v69
	v_cvt_pk_bf16_f32 v69, v72, v73
	v_add_co_u32_e32 v72, vcc, 0x847e000, v74
	v_cvt_pk_bf16_f32 v70, v70, v71
	v_cvt_pk_bf16_f32 v71, v76, v77
	v_addc_co_u32_e32 v73, vcc, 0, v75, vcc
	global_store_dwordx4 v[72:73], v[68:71], off offset:2304
.LBB0_225:
	s_and_b64 vcc, exec, s[0:1]
	s_cbranch_vccz .LBB0_228
	s_lshl_b32 s0, s48, 8
	v_add_u32_e32 v70, s0, v241
	v_ashrrev_i32_e32 v71, 31, v70
	v_lshl_add_u64 v[68:69], v[70:71], 2, s[70:71]
	v_mov_b32_e32 v86, v164
	v_mov_b32_e32 v80, v165
	v_mov_b32_e32 v76, v166
	v_mov_b32_e32 v2, v167
	s_ashr_i32 s75, s74, 31
	s_mov_b32 s0, 0x643f000
	v_or_b32_e32 v78, 16, v70
	v_ashrrev_i32_e32 v79, 31, v78
	v_lshlrev_b64 v[78:79], 11, v[78:79]
	v_lshl_add_u64 v[78:79], s[94:95], 0, v[78:79]
	v_or_b32_e32 v74, 32, v70
	v_ashrrev_i32_e32 v75, 31, v74
	v_lshlrev_b64 v[74:75], 11, v[74:75]
	v_lshl_add_u64 v[74:75], s[94:95], 0, v[74:75]
	v_or_b32_e32 v72, 48, v70
	v_ashrrev_i32_e32 v73, 31, v72
	v_lshlrev_b64 v[72:73], 11, v[72:73]
	v_lshl_add_u64 v[72:73], s[94:95], 0, v[72:73]
	s_cmp_eq_u32 s48, 64
	v_mul_f32_e32 v82, v64, v86
	v_mul_f32_e32 v83, v65, v86
	s_nop 0
	v_mul_f32_e32 v77, 0xbfb8aa3b, v82
	v_exp_f32_e32 v77, v77
	v_mul_f32_e32 v68, v66, v86
	v_mul_f32_e32 v69, v67, v86
	v_add_f32_e32 v77, 1.0, v77
	v_rcp_f32_e32 v84, v77
	v_mul_f32_e32 v77, 0xbfb8aa3b, v83
	v_exp_f32_e32 v77, v77
	s_nop 0
	v_add_f32_e32 v77, 1.0, v77
	v_rcp_f32_e32 v85, v77
	v_mul_f32_e32 v77, 0xbfb8aa3b, v68
	v_exp_f32_e32 v77, v77
	v_mul_f32_e32 v82, v82, v84
	v_mul_f32_e32 v83, v83, v85
	s_nop 0
	v_cvt_pk_bf16_f32 v82, v82, v83
	v_add_f32_e32 v77, 1.0, v77
	v_rcp_f32_e32 v84, v77
	v_mul_f32_e32 v77, 0xbfb8aa3b, v69
	v_exp_f32_e32 v77, v77
	s_nop 0
	v_add_f32_e32 v77, 1.0, v77
	v_rcp_f32_e32 v85, v77
	s_nop 0
	v_mul_f32_e32 v84, v68, v84
	v_mul_f32_e32 v85, v69, v85
	v_mul_f32_e32 v68, v62, v86
	v_mul_f32_e32 v69, v63, v86
	v_mul_f32_e32 v87, v61, v86
	v_mul_f32_e32 v86, v60, v86
	v_cvt_pk_bf16_f32 v83, v84, v85
	v_mul_f32_e32 v77, 0xbfb8aa3b, v86
	v_exp_f32_e32 v77, v77
	s_nop 0
	v_add_f32_e32 v77, 1.0, v77
	v_rcp_f32_e32 v88, v77
	v_mul_f32_e32 v77, 0xbfb8aa3b, v87
	v_exp_f32_e32 v77, v77
	s_nop 0
	v_add_f32_e32 v77, 1.0, v77
	v_rcp_f32_e32 v89, v77
	v_mul_f32_e32 v77, 0xbfb8aa3b, v68
	v_exp_f32_e32 v77, v77
	v_mul_f32_e32 v86, v86, v88
	v_mul_f32_e32 v87, v87, v89
	s_nop 0
	v_cvt_pk_bf16_f32 v84, v86, v87
	v_add_f32_e32 v77, 1.0, v77
	v_rcp_f32_e32 v88, v77
	v_mul_f32_e32 v77, 0xbfb8aa3b, v69
	v_exp_f32_e32 v77, v77
	s_nop 0
	v_add_f32_e32 v77, 1.0, v77
	v_rcp_f32_e32 v89, v77
	s_nop 0
	v_mul_f32_e32 v88, v68, v88
	v_mul_f32_e32 v89, v69, v89
	v_lshlrev_b64 v[68:69], 11, v[70:71]
	v_lshl_add_u64 v[90:91], s[94:95], 0, v[68:69]
	v_lshl_add_u64 v[68:69], s[74:75], 0, v[178:179]
	v_lshlrev_b64 v[68:69], 1, v[68:69]
	v_lshl_add_u64 v[90:91], v[90:91], 0, v[68:69]
	v_add_co_u32_e32 v86, vcc, s0, v90
	v_cvt_pk_bf16_f32 v85, v88, v89
	s_nop 0
	v_addc_co_u32_e32 v87, vcc, 0, v91, vcc
	global_store_dwordx4 v[86:87], v[82:85], off offset:256
	s_nop 1
	v_mul_f32_e32 v82, v56, v80
	v_mul_f32_e32 v83, v57, v80
	v_mul_f32_e32 v84, v58, v80
	v_mul_f32_e32 v85, v59, v80
	v_mul_f32_e32 v71, 0xbfb8aa3b, v82
	v_exp_f32_e32 v71, v71
	s_nop 0
	v_add_f32_e32 v71, 1.0, v71
	v_rcp_f32_e32 v86, v71
	v_mul_f32_e32 v71, 0xbfb8aa3b, v83
	v_exp_f32_e32 v71, v71
	s_nop 0
	v_add_f32_e32 v71, 1.0, v71
	v_rcp_f32_e32 v87, v71
	v_mul_f32_e32 v71, 0xbfb8aa3b, v84
	v_exp_f32_e32 v71, v71
	v_mul_f32_e32 v82, v82, v86
	v_mul_f32_e32 v83, v83, v87
	v_add_f32_e32 v71, 1.0, v71
	v_rcp_f32_e32 v86, v71
	v_mul_f32_e32 v71, 0xbfb8aa3b, v85
	v_exp_f32_e32 v71, v71
	s_nop 0
	v_add_f32_e32 v71, 1.0, v71
	v_rcp_f32_e32 v87, v71
	s_nop 0
	v_mul_f32_e32 v84, v84, v86
	v_mul_f32_e32 v85, v85, v87
	v_mul_f32_e32 v86, v54, v80
	v_mul_f32_e32 v87, v55, v80
	v_mul_f32_e32 v81, v53, v80
	v_mul_f32_e32 v80, v52, v80
	s_nop 0
	v_mul_f32_e32 v71, 0xbfb8aa3b, v80
	v_exp_f32_e32 v71, v71
	s_nop 0
	v_add_f32_e32 v71, 1.0, v71
	v_rcp_f32_e32 v88, v71
	v_mul_f32_e32 v71, 0xbfb8aa3b, v81
	v_exp_f32_e32 v71, v71
	s_nop 0
	v_add_f32_e32 v71, 1.0, v71
	v_rcp_f32_e32 v89, v71
	v_mul_f32_e32 v71, 0xbfb8aa3b, v86
	v_exp_f32_e32 v71, v71
	v_mul_f32_e32 v80, v80, v88
	v_mul_f32_e32 v81, v81, v89
	s_nop 0
	v_cvt_pk_bf16_f32 v80, v80, v81
	v_add_f32_e32 v71, 1.0, v71
	v_rcp_f32_e32 v88, v71
	v_mul_f32_e32 v71, 0xbfb8aa3b, v87
	v_exp_f32_e32 v71, v71
	s_nop 0
	v_add_f32_e32 v71, 1.0, v71
	v_rcp_f32_e32 v89, v71
	s_nop 0
	v_mul_f32_e32 v86, v86, v88
	v_mul_f32_e32 v87, v87, v89
	v_lshl_add_u64 v[88:89], v[78:79], 0, v[68:69]
	v_cvt_pk_bf16_f32 v78, v82, v83
	v_add_co_u32_e32 v82, vcc, s0, v88
	v_cvt_pk_bf16_f32 v79, v84, v85
	v_cvt_pk_bf16_f32 v81, v86, v87
	v_addc_co_u32_e32 v83, vcc, 0, v89, vcc
	global_store_dwordx4 v[82:83], v[78:81], off offset:256
	s_nop 1
	v_mul_f32_e32 v80, v48, v76
	v_mul_f32_e32 v81, v49, v76
	v_mul_f32_e32 v78, v50, v76
	v_mul_f32_e32 v79, v51, v76
	v_mul_f32_e32 v71, 0xbfb8aa3b, v80
	v_exp_f32_e32 v71, v71
	s_nop 0
	v_add_f32_e32 v71, 1.0, v71
	v_rcp_f32_e32 v82, v71
	v_mul_f32_e32 v71, 0xbfb8aa3b, v81
	v_exp_f32_e32 v71, v71
	s_nop 0
	v_add_f32_e32 v71, 1.0, v71
	v_rcp_f32_e32 v83, v71
	v_mul_f32_e32 v71, 0xbfb8aa3b, v78
	v_exp_f32_e32 v71, v71
	v_mul_f32_e32 v80, v80, v82
	v_mul_f32_e32 v81, v81, v83
	v_add_f32_e32 v71, 1.0, v71
	v_rcp_f32_e32 v82, v71
	v_mul_f32_e32 v71, 0xbfb8aa3b, v79
	v_exp_f32_e32 v71, v71
	s_nop 0
	v_add_f32_e32 v71, 1.0, v71
	v_rcp_f32_e32 v83, v71
	s_nop 0
	v_mul_f32_e32 v78, v78, v82
	v_mul_f32_e32 v79, v79, v83
	v_mul_f32_e32 v82, v46, v76
	v_mul_f32_e32 v83, v47, v76
	v_mul_f32_e32 v77, v45, v76
	v_mul_f32_e32 v76, v44, v76
	s_nop 0
	v_mul_f32_e32 v71, 0xbfb8aa3b, v76
	v_exp_f32_e32 v71, v71
	s_nop 0
	v_add_f32_e32 v71, 1.0, v71
	v_rcp_f32_e32 v84, v71
	v_mul_f32_e32 v71, 0xbfb8aa3b, v77
	v_exp_f32_e32 v71, v71
	s_nop 0
	v_add_f32_e32 v71, 1.0, v71
	v_rcp_f32_e32 v85, v71
	v_mul_f32_e32 v71, 0xbfb8aa3b, v82
	v_exp_f32_e32 v71, v71
	v_mul_f32_e32 v76, v76, v84
	v_mul_f32_e32 v77, v77, v85
	s_nop 0
	v_cvt_pk_bf16_f32 v76, v76, v77
	v_add_f32_e32 v71, 1.0, v71
	v_rcp_f32_e32 v84, v71
	v_mul_f32_e32 v71, 0xbfb8aa3b, v83
	v_exp_f32_e32 v71, v71
	s_nop 0
	v_add_f32_e32 v71, 1.0, v71
	v_rcp_f32_e32 v85, v71
	s_nop 0
	v_mul_f32_e32 v82, v82, v84
	v_mul_f32_e32 v83, v83, v85
	v_lshl_add_u64 v[84:85], v[74:75], 0, v[68:69]
	v_cvt_pk_bf16_f32 v75, v78, v79
	v_add_co_u32_e32 v78, vcc, s0, v84
	v_cvt_pk_bf16_f32 v74, v80, v81
	v_cvt_pk_bf16_f32 v77, v82, v83
	v_addc_co_u32_e32 v79, vcc, 0, v85, vcc
	global_store_dwordx4 v[78:79], v[74:77], off offset:256
	v_mul_f32_e32 v80, v36, v2
	v_mul_f32_e32 v81, v37, v2
	s_nop 0
	v_mul_f32_e32 v76, v40, v2
	v_mul_f32_e32 v77, v41, v2
	v_mul_f32_e32 v74, v42, v2
	v_mul_f32_e32 v75, v43, v2
	v_mul_f32_e32 v71, 0xbfb8aa3b, v76
	v_exp_f32_e32 v71, v71
	s_nop 0
	v_add_f32_e32 v71, 1.0, v71
	v_rcp_f32_e32 v78, v71
	v_mul_f32_e32 v71, 0xbfb8aa3b, v77
	v_exp_f32_e32 v71, v71
	s_nop 0
	v_add_f32_e32 v71, 1.0, v71
	v_rcp_f32_e32 v79, v71
	v_mul_f32_e32 v71, 0xbfb8aa3b, v74
	v_exp_f32_e32 v71, v71
	v_mul_f32_e32 v76, v76, v78
	v_mul_f32_e32 v77, v77, v79
	v_add_f32_e32 v71, 1.0, v71
	v_rcp_f32_e32 v78, v71
	v_mul_f32_e32 v71, 0xbfb8aa3b, v75
	v_exp_f32_e32 v71, v71
	s_nop 0
	v_add_f32_e32 v71, 1.0, v71
	v_rcp_f32_e32 v79, v71
	s_nop 0
	v_mul_f32_e32 v74, v74, v78
	v_mul_f32_e32 v75, v75, v79
	v_mul_f32_e32 v78, v38, v2
	v_mul_f32_e32 v79, v39, v2
	v_mul_f32_e32 v2, 0xbfb8aa3b, v80
	v_exp_f32_e32 v2, v2
	s_nop 0
	v_add_f32_e32 v2, 1.0, v2
	v_rcp_f32_e32 v82, v2
	v_mul_f32_e32 v2, 0xbfb8aa3b, v81
	v_exp_f32_e32 v2, v2
	s_nop 0
	v_add_f32_e32 v2, 1.0, v2
	v_rcp_f32_e32 v83, v2
	v_mul_f32_e32 v2, 0xbfb8aa3b, v78
	v_exp_f32_e32 v2, v2
	v_mul_f32_e32 v80, v80, v82
	v_mul_f32_e32 v81, v81, v83
	v_add_f32_e32 v2, 1.0, v2
	v_rcp_f32_e32 v82, v2
	v_mul_f32_e32 v2, 0xbfb8aa3b, v79
	v_exp_f32_e32 v2, v2
	s_nop 0
	v_add_f32_e32 v2, 1.0, v2
	v_rcp_f32_e32 v83, v2
	s_nop 0
	v_mul_f32_e32 v78, v78, v82
	v_mul_f32_e32 v79, v79, v83
	v_lshl_add_u64 v[82:83], v[72:73], 0, v[68:69]
	v_cvt_pk_bf16_f32 v72, v76, v77
	v_add_co_u32_e32 v76, vcc, 0x643f000, v82
	v_cvt_pk_bf16_f32 v73, v74, v75
	v_cvt_pk_bf16_f32 v74, v80, v81
	v_cvt_pk_bf16_f32 v75, v78, v79
	v_addc_co_u32_e32 v77, vcc, 0, v83, vcc
	global_store_dwordx4 v[76:77], v[72:75], off offset:256
	s_cbranch_scc1 .LBB0_228
	v_add_u32_e32 v78, 0x80, v70
	v_ashrrev_i32_e32 v79, 31, v78
	v_lshl_add_u64 v[80:81], v[78:79], 2, s[70:71]
	v_mov_b32_e32 v84, v246
	v_mov_b32_e32 v82, v247
	v_mov_b32_e32 v74, v248
	v_mov_b32_e32 v2, v249
	v_lshlrev_b64 v[78:79], 11, v[78:79]
	v_lshl_add_u64 v[78:79], s[94:95], 0, v[78:79]
	v_add_u32_e32 v76, 0x90, v70
	v_ashrrev_i32_e32 v77, 31, v76
	v_lshlrev_b64 v[76:77], 11, v[76:77]
	v_lshl_add_u64 v[76:77], s[94:95], 0, v[76:77]
	v_add_u32_e32 v72, 0xa0, v70
	v_ashrrev_i32_e32 v73, 31, v72
	v_lshlrev_b64 v[72:73], 11, v[72:73]
	v_lshl_add_u64 v[72:73], s[94:95], 0, v[72:73]
	v_add_u32_e32 v70, 0xb0, v70
	v_ashrrev_i32_e32 v71, 31, v70
	v_lshlrev_b64 v[70:71], 11, v[70:71]
	v_lshl_add_u64 v[70:71], s[94:95], 0, v[70:71]
	v_mul_f32_e32 v86, v32, v84
	v_mul_f32_e32 v87, v33, v84
	s_nop 0
	v_mul_f32_e32 v75, 0xbfb8aa3b, v86
	v_exp_f32_e32 v75, v75
	v_mul_f32_e32 v80, v34, v84
	v_mul_f32_e32 v81, v35, v84
	v_add_f32_e32 v75, 1.0, v75
	v_rcp_f32_e32 v88, v75
	v_mul_f32_e32 v75, 0xbfb8aa3b, v87
	v_exp_f32_e32 v75, v75
	s_nop 0
	v_add_f32_e32 v75, 1.0, v75
	v_rcp_f32_e32 v89, v75
	v_mul_f32_e32 v75, 0xbfb8aa3b, v80
	v_exp_f32_e32 v75, v75
	v_mul_f32_e32 v86, v86, v88
	v_mul_f32_e32 v87, v87, v89
	v_add_f32_e32 v75, 1.0, v75
	v_rcp_f32_e32 v88, v75
	v_mul_f32_e32 v75, 0xbfb8aa3b, v81
	v_exp_f32_e32 v75, v75
	s_nop 0
	v_add_f32_e32 v75, 1.0, v75
	v_rcp_f32_e32 v89, v75
	s_nop 0
	v_mul_f32_e32 v80, v80, v88
	v_mul_f32_e32 v81, v81, v89
	v_mul_f32_e32 v88, v30, v84
	v_mul_f32_e32 v89, v31, v84
	v_mul_f32_e32 v85, v29, v84
	v_mul_f32_e32 v84, v28, v84
	s_nop 0
	v_mul_f32_e32 v75, 0xbfb8aa3b, v84
	v_exp_f32_e32 v75, v75
	s_nop 0
	v_add_f32_e32 v75, 1.0, v75
	v_rcp_f32_e32 v90, v75
	v_mul_f32_e32 v75, 0xbfb8aa3b, v85
	v_exp_f32_e32 v75, v75
	s_nop 0
	v_add_f32_e32 v75, 1.0, v75
	v_rcp_f32_e32 v91, v75
	v_mul_f32_e32 v75, 0xbfb8aa3b, v88
	v_exp_f32_e32 v75, v75
	v_mul_f32_e32 v84, v84, v90
	v_mul_f32_e32 v85, v85, v91
	v_add_f32_e32 v75, 1.0, v75
	v_rcp_f32_e32 v90, v75
	v_mul_f32_e32 v75, 0xbfb8aa3b, v89
	v_exp_f32_e32 v75, v75
	s_nop 0
	v_add_f32_e32 v75, 1.0, v75
	v_rcp_f32_e32 v91, v75
	s_nop 0
	v_mul_f32_e32 v88, v88, v90
	v_mul_f32_e32 v89, v89, v91
	v_lshl_add_u64 v[90:91], v[78:79], 0, v[68:69]
	v_cvt_pk_bf16_f32 v79, v80, v81
	v_cvt_pk_bf16_f32 v80, v84, v85
	v_add_co_u32_e32 v84, vcc, s0, v90
	v_cvt_pk_bf16_f32 v78, v86, v87
	v_cvt_pk_bf16_f32 v81, v88, v89
	v_addc_co_u32_e32 v85, vcc, 0, v91, vcc
	global_store_dwordx4 v[84:85], v[78:81], off offset:256
	s_nop 1
	v_mul_f32_e32 v78, v24, v82
	v_mul_f32_e32 v79, v25, v82
	v_mul_f32_e32 v80, v26, v82
	v_mul_f32_e32 v81, v27, v82
	v_mul_f32_e32 v75, 0xbfb8aa3b, v78
	v_exp_f32_e32 v75, v75
	s_nop 0
	v_add_f32_e32 v75, 1.0, v75
	v_rcp_f32_e32 v84, v75
	v_mul_f32_e32 v75, 0xbfb8aa3b, v79
	v_exp_f32_e32 v75, v75
	s_nop 0
	v_add_f32_e32 v75, 1.0, v75
	v_rcp_f32_e32 v85, v75
	v_mul_f32_e32 v75, 0xbfb8aa3b, v80
	v_exp_f32_e32 v75, v75
	v_mul_f32_e32 v78, v78, v84
	v_mul_f32_e32 v79, v79, v85
	v_add_f32_e32 v75, 1.0, v75
	v_rcp_f32_e32 v84, v75
	v_mul_f32_e32 v75, 0xbfb8aa3b, v81
	v_exp_f32_e32 v75, v75
	s_nop 0
	v_add_f32_e32 v75, 1.0, v75
	v_rcp_f32_e32 v85, v75
	s_nop 0
	v_mul_f32_e32 v80, v80, v84
	v_mul_f32_e32 v81, v81, v85
	v_mul_f32_e32 v84, v22, v82
	v_mul_f32_e32 v85, v23, v82
	v_mul_f32_e32 v83, v21, v82
	v_mul_f32_e32 v82, v20, v82
	s_nop 0
	v_mul_f32_e32 v75, 0xbfb8aa3b, v82
	v_exp_f32_e32 v75, v75
	s_nop 0
	v_add_f32_e32 v75, 1.0, v75
	v_rcp_f32_e32 v86, v75
	v_mul_f32_e32 v75, 0xbfb8aa3b, v83
	v_exp_f32_e32 v75, v75
	s_nop 0
	v_add_f32_e32 v75, 1.0, v75
	v_rcp_f32_e32 v87, v75
	v_mul_f32_e32 v75, 0xbfb8aa3b, v84
	v_exp_f32_e32 v75, v75
	v_mul_f32_e32 v82, v82, v86
	v_mul_f32_e32 v83, v83, v87
	v_add_f32_e32 v75, 1.0, v75
	v_rcp_f32_e32 v86, v75
	v_mul_f32_e32 v75, 0xbfb8aa3b, v85
	v_exp_f32_e32 v75, v75
	s_nop 0
	v_add_f32_e32 v75, 1.0, v75
	v_rcp_f32_e32 v87, v75
	s_nop 0
	v_mul_f32_e32 v84, v84, v86
	v_mul_f32_e32 v85, v85, v87
	v_lshl_add_u64 v[86:87], v[76:77], 0, v[68:69]
	v_cvt_pk_bf16_f32 v77, v80, v81
	v_add_co_u32_e32 v80, vcc, s0, v86
	v_cvt_pk_bf16_f32 v76, v78, v79
	v_cvt_pk_bf16_f32 v78, v82, v83
	v_cvt_pk_bf16_f32 v79, v84, v85
	v_addc_co_u32_e32 v81, vcc, 0, v87, vcc
	global_store_dwordx4 v[80:81], v[76:79], off offset:256
	s_nop 1
	v_mul_f32_e32 v78, v16, v74
	v_mul_f32_e32 v79, v17, v74
	v_mul_f32_e32 v76, v18, v74
	v_mul_f32_e32 v77, v19, v74
	v_mul_f32_e32 v75, 0xbfb8aa3b, v78
	v_exp_f32_e32 v75, v75
	s_nop 0
	v_add_f32_e32 v75, 1.0, v75
	v_rcp_f32_e32 v80, v75
	v_mul_f32_e32 v75, 0xbfb8aa3b, v79
	v_exp_f32_e32 v75, v75
	s_nop 0
	v_add_f32_e32 v75, 1.0, v75
	v_rcp_f32_e32 v81, v75
	v_mul_f32_e32 v75, 0xbfb8aa3b, v76
	v_exp_f32_e32 v75, v75
	v_mul_f32_e32 v78, v78, v80
	v_mul_f32_e32 v79, v79, v81
	v_add_f32_e32 v75, 1.0, v75
	v_rcp_f32_e32 v80, v75
	v_mul_f32_e32 v75, 0xbfb8aa3b, v77
	v_exp_f32_e32 v75, v75
	s_nop 0
	v_add_f32_e32 v75, 1.0, v75
	v_rcp_f32_e32 v81, v75
	s_nop 0
	v_mul_f32_e32 v76, v76, v80
	v_mul_f32_e32 v77, v77, v81
	v_mul_f32_e32 v80, v14, v74
	v_mul_f32_e32 v81, v15, v74
	v_mul_f32_e32 v75, v13, v74
	v_mul_f32_e32 v74, v12, v74
	s_nop 0
	v_mul_f32_e32 v82, 0xbfb8aa3b, v74
	v_mul_f32_e32 v83, 0xbfb8aa3b, v75
	v_exp_f32_e32 v82, v82
	v_exp_f32_e32 v83, v83
	v_add_f32_e32 v82, 1.0, v82
	v_add_f32_e32 v83, 1.0, v83
	v_rcp_f32_e32 v82, v82
	v_rcp_f32_e32 v83, v83
	s_nop 0
	v_mul_f32_e32 v74, v74, v82
	v_mul_f32_e32 v75, v75, v83
	v_mul_f32_e32 v82, 0xbfb8aa3b, v80
	v_mul_f32_e32 v83, 0xbfb8aa3b, v81
	v_exp_f32_e32 v82, v82
	v_exp_f32_e32 v83, v83
	v_cvt_pk_bf16_f32 v74, v74, v75
	v_add_f32_e32 v82, 1.0, v82
	v_add_f32_e32 v83, 1.0, v83
	v_rcp_f32_e32 v82, v82
	v_rcp_f32_e32 v83, v83
	s_nop 0
	v_mul_f32_e32 v80, v80, v82
	v_mul_f32_e32 v81, v81, v83
	v_lshl_add_u64 v[82:83], v[72:73], 0, v[68:69]
	v_cvt_pk_bf16_f32 v73, v76, v77
	v_add_co_u32_e32 v76, vcc, s0, v82
	v_cvt_pk_bf16_f32 v72, v78, v79
	v_cvt_pk_bf16_f32 v75, v80, v81
	v_addc_co_u32_e32 v77, vcc, 0, v83, vcc
	global_store_dwordx4 v[76:77], v[72:75], off offset:256
	v_mul_f32_e32 v78, v4, v2
	v_mul_f32_e32 v79, v5, v2
	s_mov_b64 s[0:1], 0
	v_mul_f32_e32 v74, v8, v2
	v_mul_f32_e32 v75, v9, v2
	v_mul_f32_e32 v72, v10, v2
	v_mul_f32_e32 v73, v11, v2
	v_mul_f32_e32 v76, 0xbfb8aa3b, v74
	v_mul_f32_e32 v77, 0xbfb8aa3b, v75
	v_exp_f32_e32 v76, v76
	v_exp_f32_e32 v77, v77
	v_add_f32_e32 v76, 1.0, v76
	v_add_f32_e32 v77, 1.0, v77
	v_rcp_f32_e32 v76, v76
	v_rcp_f32_e32 v77, v77
	s_nop 0
	v_mul_f32_e32 v74, v74, v76
	v_mul_f32_e32 v75, v75, v77
	v_mul_f32_e32 v76, 0xbfb8aa3b, v72
	v_mul_f32_e32 v77, 0xbfb8aa3b, v73
	v_exp_f32_e32 v76, v76
	v_exp_f32_e32 v77, v77
	v_add_f32_e32 v76, 1.0, v76
	v_add_f32_e32 v77, 1.0, v77
	v_rcp_f32_e32 v76, v76
	v_rcp_f32_e32 v77, v77
	s_nop 0
	v_mul_f32_e32 v72, v72, v76
	v_mul_f32_e32 v73, v73, v77
	v_mul_f32_e32 v76, v6, v2
	v_mul_f32_e32 v77, v7, v2
	v_mul_f32_e32 v2, 0xbfb8aa3b, v78
	v_exp_f32_e32 v2, v2
	s_nop 0
	v_add_f32_e32 v2, 1.0, v2
	v_rcp_f32_e32 v80, v2
	v_mul_f32_e32 v2, 0xbfb8aa3b, v79
	v_exp_f32_e32 v2, v2
	s_nop 0
	v_add_f32_e32 v2, 1.0, v2
	v_rcp_f32_e32 v81, v2
	v_mul_f32_e32 v2, 0xbfb8aa3b, v76
	v_exp_f32_e32 v2, v2
	v_mul_f32_e32 v78, v78, v80
	v_mul_f32_e32 v79, v79, v81
	v_add_f32_e32 v2, 1.0, v2
	v_rcp_f32_e32 v80, v2
	v_mul_f32_e32 v2, 0xbfb8aa3b, v77
	v_exp_f32_e32 v2, v2
	s_nop 0
	v_add_f32_e32 v2, 1.0, v2
	v_rcp_f32_e32 v81, v2
	s_nop 0
	v_mul_f32_e32 v76, v76, v80
	v_mul_f32_e32 v77, v77, v81
	v_lshl_add_u64 v[80:81], v[70:71], 0, v[68:69]
	v_cvt_pk_bf16_f32 v69, v72, v73
	v_add_co_u32_e32 v72, vcc, 0x643f000, v80
	v_cvt_pk_bf16_f32 v68, v74, v75
	v_cvt_pk_bf16_f32 v70, v78, v79
	v_cvt_pk_bf16_f32 v71, v76, v77
	v_addc_co_u32_e32 v73, vcc, 0, v81, vcc
	global_store_dwordx4 v[72:73], v[68:71], off offset:256
	s_branch .LBB0_229

.LBB0_239:
	s_andn2_b64 vcc, exec, s[0:1]
	s_cbranch_vccnz .LBB0_45
	s_lshl_b32 s0, s48, 8
	v_add_u32_e32 v92, s0, v241
	s_movk_i32 s0, 0x7cf
	v_cmp_gt_i32_e32 vcc, s20, v92
	v_and_or_b32 v2, v92, s0, 16
	v_ashrrev_i32_e32 v93, 31, v92
	v_cndmask_b32_e32 v2, v181, v2, vcc
	v_lshl_add_u64 v[68:69], v[92:93], 2, s[70:71]
	v_lshlrev_b32_e32 v2, 8, v2
	v_mov_b32_e32 v114, v164
	v_lshl_add_u64 v[70:71], v[182:183], 0, v[2:3]
	global_load_dwordx4 v[106:109], v[70:71], off offset:16
	global_load_dwordx4 v[110:113], v[70:71], off
	s_movk_i32 s0, 0x7df
	v_or_b32_e32 v98, 16, v92
	v_bitop3_b32 v2, v92, s0, 16 bitop3:0xc8
	v_cmp_gt_i32_e32 vcc, s20, v98
	v_add_u32_e32 v2, 16, v2
	v_mov_b32_e32 v104, v165
	v_cndmask_b32_e32 v2, v181, v2, vcc
	v_lshlrev_b32_e32 v2, 8, v2
	v_lshl_add_u64 v[70:71], v[182:183], 0, v[2:3]
	global_load_dwordx4 v[84:87], v[70:71], off offset:16
	global_load_dwordx4 v[88:91], v[70:71], off
	v_or_b32_e32 v100, 32, v92
	s_movk_i32 s0, 0x7ef
	v_cmp_gt_i32_e32 vcc, s20, v100
	v_and_or_b32 v2, v100, s0, 16
	v_mov_b32_e32 v102, v166
	v_cndmask_b32_e32 v2, v181, v2, vcc
	v_lshlrev_b32_e32 v2, 8, v2
	v_lshl_add_u64 v[70:71], v[182:183], 0, v[2:3]
	global_load_dwordx4 v[76:79], v[70:71], off offset:16
	global_load_dwordx4 v[80:83], v[70:71], off
	s_movk_i32 s0, 0x7ff
	v_or_b32_e32 v94, 48, v92
	v_bitop3_b32 v2, v92, s0, 48 bitop3:0xc8
	v_cmp_gt_i32_e32 vcc, s20, v94
	v_add_u32_e32 v2, 16, v2
	v_mov_b32_e32 v96, v167
	v_cndmask_b32_e32 v2, v181, v2, vcc
	v_lshlrev_b32_e32 v2, 8, v2
	v_lshl_add_u64 v[72:73], v[182:183], 0, v[2:3]
	global_load_dwordx4 v[68:71], v[72:73], off offset:16
	s_nop 0
	global_load_dwordx4 v[72:75], v[72:73], off
	s_mov_b32 s0, 0x3e000000
	s_ashr_i32 s75, s74, 31
	v_ashrrev_i32_e32 v99, 31, v98
	v_ashrrev_i32_e32 v101, 31, v100
	v_ashrrev_i32_e32 v95, 31, v94
	s_cmp_eq_u32 s48, 64
	s_waitcnt vmcnt(0)
	v_mul_f32_e32 v64, v64, v114
	v_mul_f32_e32 v65, v65, v114
	v_mul_f32_e32 v66, v66, v114
	v_mul_f32_e32 v67, v67, v114
	v_pk_mul_f32 v[116:117], v[110:111], v[64:65] op_sel:[1,1] op_sel_hi:[1,0]
	v_mov_b32_e32 v2, v113
	v_pk_fma_f32 v[118:119], v[110:111], v[64:65], v[116:117] op_sel_hi:[0,1,1] neg_lo:[0,0,1] neg_hi:[0,0,1]
	v_pk_fma_f32 v[110:111], v[110:111], v[64:65], v[116:117] op_sel_hi:[0,1,1]
	v_mul_f32_e32 v60, v60, v114
	v_mul_f32_e32 v61, v61, v114
	v_pk_mul_f32 v[64:65], v[2:3], v[66:67] op_sel:[0,1] op_sel_hi:[0,0]
	v_mov_b32_e32 v119, v111
	v_mul_f32_e32 v62, v62, v114
	v_mul_f32_e32 v63, v63, v114
	v_pk_mul_f32 v[110:111], v[106:107], v[60:61] op_sel:[1,1] op_sel_hi:[1,0]
	v_mov_b32_e32 v2, v109
	v_pk_fma_f32 v[116:117], v[112:113], v[66:67], v[64:65] op_sel_hi:[0,1,1] neg_lo:[0,0,1] neg_hi:[0,0,1]
	v_pk_fma_f32 v[64:65], v[112:113], v[66:67], v[64:65] op_sel_hi:[0,1,1]
	v_pk_fma_f32 v[112:113], v[106:107], v[60:61], v[110:111] op_sel_hi:[0,1,1] neg_lo:[0,0,1] neg_hi:[0,0,1]
	v_pk_fma_f32 v[60:61], v[106:107], v[60:61], v[110:111] op_sel_hi:[0,1,1]
	v_pk_mul_f32 v[106:107], v[2:3], v[62:63] op_sel:[0,1] op_sel_hi:[0,0]
	v_pk_fma_f32 v[110:111], v[108:109], v[62:63], v[106:107] op_sel_hi:[0,1,1] neg_lo:[0,0,1] neg_hi:[0,0,1]
	v_pk_fma_f32 v[62:63], v[108:109], v[62:63], v[106:107] op_sel_hi:[0,1,1]
	v_mov_b32_e32 v111, v63
	v_mov_b32_e32 v113, v61
	v_lshlrev_b64 v[60:61], 10, v[92:93]
	v_mov_b32_e32 v117, v65
	v_mul_f32_e32 v62, s0, v110
	v_mul_f32_e32 v63, s0, v111
	v_lshl_add_u64 v[108:109], s[94:95], 0, v[60:61]
	v_lshl_add_u64 v[60:61], s[74:75], 0, v[178:179]
	v_mul_f32_e32 v56, v56, v104
	v_mul_f32_e32 v57, v57, v104
	v_mul_f32_e32 v64, s0, v116
	v_mul_f32_e32 v65, s0, v117
	v_lshlrev_b64 v[60:61], 1, v[60:61]
	v_cvt_pk_bf16_f32 v111, v62, v63
	v_mul_f32_e32 v58, v58, v104
	v_mul_f32_e32 v59, v59, v104
	v_pk_mul_f32 v[62:63], v[88:89], v[56:57] op_sel:[1,1] op_sel_hi:[1,0]
	v_mov_b32_e32 v2, v91
	v_mul_f32_e32 v66, s0, v118
	v_mul_f32_e32 v67, s0, v119
	v_mul_f32_e32 v106, s0, v112
	v_mul_f32_e32 v107, s0, v113
	v_lshl_add_u64 v[112:113], v[108:109], 0, v[60:61]
	v_cvt_pk_bf16_f32 v109, v64, v65
	v_pk_fma_f32 v[64:65], v[88:89], v[56:57], v[62:63] op_sel_hi:[0,1,1] neg_lo:[0,0,1] neg_hi:[0,0,1]
	v_pk_fma_f32 v[56:57], v[88:89], v[56:57], v[62:63] op_sel_hi:[0,1,1]
	v_pk_mul_f32 v[62:63], v[2:3], v[58:59] op_sel:[0,1] op_sel_hi:[0,0]
	v_mul_f32_e32 v52, v52, v104
	v_mul_f32_e32 v53, v53, v104
	v_cvt_pk_bf16_f32 v108, v66, v67
	v_pk_fma_f32 v[66:67], v[90:91], v[58:59], v[62:63] op_sel_hi:[0,1,1] neg_lo:[0,0,1] neg_hi:[0,0,1]
	v_pk_fma_f32 v[58:59], v[90:91], v[58:59], v[62:63] op_sel_hi:[0,1,1]
	v_mov_b32_e32 v65, v57
	v_mul_f32_e32 v54, v54, v104
	v_mul_f32_e32 v55, v55, v104
	v_pk_mul_f32 v[62:63], v[84:85], v[52:53] op_sel:[1,1] op_sel_hi:[1,0]
	v_mov_b32_e32 v2, v87
	v_mov_b32_e32 v67, v59
	v_mul_f32_e32 v56, s0, v64
	v_mul_f32_e32 v57, s0, v65
	v_pk_fma_f32 v[64:65], v[84:85], v[52:53], v[62:63] op_sel_hi:[0,1,1] neg_lo:[0,0,1] neg_hi:[0,0,1]
	v_pk_fma_f32 v[52:53], v[84:85], v[52:53], v[62:63] op_sel_hi:[0,1,1]
	v_pk_mul_f32 v[62:63], v[2:3], v[54:55] op_sel:[0,1] op_sel_hi:[0,0]
	v_mul_f32_e32 v58, s0, v66
	v_mul_f32_e32 v59, s0, v67
	v_pk_fma_f32 v[66:67], v[86:87], v[54:55], v[62:63] op_sel_hi:[0,1,1] neg_lo:[0,0,1] neg_hi:[0,0,1]
	v_pk_fma_f32 v[54:55], v[86:87], v[54:55], v[62:63] op_sel_hi:[0,1,1]
	v_mov_b32_e32 v67, v55
	v_mov_b32_e32 v65, v53
	v_lshlrev_b64 v[52:53], 10, v[98:99]
	v_mul_f32_e32 v62, s0, v66
	v_mul_f32_e32 v63, s0, v67
	v_mul_f32_e32 v54, s0, v64
	v_mul_f32_e32 v55, s0, v65
	v_lshl_add_u64 v[52:53], s[94:95], 0, v[52:53]
	v_lshl_add_u64 v[64:65], v[52:53], 0, v[60:61]
	v_cvt_pk_bf16_f32 v52, v56, v57
	v_cvt_pk_bf16_f32 v53, v58, v59
	v_cvt_pk_bf16_f32 v54, v54, v55
	v_cvt_pk_bf16_f32 v55, v62, v63
	v_mul_f32_e32 v48, v48, v102
	v_mul_f32_e32 v49, v49, v102
	global_store_dwordx4 v[64:65], v[52:55], off offset:256
	v_mul_f32_e32 v50, v50, v102
	v_mul_f32_e32 v51, v51, v102
	v_mov_b32_e32 v2, v83
	v_pk_mul_f32 v[52:53], v[80:81], v[48:49] op_sel:[1,1] op_sel_hi:[1,0]
	v_mul_f32_e32 v44, v44, v102
	v_mul_f32_e32 v45, v45, v102
	v_pk_fma_f32 v[54:55], v[80:81], v[48:49], v[52:53] op_sel_hi:[0,1,1] neg_lo:[0,0,1] neg_hi:[0,0,1]
	v_pk_fma_f32 v[48:49], v[80:81], v[48:49], v[52:53] op_sel_hi:[0,1,1]
	v_pk_mul_f32 v[52:53], v[2:3], v[50:51] op_sel:[0,1] op_sel_hi:[0,0]
	v_pk_fma_f32 v[56:57], v[82:83], v[50:51], v[52:53] op_sel_hi:[0,1,1] neg_lo:[0,0,1] neg_hi:[0,0,1]
	v_pk_fma_f32 v[50:51], v[82:83], v[50:51], v[52:53] op_sel_hi:[0,1,1]
	v_mov_b32_e32 v55, v49
	v_mul_f32_e32 v46, v46, v102
	v_mul_f32_e32 v47, v47, v102
	v_pk_mul_f32 v[52:53], v[76:77], v[44:45] op_sel:[1,1] op_sel_hi:[1,0]
	v_mov_b32_e32 v2, v79
	v_mov_b32_e32 v57, v51
	v_mul_f32_e32 v48, s0, v54
	v_mul_f32_e32 v49, s0, v55
	v_pk_fma_f32 v[54:55], v[76:77], v[44:45], v[52:53] op_sel_hi:[0,1,1] neg_lo:[0,0,1] neg_hi:[0,0,1]
	v_pk_fma_f32 v[44:45], v[76:77], v[44:45], v[52:53] op_sel_hi:[0,1,1]
	v_pk_mul_f32 v[52:53], v[2:3], v[46:47] op_sel:[0,1] op_sel_hi:[0,0]
	v_mul_f32_e32 v50, s0, v56
	v_mul_f32_e32 v51, s0, v57
	v_pk_fma_f32 v[56:57], v[78:79], v[46:47], v[52:53] op_sel_hi:[0,1,1] neg_lo:[0,0,1] neg_hi:[0,0,1]
	v_pk_fma_f32 v[46:47], v[78:79], v[46:47], v[52:53] op_sel_hi:[0,1,1]
	v_mov_b32_e32 v57, v47
	v_mov_b32_e32 v55, v45
	v_lshlrev_b64 v[44:45], 10, v[100:101]
	v_mul_f32_e32 v52, s0, v56
	v_mul_f32_e32 v53, s0, v57
	v_mul_f32_e32 v46, s0, v54
	v_mul_f32_e32 v47, s0, v55
	v_lshl_add_u64 v[44:45], s[94:95], 0, v[44:45]
	v_lshl_add_u64 v[54:55], v[44:45], 0, v[60:61]
	v_cvt_pk_bf16_f32 v44, v48, v49
	v_cvt_pk_bf16_f32 v45, v50, v51
	v_cvt_pk_bf16_f32 v46, v46, v47
	v_cvt_pk_bf16_f32 v47, v52, v53
	v_mul_f32_e32 v40, v40, v96
	v_mul_f32_e32 v41, v41, v96
	global_store_dwordx4 v[54:55], v[44:47], off offset:256
	v_mul_f32_e32 v42, v42, v96
	v_mul_f32_e32 v43, v43, v96
	v_mov_b32_e32 v2, v75
	v_pk_mul_f32 v[44:45], v[72:73], v[40:41] op_sel:[1,1] op_sel_hi:[1,0]
	v_mul_f32_e32 v36, v36, v96
	v_mul_f32_e32 v37, v37, v96
	v_pk_fma_f32 v[46:47], v[72:73], v[40:41], v[44:45] op_sel_hi:[0,1,1] neg_lo:[0,0,1] neg_hi:[0,0,1]
	v_pk_fma_f32 v[40:41], v[72:73], v[40:41], v[44:45] op_sel_hi:[0,1,1]
	v_pk_mul_f32 v[44:45], v[2:3], v[42:43] op_sel:[0,1] op_sel_hi:[0,0]
	v_pk_fma_f32 v[48:49], v[74:75], v[42:43], v[44:45] op_sel_hi:[0,1,1] neg_lo:[0,0,1] neg_hi:[0,0,1]
	v_pk_fma_f32 v[42:43], v[74:75], v[42:43], v[44:45] op_sel_hi:[0,1,1]
	v_mov_b32_e32 v47, v41
	v_mul_f32_e32 v38, v38, v96
	v_mul_f32_e32 v39, v39, v96
	v_pk_mul_f32 v[44:45], v[68:69], v[36:37] op_sel:[1,1] op_sel_hi:[1,0]
	v_mov_b32_e32 v2, v71
	v_mov_b32_e32 v49, v43
	v_mul_f32_e32 v40, s0, v46
	v_mul_f32_e32 v41, s0, v47
	v_pk_fma_f32 v[46:47], v[68:69], v[36:37], v[44:45] op_sel_hi:[0,1,1] neg_lo:[0,0,1] neg_hi:[0,0,1]
	v_pk_fma_f32 v[36:37], v[68:69], v[36:37], v[44:45] op_sel_hi:[0,1,1]
	v_pk_mul_f32 v[44:45], v[2:3], v[38:39] op_sel:[0,1] op_sel_hi:[0,0]
	v_mul_f32_e32 v42, s0, v48
	v_mul_f32_e32 v43, s0, v49
	v_pk_fma_f32 v[48:49], v[70:71], v[38:39], v[44:45] op_sel_hi:[0,1,1] neg_lo:[0,0,1] neg_hi:[0,0,1]
	v_pk_fma_f32 v[38:39], v[70:71], v[38:39], v[44:45] op_sel_hi:[0,1,1]
	v_mov_b32_e32 v49, v39
	v_mov_b32_e32 v47, v37
	v_lshlrev_b64 v[36:37], 10, v[94:95]
	v_mul_f32_e32 v44, s0, v48
	v_mul_f32_e32 v45, s0, v49
	v_mul_f32_e32 v38, s0, v46
	v_mul_f32_e32 v39, s0, v47
	v_lshl_add_u64 v[36:37], s[94:95], 0, v[36:37]
	v_cvt_pk_bf16_f32 v110, v106, v107
	v_lshl_add_u64 v[46:47], v[36:37], 0, v[60:61]
	v_cvt_pk_bf16_f32 v36, v40, v41
	v_cvt_pk_bf16_f32 v37, v42, v43
	v_cvt_pk_bf16_f32 v38, v38, v39
	v_cvt_pk_bf16_f32 v39, v44, v45
	global_store_dwordx4 v[112:113], v[108:111], off offset:256
	global_store_dwordx4 v[46:47], v[36:39], off offset:256
	s_cbranch_scc1 .LBB0_45
	v_add_u32_e32 v74, 0x80, v92
	s_movk_i32 s0, 0x7cf
	v_cmp_gt_i32_e32 vcc, s20, v74
	v_and_or_b32 v2, v74, s0, 16
	v_ashrrev_i32_e32 v75, 31, v74
	v_cndmask_b32_e32 v2, v181, v2, vcc
	v_lshl_add_u64 v[48:49], v[74:75], 2, s[70:71]
	v_lshlrev_b32_e32 v2, 8, v2
	v_mov_b32_e32 v84, v246
	v_lshl_add_u64 v[36:37], v[182:183], 0, v[2:3]
	global_load_dwordx4 v[76:79], v[36:37], off offset:16
	global_load_dwordx4 v[80:83], v[36:37], off
	v_add_u32_e32 v62, 0x90, v92
	v_and_b32_e32 v2, 0x7df, v62
	v_cmp_gt_i32_e32 vcc, s20, v62
	v_add_u32_e32 v2, 16, v2
	v_mov_b32_e32 v72, v247
	v_cndmask_b32_e32 v2, v181, v2, vcc
	v_lshlrev_b32_e32 v2, 8, v2
	v_lshl_add_u64 v[36:37], v[182:183], 0, v[2:3]
	global_load_dwordx4 v[44:47], v[36:37], off offset:16
	global_load_dwordx4 v[56:59], v[36:37], off
	v_add_u32_e32 v64, 0xa0, v92
	s_movk_i32 s0, 0x7ef
	v_cmp_gt_i32_e32 vcc, s20, v64
	v_and_or_b32 v2, v64, s0, 16
	v_mov_b32_e32 v68, v248
	v_cndmask_b32_e32 v2, v181, v2, vcc
	v_lshlrev_b32_e32 v2, 8, v2
	v_lshl_add_u64 v[40:41], v[182:183], 0, v[2:3]
	global_load_dwordx4 v[36:39], v[40:41], off offset:16
	s_nop 0
	global_load_dwordx4 v[40:43], v[40:41], off
	v_add_u32_e32 v66, 0xb0, v92
	v_and_b32_e32 v2, 0x7ff, v66
	v_cmp_gt_i32_e32 vcc, s20, v66
	v_add_u32_e32 v2, 16, v2
	v_mov_b32_e32 v70, v249
	v_cndmask_b32_e32 v2, v181, v2, vcc
	v_lshlrev_b32_e32 v2, 8, v2
	v_lshl_add_u64 v[52:53], v[182:183], 0, v[2:3]
	global_load_dwordx4 v[48:51], v[52:53], off offset:16
	s_nop 0
	global_load_dwordx4 v[52:55], v[52:53], off
	s_mov_b32 s0, 0x3e000000
	v_ashrrev_i32_e32 v63, 31, v62
	v_ashrrev_i32_e32 v65, 31, v64
	v_ashrrev_i32_e32 v67, 31, v66
	s_waitcnt vmcnt(0)
	v_mul_f32_e32 v32, v32, v84
	v_mul_f32_e32 v33, v33, v84
	v_mul_f32_e32 v34, v34, v84
	v_mul_f32_e32 v35, v35, v84
	v_pk_mul_f32 v[86:87], v[80:81], v[32:33] op_sel:[1,1] op_sel_hi:[1,0]
	v_mov_b32_e32 v2, v83
	v_pk_fma_f32 v[88:89], v[80:81], v[32:33], v[86:87] op_sel_hi:[0,1,1] neg_lo:[0,0,1] neg_hi:[0,0,1]
	v_pk_fma_f32 v[32:33], v[80:81], v[32:33], v[86:87] op_sel_hi:[0,1,1]
	v_pk_mul_f32 v[80:81], v[2:3], v[34:35] op_sel:[0,1] op_sel_hi:[0,0]
	v_mul_f32_e32 v28, v28, v84
	v_mul_f32_e32 v29, v29, v84
	v_pk_fma_f32 v[86:87], v[82:83], v[34:35], v[80:81] op_sel_hi:[0,1,1] neg_lo:[0,0,1] neg_hi:[0,0,1]
	v_pk_fma_f32 v[34:35], v[82:83], v[34:35], v[80:81] op_sel_hi:[0,1,1]
	v_mul_f32_e32 v30, v30, v84
	v_mul_f32_e32 v31, v31, v84
	v_pk_mul_f32 v[80:81], v[76:77], v[28:29] op_sel:[1,1] op_sel_hi:[1,0]
	v_mov_b32_e32 v2, v79
	v_pk_fma_f32 v[82:83], v[76:77], v[28:29], v[80:81] op_sel_hi:[0,1,1] neg_lo:[0,0,1] neg_hi:[0,0,1]
	v_pk_fma_f32 v[28:29], v[76:77], v[28:29], v[80:81] op_sel_hi:[0,1,1]
	v_pk_mul_f32 v[76:77], v[2:3], v[30:31] op_sel:[0,1] op_sel_hi:[0,0]
	v_pk_fma_f32 v[80:81], v[78:79], v[30:31], v[76:77] op_sel_hi:[0,1,1] neg_lo:[0,0,1] neg_hi:[0,0,1]
	v_pk_fma_f32 v[30:31], v[78:79], v[30:31], v[76:77] op_sel_hi:[0,1,1]
	v_mov_b32_e32 v87, v35
	v_mov_b32_e32 v89, v33
	v_mov_b32_e32 v81, v31
	v_mov_b32_e32 v83, v29
	v_lshlrev_b64 v[28:29], 10, v[74:75]
	v_mul_f32_e32 v34, s0, v86
	v_mul_f32_e32 v35, s0, v87
	v_mul_f32_e32 v32, s0, v88
	v_mul_f32_e32 v33, s0, v89
	v_mul_f32_e32 v76, s0, v80
	v_mul_f32_e32 v77, s0, v81
	v_mul_f32_e32 v30, s0, v82
	v_mul_f32_e32 v31, s0, v83
	v_lshl_add_u64 v[28:29], s[94:95], 0, v[28:29]
	v_lshl_add_u64 v[74:75], v[28:29], 0, v[60:61]
	v_cvt_pk_bf16_f32 v28, v32, v33
	v_cvt_pk_bf16_f32 v29, v34, v35
	v_cvt_pk_bf16_f32 v30, v30, v31
	v_cvt_pk_bf16_f32 v31, v76, v77
	v_mul_f32_e32 v24, v24, v72
	v_mul_f32_e32 v25, v25, v72
	global_store_dwordx4 v[74:75], v[28:31], off offset:256
	v_mul_f32_e32 v26, v26, v72
	v_mul_f32_e32 v27, v27, v72
	v_mov_b32_e32 v2, v59
	v_pk_mul_f32 v[28:29], v[56:57], v[24:25] op_sel:[1,1] op_sel_hi:[1,0]
	v_mul_f32_e32 v20, v20, v72
	v_mul_f32_e32 v21, v21, v72
	v_pk_fma_f32 v[30:31], v[56:57], v[24:25], v[28:29] op_sel_hi:[0,1,1] neg_lo:[0,0,1] neg_hi:[0,0,1]
	v_pk_fma_f32 v[24:25], v[56:57], v[24:25], v[28:29] op_sel_hi:[0,1,1]
	v_pk_mul_f32 v[28:29], v[2:3], v[26:27] op_sel:[0,1] op_sel_hi:[0,0]
	v_pk_fma_f32 v[32:33], v[58:59], v[26:27], v[28:29] op_sel_hi:[0,1,1] neg_lo:[0,0,1] neg_hi:[0,0,1]
	v_pk_fma_f32 v[26:27], v[58:59], v[26:27], v[28:29] op_sel_hi:[0,1,1]
	v_mov_b32_e32 v31, v25
	v_mul_f32_e32 v22, v22, v72
	v_mul_f32_e32 v23, v23, v72
	v_pk_mul_f32 v[28:29], v[44:45], v[20:21] op_sel:[1,1] op_sel_hi:[1,0]
	v_mov_b32_e32 v2, v47
	v_mov_b32_e32 v33, v27
	v_mul_f32_e32 v24, s0, v30
	v_mul_f32_e32 v25, s0, v31
	v_pk_fma_f32 v[30:31], v[44:45], v[20:21], v[28:29] op_sel_hi:[0,1,1] neg_lo:[0,0,1] neg_hi:[0,0,1]
	v_pk_fma_f32 v[20:21], v[44:45], v[20:21], v[28:29] op_sel_hi:[0,1,1]
	v_pk_mul_f32 v[28:29], v[2:3], v[22:23] op_sel:[0,1] op_sel_hi:[0,0]
	v_mul_f32_e32 v26, s0, v32
	v_mul_f32_e32 v27, s0, v33
	v_pk_fma_f32 v[32:33], v[46:47], v[22:23], v[28:29] op_sel_hi:[0,1,1] neg_lo:[0,0,1] neg_hi:[0,0,1]
	v_pk_fma_f32 v[22:23], v[46:47], v[22:23], v[28:29] op_sel_hi:[0,1,1]
	v_mov_b32_e32 v33, v23
	v_mov_b32_e32 v31, v21
	v_lshlrev_b64 v[20:21], 10, v[62:63]
	v_mul_f32_e32 v28, s0, v32
	v_mul_f32_e32 v29, s0, v33
	v_mul_f32_e32 v22, s0, v30
	v_mul_f32_e32 v23, s0, v31
	v_lshl_add_u64 v[20:21], s[94:95], 0, v[20:21]
	v_lshl_add_u64 v[30:31], v[20:21], 0, v[60:61]
	v_cvt_pk_bf16_f32 v20, v24, v25
	v_cvt_pk_bf16_f32 v21, v26, v27
	v_cvt_pk_bf16_f32 v22, v22, v23
	v_cvt_pk_bf16_f32 v23, v28, v29
	v_mul_f32_e32 v16, v16, v68
	v_mul_f32_e32 v17, v17, v68
	global_store_dwordx4 v[30:31], v[20:23], off offset:256
	v_mul_f32_e32 v18, v18, v68
	v_mul_f32_e32 v19, v19, v68
	v_mov_b32_e32 v2, v43
	v_pk_mul_f32 v[20:21], v[40:41], v[16:17] op_sel:[1,1] op_sel_hi:[1,0]
	v_mul_f32_e32 v12, v12, v68
	v_mul_f32_e32 v13, v13, v68
	v_pk_fma_f32 v[22:23], v[40:41], v[16:17], v[20:21] op_sel_hi:[0,1,1] neg_lo:[0,0,1] neg_hi:[0,0,1]
	v_pk_fma_f32 v[16:17], v[40:41], v[16:17], v[20:21] op_sel_hi:[0,1,1]
	v_pk_mul_f32 v[20:21], v[2:3], v[18:19] op_sel:[0,1] op_sel_hi:[0,0]
	v_pk_fma_f32 v[24:25], v[42:43], v[18:19], v[20:21] op_sel_hi:[0,1,1] neg_lo:[0,0,1] neg_hi:[0,0,1]
	v_pk_fma_f32 v[18:19], v[42:43], v[18:19], v[20:21] op_sel_hi:[0,1,1]
	v_mov_b32_e32 v23, v17
	v_mul_f32_e32 v14, v14, v68
	v_mul_f32_e32 v15, v15, v68
	v_pk_mul_f32 v[20:21], v[36:37], v[12:13] op_sel:[1,1] op_sel_hi:[1,0]
	v_mov_b32_e32 v2, v39
	v_mov_b32_e32 v25, v19
	v_mul_f32_e32 v16, s0, v22
	v_mul_f32_e32 v17, s0, v23
	v_pk_fma_f32 v[22:23], v[36:37], v[12:13], v[20:21] op_sel_hi:[0,1,1] neg_lo:[0,0,1] neg_hi:[0,0,1]
	v_pk_fma_f32 v[12:13], v[36:37], v[12:13], v[20:21] op_sel_hi:[0,1,1]
	v_pk_mul_f32 v[20:21], v[2:3], v[14:15] op_sel:[0,1] op_sel_hi:[0,0]
	v_mul_f32_e32 v18, s0, v24
	v_mul_f32_e32 v19, s0, v25
	v_pk_fma_f32 v[24:25], v[38:39], v[14:15], v[20:21] op_sel_hi:[0,1,1] neg_lo:[0,0,1] neg_hi:[0,0,1]
	v_pk_fma_f32 v[14:15], v[38:39], v[14:15], v[20:21] op_sel_hi:[0,1,1]
	v_mov_b32_e32 v25, v15
	v_mov_b32_e32 v23, v13
	v_lshlrev_b64 v[12:13], 10, v[64:65]
	v_mul_f32_e32 v20, s0, v24
	v_mul_f32_e32 v21, s0, v25
	v_mul_f32_e32 v14, s0, v22
	v_mul_f32_e32 v15, s0, v23
	v_lshl_add_u64 v[12:13], s[94:95], 0, v[12:13]
	v_lshl_add_u64 v[22:23], v[12:13], 0, v[60:61]
	v_cvt_pk_bf16_f32 v12, v16, v17
	v_cvt_pk_bf16_f32 v13, v18, v19
	v_cvt_pk_bf16_f32 v14, v14, v15
	v_cvt_pk_bf16_f32 v15, v20, v21
	v_mul_f32_e32 v8, v8, v70
	v_mul_f32_e32 v9, v9, v70
	global_store_dwordx4 v[22:23], v[12:15], off offset:256
	v_mul_f32_e32 v10, v10, v70
	v_mul_f32_e32 v11, v11, v70
	v_mov_b32_e32 v2, v55
	v_pk_mul_f32 v[12:13], v[52:53], v[8:9] op_sel:[1,1] op_sel_hi:[1,0]
	v_mul_f32_e32 v4, v4, v70
	v_mul_f32_e32 v5, v5, v70
	v_pk_fma_f32 v[14:15], v[52:53], v[8:9], v[12:13] op_sel_hi:[0,1,1] neg_lo:[0,0,1] neg_hi:[0,0,1]
	v_pk_fma_f32 v[8:9], v[52:53], v[8:9], v[12:13] op_sel_hi:[0,1,1]
	v_pk_mul_f32 v[12:13], v[2:3], v[10:11] op_sel:[0,1] op_sel_hi:[0,0]
	v_pk_fma_f32 v[16:17], v[54:55], v[10:11], v[12:13] op_sel_hi:[0,1,1] neg_lo:[0,0,1] neg_hi:[0,0,1]
	v_pk_fma_f32 v[10:11], v[54:55], v[10:11], v[12:13] op_sel_hi:[0,1,1]
	v_mov_b32_e32 v15, v9
	v_mul_f32_e32 v6, v6, v70
	v_mul_f32_e32 v7, v7, v70
	v_pk_mul_f32 v[12:13], v[48:49], v[4:5] op_sel:[1,1] op_sel_hi:[1,0]
	v_mov_b32_e32 v2, v51
	v_mov_b32_e32 v17, v11
	v_mul_f32_e32 v8, s0, v14
	v_mul_f32_e32 v9, s0, v15
	v_pk_fma_f32 v[14:15], v[48:49], v[4:5], v[12:13] op_sel_hi:[0,1,1] neg_lo:[0,0,1] neg_hi:[0,0,1]
	v_pk_fma_f32 v[4:5], v[48:49], v[4:5], v[12:13] op_sel_hi:[0,1,1]
	v_pk_mul_f32 v[12:13], v[2:3], v[6:7] op_sel:[0,1] op_sel_hi:[0,0]
	v_mul_f32_e32 v10, s0, v16
	v_mul_f32_e32 v11, s0, v17
	v_pk_fma_f32 v[16:17], v[50:51], v[6:7], v[12:13] op_sel_hi:[0,1,1] neg_lo:[0,0,1] neg_hi:[0,0,1]
	v_pk_fma_f32 v[6:7], v[50:51], v[6:7], v[12:13] op_sel_hi:[0,1,1]
	v_mov_b32_e32 v17, v7
	v_mov_b32_e32 v15, v5
	v_lshlrev_b64 v[4:5], 10, v[66:67]
	v_mul_f32_e32 v12, s0, v16
	v_mul_f32_e32 v13, s0, v17
	v_mul_f32_e32 v6, s0, v14
	v_mul_f32_e32 v7, s0, v15
	v_lshl_add_u64 v[4:5], s[94:95], 0, v[4:5]
	v_lshl_add_u64 v[14:15], v[4:5], 0, v[60:61]
	v_cvt_pk_bf16_f32 v4, v8, v9
	v_cvt_pk_bf16_f32 v5, v10, v11
	v_cvt_pk_bf16_f32 v6, v6, v7
	v_cvt_pk_bf16_f32 v7, v12, v13
	global_store_dwordx4 v[14:15], v[4:7], off offset:256
	s_branch .LBB0_45

.LBB0_1098:
	s_add_u32 s4, s2, 0xfffc0080
	s_addc_u32 s5, s3, -1
	s_add_i32 s72, 0, 0x10000
	v_add_u32_e32 v152, s72, v157
	ds_read_b128 v[140:143], v152
	ds_read_b128 v[144:147], v152 offset:1024
	ds_read_b128 v[148:151], v152 offset:2048
	ds_read_b128 v[152:155], v152 offset:3072
	s_cmp_eq_u32 s53, 12
	s_cselect_b32 s17, s49, s5
	s_cselect_b32 s16, s48, s4
	s_cselect_b32 s5, s21, s11
	s_cselect_b32 s4, s20, s9
	v_lshl_add_u64 v[168:169], s[2:3], 0, v[136:137]
	s_add_i32 m0, s26, 0xc000
	ds_read_b128 v[160:163], v159
	ds_read_b128 v[172:175], v159 offset:1024
	ds_read_b128 v[176:179], v159 offset:2048
	ds_read_b128 v[180:183], v159 offset:3072
	ds_read_b128 v[184:187], v159 offset:4096
	ds_read_b128 v[188:191], v159 offset:5120
	ds_read_b128 v[192:195], v159 offset:6144
	ds_read_b128 v[196:199], v159 offset:7168
	global_load_lds_dwordx4 v[168:169], off
	v_lshl_add_u64 v[168:169], s[2:3], 0, v[138:139]
	s_add_i32 m0, s26, 0xe000
	s_nop 0
	global_load_lds_dwordx4 v[168:169], off
	s_waitcnt lgkmcnt(8)
	s_barrier
	s_waitcnt lgkmcnt(0)
	s_waitcnt lgkmcnt(0)
	v_mfma_f32_16x16x32_bf16 v[128:131], v[140:143], v[160:163], v[128:131]
	v_mfma_f32_16x16x32_bf16 v[124:127], v[148:151], v[160:163], v[124:127]
	v_mfma_f32_16x16x32_bf16 v[120:123], v[140:143], v[176:179], v[120:123]
	v_mfma_f32_16x16x32_bf16 v[116:119], v[148:151], v[176:179], v[116:119]
	v_mfma_f32_16x16x32_bf16 v[112:115], v[140:143], v[184:187], v[112:115]
	v_mfma_f32_16x16x32_bf16 v[108:111], v[148:151], v[184:187], v[108:111]
	v_mfma_f32_16x16x32_bf16 v[104:107], v[140:143], v[192:195], v[104:107]
	v_mfma_f32_16x16x32_bf16 v[100:103], v[148:151], v[192:195], v[100:103]
	v_mfma_f32_16x16x32_bf16 v[128:131], v[144:147], v[172:175], v[128:131]
	v_mfma_f32_16x16x32_bf16 v[124:127], v[152:155], v[172:175], v[124:127]
	v_mfma_f32_16x16x32_bf16 v[120:123], v[144:147], v[180:183], v[120:123]
	v_mfma_f32_16x16x32_bf16 v[116:119], v[152:155], v[180:183], v[116:119]
	v_mfma_f32_16x16x32_bf16 v[112:115], v[144:147], v[188:191], v[112:115]
	v_mfma_f32_16x16x32_bf16 v[108:111], v[152:155], v[188:191], v[108:111]
	v_mfma_f32_16x16x32_bf16 v[104:107], v[144:147], v[196:199], v[104:107]
	v_mfma_f32_16x16x32_bf16 v[100:103], v[152:155], v[196:199], v[100:103]
	s_barrier
	s_add_i32 s74, 0, 0x14000
	v_add_u32_e32 v168, s74, v157
	s_add_i32 s72, s72, s23
	ds_read_b128 v[200:203], v168
	ds_read_b128 v[204:207], v168 offset:1024
	ds_read_b128 v[208:211], v168 offset:2048
	ds_read_b128 v[220:223], v168 offset:3072
	v_lshl_add_u64 v[168:169], s[4:5], 0, v[2:3]
	s_mov_b32 m0, s72
	v_lshl_add_u64 v[214:215], s[4:5], 0, v[0:1]
	global_load_lds_dwordx4 v[168:169], off
	s_add_i32 m0, s72, 0x2000
	s_nop 0
	global_load_lds_dwordx4 v[214:215], off
	s_barrier
	s_waitcnt lgkmcnt(0)
	s_waitcnt lgkmcnt(0)
	v_mfma_f32_16x16x32_bf16 v[72:75], v[200:203], v[160:163], v[72:75]
	v_mfma_f32_16x16x32_bf16 v[68:71], v[208:211], v[160:163], v[68:71]
	v_mfma_f32_16x16x32_bf16 v[56:59], v[200:203], v[176:179], v[56:59]
	v_mfma_f32_16x16x32_bf16 v[52:55], v[208:211], v[176:179], v[52:55]
	v_mfma_f32_16x16x32_bf16 v[48:51], v[200:203], v[184:187], v[48:51]
	v_mfma_f32_16x16x32_bf16 v[44:47], v[208:211], v[184:187], v[44:47]
	v_mfma_f32_16x16x32_bf16 v[40:43], v[200:203], v[192:195], v[40:43]
	v_mfma_f32_16x16x32_bf16 v[36:39], v[208:211], v[192:195], v[36:39]
	v_mfma_f32_16x16x32_bf16 v[72:75], v[204:207], v[172:175], v[72:75]
	v_mfma_f32_16x16x32_bf16 v[68:71], v[220:223], v[172:175], v[68:71]
	v_mfma_f32_16x16x32_bf16 v[56:59], v[204:207], v[180:183], v[56:59]
	v_mfma_f32_16x16x32_bf16 v[52:55], v[220:223], v[180:183], v[52:55]
	v_mfma_f32_16x16x32_bf16 v[48:51], v[204:207], v[188:191], v[48:51]
	v_mfma_f32_16x16x32_bf16 v[44:47], v[220:223], v[188:191], v[44:47]
	v_mfma_f32_16x16x32_bf16 v[40:43], v[204:207], v[196:199], v[40:43]
	v_mfma_f32_16x16x32_bf16 v[36:39], v[220:223], v[196:199], v[36:39]
	s_mov_b32 m0, s26
	v_lshl_add_u64 v[224:225], s[16:17], 0, v[134:135]
	s_barrier
	ds_read_b128 v[160:163], v159 offset:16384
	ds_read_b128 v[172:175], v159 offset:17408
	ds_read_b128 v[176:179], v159 offset:18432
	ds_read_b128 v[180:183], v159 offset:19456
	ds_read_b128 v[184:187], v159 offset:20480
	ds_read_b128 v[188:191], v159 offset:21504
	ds_read_b128 v[192:195], v159 offset:22528
	ds_read_b128 v[196:199], v159 offset:23552
	global_load_lds_dwordx4 v[224:225], off
	v_lshl_add_u64 v[234:235], s[16:17], 0, v[132:133]
	s_mov_b32 m0, s27
	s_nop 0
	global_load_lds_dwordx4 v[234:235], off
	s_barrier
	s_waitcnt lgkmcnt(0)
	s_waitcnt lgkmcnt(0)
	v_mfma_f32_16x16x32_bf16 v[96:99], v[140:143], v[160:163], v[96:99]
	v_mfma_f32_16x16x32_bf16 v[92:95], v[148:151], v[160:163], v[92:95]
	v_mfma_f32_16x16x32_bf16 v[88:91], v[140:143], v[176:179], v[88:91]
	v_mfma_f32_16x16x32_bf16 v[84:87], v[148:151], v[176:179], v[84:87]
	v_mfma_f32_16x16x32_bf16 v[80:83], v[140:143], v[184:187], v[80:83]
	v_mfma_f32_16x16x32_bf16 v[76:79], v[148:151], v[184:187], v[76:79]
	v_mfma_f32_16x16x32_bf16 v[64:67], v[140:143], v[192:195], v[64:67]
	v_mfma_f32_16x16x32_bf16 v[60:63], v[148:151], v[192:195], v[60:63]
	v_mfma_f32_16x16x32_bf16 v[96:99], v[144:147], v[172:175], v[96:99]
	v_mfma_f32_16x16x32_bf16 v[92:95], v[152:155], v[172:175], v[92:95]
	v_mfma_f32_16x16x32_bf16 v[88:91], v[144:147], v[180:183], v[88:91]
	v_mfma_f32_16x16x32_bf16 v[84:87], v[152:155], v[180:183], v[84:87]
	v_mfma_f32_16x16x32_bf16 v[80:83], v[144:147], v[188:191], v[80:83]
	v_mfma_f32_16x16x32_bf16 v[76:79], v[152:155], v[188:191], v[76:79]
	v_mfma_f32_16x16x32_bf16 v[64:67], v[144:147], v[196:199], v[64:67]
	v_mfma_f32_16x16x32_bf16 v[60:63], v[152:155], v[196:199], v[60:63]
	s_barrier
	s_add_u32 s72, s4, 0x40000
	s_addc_u32 s73, s5, 0
	s_add_i32 s74, s74, s23
	v_lshl_add_u64 v[140:141], s[72:73], 0, v[2:3]
	s_mov_b32 m0, s74
	s_nop 0
	global_load_lds_dwordx4 v[140:141], off
	v_lshl_add_u64 v[140:141], s[72:73], 0, v[0:1]
	s_add_i32 m0, s74, 0x2000
	s_nop 0
	global_load_lds_dwordx4 v[140:141], off
	s_waitcnt vmcnt(6)
	s_barrier
	v_mfma_f32_16x16x32_bf16 v[32:35], v[200:203], v[160:163], v[32:35]
	v_mfma_f32_16x16x32_bf16 v[28:31], v[208:211], v[160:163], v[28:31]
	v_mfma_f32_16x16x32_bf16 v[24:27], v[200:203], v[176:179], v[24:27]
	v_mfma_f32_16x16x32_bf16 v[20:23], v[208:211], v[176:179], v[20:23]
	v_mfma_f32_16x16x32_bf16 v[16:19], v[200:203], v[184:187], v[16:19]
	v_mfma_f32_16x16x32_bf16 v[12:15], v[208:211], v[184:187], v[12:15]
	v_mfma_f32_16x16x32_bf16 v[8:11], v[200:203], v[192:195], v[8:11]
	v_mfma_f32_16x16x32_bf16 v[4:7], v[208:211], v[192:195], v[4:7]
	v_mfma_f32_16x16x32_bf16 v[32:35], v[204:207], v[172:175], v[32:35]
	v_mfma_f32_16x16x32_bf16 v[28:31], v[220:223], v[172:175], v[28:31]
	v_mfma_f32_16x16x32_bf16 v[24:27], v[204:207], v[180:183], v[24:27]
	v_mfma_f32_16x16x32_bf16 v[20:23], v[220:223], v[180:183], v[20:23]
	v_mfma_f32_16x16x32_bf16 v[16:19], v[204:207], v[188:191], v[16:19]
	v_mfma_f32_16x16x32_bf16 v[12:15], v[220:223], v[188:191], v[12:15]
	v_mfma_f32_16x16x32_bf16 v[8:11], v[204:207], v[196:199], v[8:11]
	v_mfma_f32_16x16x32_bf16 v[4:7], v[220:223], v[196:199], v[4:7]
	s_add_i32 s72, 0, 0x18000
	v_add_u32_e32 v152, s72, v157
	s_barrier
	ds_read_b128 v[140:143], v152
	ds_read_b128 v[144:147], v152 offset:1024
	ds_read_b128 v[148:151], v152 offset:2048
	ds_read_b128 v[152:155], v152 offset:3072
	s_add_u32 s16, s16, 0x40000
	s_addc_u32 s17, s17, 0
	s_mov_b32 m0, s30
	v_lshl_add_u64 v[200:201], s[16:17], 0, v[134:135]
	ds_read_b128 v[160:163], v159 offset:32768
	ds_read_b128 v[172:175], v159 offset:33792
	ds_read_b128 v[176:179], v159 offset:34816
	ds_read_b128 v[180:183], v159 offset:35840
	ds_read_b128 v[184:187], v159 offset:36864
	ds_read_b128 v[188:191], v159 offset:37888
	ds_read_b128 v[192:195], v159 offset:38912
	ds_read_b128 v[196:199], v159 offset:39936
	global_load_lds_dwordx4 v[200:201], off
	v_lshl_add_u64 v[200:201], s[16:17], 0, v[132:133]
	s_mov_b32 m0, s31
	s_nop 0
	global_load_lds_dwordx4 v[200:201], off
	s_waitcnt lgkmcnt(8)
	s_barrier
	s_waitcnt lgkmcnt(0)
	s_waitcnt lgkmcnt(0)
	v_mfma_f32_16x16x32_bf16 v[128:131], v[140:143], v[160:163], v[128:131]
	v_mfma_f32_16x16x32_bf16 v[124:127], v[148:151], v[160:163], v[124:127]
	v_mfma_f32_16x16x32_bf16 v[120:123], v[140:143], v[176:179], v[120:123]
	v_mfma_f32_16x16x32_bf16 v[116:119], v[148:151], v[176:179], v[116:119]
	v_mfma_f32_16x16x32_bf16 v[112:115], v[140:143], v[184:187], v[112:115]
	v_mfma_f32_16x16x32_bf16 v[108:111], v[148:151], v[184:187], v[108:111]
	v_mfma_f32_16x16x32_bf16 v[104:107], v[140:143], v[192:195], v[104:107]
	v_mfma_f32_16x16x32_bf16 v[100:103], v[148:151], v[192:195], v[100:103]
	v_mfma_f32_16x16x32_bf16 v[128:131], v[144:147], v[172:175], v[128:131]
	v_mfma_f32_16x16x32_bf16 v[124:127], v[152:155], v[172:175], v[124:127]
	v_mfma_f32_16x16x32_bf16 v[120:123], v[144:147], v[180:183], v[120:123]
	v_mfma_f32_16x16x32_bf16 v[116:119], v[152:155], v[180:183], v[116:119]
	v_mfma_f32_16x16x32_bf16 v[112:115], v[144:147], v[188:191], v[112:115]
	v_mfma_f32_16x16x32_bf16 v[108:111], v[152:155], v[188:191], v[108:111]
	v_mfma_f32_16x16x32_bf16 v[104:107], v[144:147], v[196:199], v[104:107]
	v_mfma_f32_16x16x32_bf16 v[100:103], v[152:155], v[196:199], v[100:103]
	s_barrier
	s_add_i32 s16, 0, 0x1c000
	s_add_i32 s17, s72, s23
	v_add_u32_e32 v170, s16, v157
	v_lshl_add_u64 v[168:169], v[168:169], 0, s[28:29]
	s_mov_b32 m0, s17
	ds_read_b128 v[200:203], v170
	ds_read_b128 v[204:207], v170 offset:1024
	ds_read_b128 v[208:211], v170 offset:2048
	ds_read_b128 v[220:223], v170 offset:3072
	global_load_lds_dwordx4 v[168:169], off
	v_lshl_add_u64 v[168:169], v[214:215], 0, s[28:29]
	s_add_i32 m0, s17, 0x2000
	s_nop 0
	global_load_lds_dwordx4 v[168:169], off
	s_barrier
	s_waitcnt lgkmcnt(0)
	s_waitcnt lgkmcnt(0)
	v_mfma_f32_16x16x32_bf16 v[72:75], v[200:203], v[160:163], v[72:75]
	v_mfma_f32_16x16x32_bf16 v[68:71], v[208:211], v[160:163], v[68:71]
	v_mfma_f32_16x16x32_bf16 v[56:59], v[200:203], v[176:179], v[56:59]
	v_mfma_f32_16x16x32_bf16 v[52:55], v[208:211], v[176:179], v[52:55]
	v_mfma_f32_16x16x32_bf16 v[48:51], v[200:203], v[184:187], v[48:51]
	v_mfma_f32_16x16x32_bf16 v[44:47], v[208:211], v[184:187], v[44:47]
	v_mfma_f32_16x16x32_bf16 v[40:43], v[200:203], v[192:195], v[40:43]
	v_mfma_f32_16x16x32_bf16 v[36:39], v[208:211], v[192:195], v[36:39]
	v_mfma_f32_16x16x32_bf16 v[72:75], v[204:207], v[172:175], v[72:75]
	v_mfma_f32_16x16x32_bf16 v[68:71], v[220:223], v[172:175], v[68:71]
	v_mfma_f32_16x16x32_bf16 v[56:59], v[204:207], v[180:183], v[56:59]
	v_mfma_f32_16x16x32_bf16 v[52:55], v[220:223], v[180:183], v[52:55]
	v_mfma_f32_16x16x32_bf16 v[48:51], v[204:207], v[188:191], v[48:51]
	v_mfma_f32_16x16x32_bf16 v[44:47], v[220:223], v[188:191], v[44:47]
	v_mfma_f32_16x16x32_bf16 v[40:43], v[204:207], v[196:199], v[40:43]
	v_mfma_f32_16x16x32_bf16 v[36:39], v[220:223], v[196:199], v[36:39]
	s_mov_b32 m0, s50
	v_lshl_add_u64 v[168:169], v[224:225], 0, s[28:29]
	s_barrier
	ds_read_b128 v[160:163], v159 offset:49152
	ds_read_b128 v[172:175], v159 offset:50176
	ds_read_b128 v[176:179], v159 offset:51200
	ds_read_b128 v[180:183], v159 offset:52224
	ds_read_b128 v[184:187], v159 offset:53248
	ds_read_b128 v[188:191], v159 offset:54272
	ds_read_b128 v[192:195], v159 offset:55296
	ds_read_b128 v[196:199], v159 offset:56320
	global_load_lds_dwordx4 v[168:169], off
	v_lshl_add_u64 v[168:169], v[234:235], 0, s[28:29]
	s_mov_b32 m0, s51
	s_nop 0
	global_load_lds_dwordx4 v[168:169], off
	s_barrier
	s_waitcnt lgkmcnt(0)
	s_waitcnt lgkmcnt(0)
	v_mfma_f32_16x16x32_bf16 v[96:99], v[140:143], v[160:163], v[96:99]
	v_mfma_f32_16x16x32_bf16 v[92:95], v[148:151], v[160:163], v[92:95]
	v_mfma_f32_16x16x32_bf16 v[88:91], v[140:143], v[176:179], v[88:91]
	v_mfma_f32_16x16x32_bf16 v[84:87], v[148:151], v[176:179], v[84:87]
	v_mfma_f32_16x16x32_bf16 v[80:83], v[140:143], v[184:187], v[80:83]
	v_mfma_f32_16x16x32_bf16 v[76:79], v[148:151], v[184:187], v[76:79]
	v_mfma_f32_16x16x32_bf16 v[64:67], v[140:143], v[192:195], v[64:67]
	v_mfma_f32_16x16x32_bf16 v[60:63], v[148:151], v[192:195], v[60:63]
	v_mfma_f32_16x16x32_bf16 v[96:99], v[144:147], v[172:175], v[96:99]
	v_mfma_f32_16x16x32_bf16 v[92:95], v[152:155], v[172:175], v[92:95]
	v_mfma_f32_16x16x32_bf16 v[88:91], v[144:147], v[180:183], v[88:91]
	v_mfma_f32_16x16x32_bf16 v[84:87], v[152:155], v[180:183], v[84:87]
	v_mfma_f32_16x16x32_bf16 v[80:83], v[144:147], v[188:191], v[80:83]
	v_mfma_f32_16x16x32_bf16 v[76:79], v[152:155], v[188:191], v[76:79]
	v_mfma_f32_16x16x32_bf16 v[64:67], v[144:147], v[196:199], v[64:67]
	v_mfma_f32_16x16x32_bf16 v[60:63], v[152:155], v[196:199], v[60:63]
	s_barrier
	s_add_u32 s4, s4, 0x40080
	s_addc_u32 s5, s5, 0
	s_add_i32 s16, s16, s23
	v_lshl_add_u64 v[140:141], s[4:5], 0, v[2:3]
	s_mov_b32 m0, s16
	s_nop 0
	global_load_lds_dwordx4 v[140:141], off
	v_lshl_add_u64 v[140:141], s[4:5], 0, v[0:1]
	s_add_i32 m0, s16, 0x2000
	s_nop 0
	global_load_lds_dwordx4 v[140:141], off
	s_waitcnt vmcnt(6)
	s_barrier
	v_mfma_f32_16x16x32_bf16 v[32:35], v[200:203], v[160:163], v[32:35]
	v_mfma_f32_16x16x32_bf16 v[28:31], v[208:211], v[160:163], v[28:31]
	v_mfma_f32_16x16x32_bf16 v[24:27], v[200:203], v[176:179], v[24:27]
	v_mfma_f32_16x16x32_bf16 v[20:23], v[208:211], v[176:179], v[20:23]
	v_mfma_f32_16x16x32_bf16 v[16:19], v[200:203], v[184:187], v[16:19]
	v_mfma_f32_16x16x32_bf16 v[12:15], v[208:211], v[184:187], v[12:15]
	v_mfma_f32_16x16x32_bf16 v[8:11], v[200:203], v[192:195], v[8:11]
	v_mfma_f32_16x16x32_bf16 v[4:7], v[208:211], v[192:195], v[4:7]
	v_mfma_f32_16x16x32_bf16 v[32:35], v[204:207], v[172:175], v[32:35]
	v_mfma_f32_16x16x32_bf16 v[28:31], v[220:223], v[172:175], v[28:31]
	v_mfma_f32_16x16x32_bf16 v[24:27], v[204:207], v[180:183], v[24:27]
	v_mfma_f32_16x16x32_bf16 v[20:23], v[220:223], v[180:183], v[20:23]
	v_mfma_f32_16x16x32_bf16 v[16:19], v[204:207], v[188:191], v[16:19]
	v_mfma_f32_16x16x32_bf16 v[12:15], v[220:223], v[188:191], v[12:15]
	v_mfma_f32_16x16x32_bf16 v[8:11], v[204:207], v[196:199], v[8:11]
	v_mfma_f32_16x16x32_bf16 v[4:7], v[220:223], v[196:199], v[4:7]
	s_add_i32 s53, s53, 2
	s_add_u32 s2, s2, 0x100
	s_addc_u32 s3, s3, 0
	s_add_u32 s9, s9, 0x100
	s_addc_u32 s11, s11, 0
	s_cmp_gt_u32 s53, 13
	s_barrier
	s_cbranch_scc0 .LBB0_1098
	v_lshl_add_u32 v154, s37, 8, v156
	v_ashrrev_i32_e32 v155, 31, v154
	v_lshl_add_u64 v[168:169], v[154:155], 2, s[70:71]
	v_mov_b32_e32 v174, v164
	v_mov_b32_e32 v173, v165
	v_mov_b32_e32 v172, v166
	v_mov_b32_e32 v170, v167
	v_mov_b32_e32 v163, v246
	v_mov_b32_e32 v162, v247
	v_mov_b32_e32 v161, v248
	v_mov_b32_e32 v160, v249
	v_lshl_or_b32 v168, s36, 8, v158
	v_ashrrev_i32_e32 v169, 31, v168
	v_or_b32_e32 v152, 16, v154
	v_ashrrev_i32_e32 v153, 31, v152
	v_or_b32_e32 v150, 32, v154
	v_ashrrev_i32_e32 v151, 31, v150
	v_or_b32_e32 v148, 48, v154
	v_ashrrev_i32_e32 v149, 31, v148
	v_add_u32_e32 v146, 0x80, v154
	v_ashrrev_i32_e32 v147, 31, v146
	v_add_u32_e32 v144, 0x90, v154
	v_ashrrev_i32_e32 v145, 31, v144
	v_add_u32_e32 v142, 0xa0, v154
	v_ashrrev_i32_e32 v143, 31, v142
	v_add_u32_e32 v140, 0xb0, v154
	v_ashrrev_i32_e32 v141, 31, v140
	v_readlane_b32 s72, v255, 28
	s_and_b64 vcc, exec, s[46:47]
	s_mov_b32 s36, s8
	s_mov_b32 s37, s10
	s_mov_b64 s[4:5], s[20:21]
	s_mov_b64 s[2:3], s[48:49]
	v_readlane_b32 s73, v255, 29
	v_mul_f32_e32 v124, v124, v174
	v_mul_f32_e32 v125, v125, v174
	v_max_f32_e32 v124, 0, v124
	v_max_f32_e32 v125, 0, v125
	v_mul_f32_e32 v176, v124, v124
	v_mul_f32_e32 v177, v125, v125
	v_mul_f32_e32 v125, v126, v174
	v_mul_f32_e32 v124, v174, v130
	v_max_f32_e32 v126, 0, v125
	v_mul_f32_e32 v125, v174, v131
	v_mul_f32_e32 v128, v174, v128
	v_mul_f32_e32 v129, v174, v129
	v_max_f32_e32 v124, 0, v124
	v_max_f32_e32 v125, 0, v125
	v_mul_f32_e32 v127, v127, v174
	v_max_f32_e32 v128, 0, v128
	v_max_f32_e32 v129, 0, v129
	v_max_f32_e32 v127, 0, v127
	v_mul_f32_e32 v130, v124, v124
	v_mul_f32_e32 v131, v125, v125
	v_lshlrev_b64 v[124:125], 13, v[154:155]
	v_mul_f32_e32 v128, v128, v128
	v_mul_f32_e32 v129, v129, v129
	v_mul_f32_e32 v178, v126, v126
	v_mul_f32_e32 v179, v127, v127
	v_lshl_add_u64 v[124:125], s[94:95], 0, v[124:125]
	v_lshlrev_b64 v[126:127], 1, v[168:169]
	v_mul_f32_e32 v116, v116, v173
	v_mul_f32_e32 v117, v117, v173
	v_lshl_add_u64 v[124:125], v[124:125], 0, v[126:127]
	v_cvt_pk_bf16_f32 v128, v128, v129
	v_cvt_pk_bf16_f32 v129, v130, v131
	v_cvt_pk_bf16_f32 v130, v176, v177
	v_cvt_pk_bf16_f32 v131, v178, v179
	v_max_f32_e32 v116, 0, v116
	v_max_f32_e32 v117, 0, v117
	global_store_dwordx4 v[124:125], v[128:131], off
	v_mul_f32_e32 v120, v120, v173
	v_mul_f32_e32 v121, v121, v173
	v_mul_f32_e32 v128, v116, v116
	v_mul_f32_e32 v129, v117, v117
	v_mul_f32_e32 v117, v118, v173
	v_mul_f32_e32 v116, v122, v173
	v_max_f32_e32 v118, 0, v117
	v_mul_f32_e32 v117, v123, v173
	v_max_f32_e32 v116, 0, v116
	v_max_f32_e32 v117, 0, v117
	v_mul_f32_e32 v119, v119, v173
	v_max_f32_e32 v120, 0, v120
	v_max_f32_e32 v121, 0, v121
	v_max_f32_e32 v119, 0, v119
	v_mul_f32_e32 v122, v116, v116
	v_mul_f32_e32 v123, v117, v117
	v_lshlrev_b64 v[116:117], 13, v[152:153]
	v_mul_f32_e32 v120, v120, v120
	v_mul_f32_e32 v121, v121, v121
	v_mul_f32_e32 v130, v118, v118
	v_mul_f32_e32 v131, v119, v119
	v_lshl_add_u64 v[116:117], s[94:95], 0, v[116:117]
	v_mul_f32_e32 v108, v108, v172
	v_mul_f32_e32 v109, v109, v172
	v_lshl_add_u64 v[116:117], v[116:117], 0, v[126:127]
	v_cvt_pk_bf16_f32 v118, v120, v121
	v_cvt_pk_bf16_f32 v119, v122, v123
	v_cvt_pk_bf16_f32 v120, v128, v129
	v_cvt_pk_bf16_f32 v121, v130, v131
	v_max_f32_e32 v108, 0, v108
	v_max_f32_e32 v109, 0, v109
	global_store_dwordx4 v[116:117], v[118:121], off
	v_mul_f32_e32 v112, v112, v172
	v_mul_f32_e32 v113, v113, v172
	v_mul_f32_e32 v118, v108, v108
	v_mul_f32_e32 v119, v109, v109
	v_mul_f32_e32 v109, v110, v172
	v_mul_f32_e32 v108, v114, v172
	v_max_f32_e32 v110, 0, v109
	v_mul_f32_e32 v109, v115, v172
	v_max_f32_e32 v108, 0, v108
	v_max_f32_e32 v109, 0, v109
	v_mul_f32_e32 v111, v111, v172
	v_max_f32_e32 v112, 0, v112
	v_max_f32_e32 v113, 0, v113
	v_max_f32_e32 v111, 0, v111
	v_mul_f32_e32 v114, v108, v108
	v_mul_f32_e32 v115, v109, v109
	v_lshlrev_b64 v[108:109], 13, v[150:151]
	v_mul_f32_e32 v112, v112, v112
	v_mul_f32_e32 v113, v113, v113
	v_mul_f32_e32 v120, v110, v110
	v_mul_f32_e32 v121, v111, v111
	v_lshl_add_u64 v[108:109], s[94:95], 0, v[108:109]
	v_mul_f32_e32 v100, v100, v170
	v_mul_f32_e32 v101, v101, v170
	v_lshl_add_u64 v[108:109], v[108:109], 0, v[126:127]
	v_cvt_pk_bf16_f32 v110, v112, v113
	v_cvt_pk_bf16_f32 v111, v114, v115
	v_cvt_pk_bf16_f32 v112, v118, v119
	v_cvt_pk_bf16_f32 v113, v120, v121
	v_max_f32_e32 v100, 0, v100
	v_max_f32_e32 v101, 0, v101
	global_store_dwordx4 v[108:109], v[110:113], off
	v_mul_f32_e32 v104, v104, v170
	v_mul_f32_e32 v105, v105, v170
	v_mul_f32_e32 v110, v100, v100
	v_mul_f32_e32 v111, v101, v101
	v_mul_f32_e32 v101, v102, v170
	v_mul_f32_e32 v100, v106, v170
	v_max_f32_e32 v102, 0, v101
	v_mul_f32_e32 v101, v107, v170
	v_max_f32_e32 v100, 0, v100
	v_max_f32_e32 v101, 0, v101
	v_mul_f32_e32 v103, v103, v170
	v_max_f32_e32 v104, 0, v104
	v_max_f32_e32 v105, 0, v105
	v_max_f32_e32 v103, 0, v103
	v_mul_f32_e32 v106, v100, v100
	v_mul_f32_e32 v107, v101, v101
	v_lshlrev_b64 v[100:101], 13, v[148:149]
	v_mul_f32_e32 v104, v104, v104
	v_mul_f32_e32 v105, v105, v105
	v_mul_f32_e32 v112, v102, v102
	v_mul_f32_e32 v113, v103, v103
	v_lshl_add_u64 v[100:101], s[94:95], 0, v[100:101]
	v_mul_f32_e32 v92, v92, v163
	v_mul_f32_e32 v93, v93, v163
	v_lshl_add_u64 v[100:101], v[100:101], 0, v[126:127]
	v_cvt_pk_bf16_f32 v102, v104, v105
	v_cvt_pk_bf16_f32 v103, v106, v107
	v_cvt_pk_bf16_f32 v104, v110, v111
	v_cvt_pk_bf16_f32 v105, v112, v113
	v_max_f32_e32 v92, 0, v92
	v_max_f32_e32 v93, 0, v93
	global_store_dwordx4 v[100:101], v[102:105], off
	v_mul_f32_e32 v96, v96, v163
	v_mul_f32_e32 v97, v97, v163
	v_mul_f32_e32 v102, v92, v92
	v_mul_f32_e32 v103, v93, v93
	v_mul_f32_e32 v93, v94, v163
	v_mul_f32_e32 v92, v98, v163
	v_max_f32_e32 v94, 0, v93
	v_mul_f32_e32 v93, v99, v163
	v_max_f32_e32 v92, 0, v92
	v_max_f32_e32 v93, 0, v93
	v_mul_f32_e32 v95, v95, v163
	v_max_f32_e32 v96, 0, v96
	v_max_f32_e32 v97, 0, v97
	v_max_f32_e32 v95, 0, v95
	v_mul_f32_e32 v98, v92, v92
	v_mul_f32_e32 v99, v93, v93
	v_lshlrev_b64 v[92:93], 13, v[146:147]
	v_mul_f32_e32 v96, v96, v96
	v_mul_f32_e32 v97, v97, v97
	v_mul_f32_e32 v104, v94, v94
	v_mul_f32_e32 v105, v95, v95
	v_lshl_add_u64 v[92:93], s[94:95], 0, v[92:93]
	v_mul_f32_e32 v84, v84, v162
	v_mul_f32_e32 v85, v85, v162
	v_lshl_add_u64 v[92:93], v[92:93], 0, v[126:127]
	v_cvt_pk_bf16_f32 v94, v96, v97
	v_cvt_pk_bf16_f32 v95, v98, v99
	v_cvt_pk_bf16_f32 v96, v102, v103
	v_cvt_pk_bf16_f32 v97, v104, v105
	v_max_f32_e32 v84, 0, v84
	v_max_f32_e32 v85, 0, v85
	global_store_dwordx4 v[92:93], v[94:97], off
	v_mul_f32_e32 v88, v88, v162
	v_mul_f32_e32 v89, v89, v162
	v_mul_f32_e32 v94, v84, v84
	v_mul_f32_e32 v95, v85, v85
	v_mul_f32_e32 v85, v86, v162
	v_mul_f32_e32 v84, v90, v162
	v_max_f32_e32 v86, 0, v85
	v_mul_f32_e32 v85, v91, v162
	v_max_f32_e32 v84, 0, v84
	v_max_f32_e32 v85, 0, v85
	v_mul_f32_e32 v87, v87, v162
	v_max_f32_e32 v88, 0, v88
	v_max_f32_e32 v89, 0, v89
	v_max_f32_e32 v87, 0, v87
	v_mul_f32_e32 v90, v84, v84
	v_mul_f32_e32 v91, v85, v85
	v_lshlrev_b64 v[84:85], 13, v[144:145]
	v_mul_f32_e32 v88, v88, v88
	v_mul_f32_e32 v89, v89, v89
	v_mul_f32_e32 v96, v86, v86
	v_mul_f32_e32 v97, v87, v87
	v_lshl_add_u64 v[84:85], s[94:95], 0, v[84:85]
	v_mul_f32_e32 v76, v76, v161
	v_mul_f32_e32 v77, v77, v161
	v_lshl_add_u64 v[84:85], v[84:85], 0, v[126:127]
	v_cvt_pk_bf16_f32 v86, v88, v89
	v_cvt_pk_bf16_f32 v87, v90, v91
	v_cvt_pk_bf16_f32 v88, v94, v95
	v_cvt_pk_bf16_f32 v89, v96, v97
	v_max_f32_e32 v76, 0, v76
	v_max_f32_e32 v77, 0, v77
	global_store_dwordx4 v[84:85], v[86:89], off
	v_mul_f32_e32 v80, v80, v161
	v_mul_f32_e32 v81, v81, v161
	v_mul_f32_e32 v86, v76, v76
	v_mul_f32_e32 v87, v77, v77
	v_mul_f32_e32 v77, v78, v161
	v_mul_f32_e32 v76, v82, v161
	v_max_f32_e32 v78, 0, v77
	v_mul_f32_e32 v77, v83, v161
	v_max_f32_e32 v76, 0, v76
	v_max_f32_e32 v77, 0, v77
	v_mul_f32_e32 v79, v79, v161
	v_max_f32_e32 v80, 0, v80
	v_max_f32_e32 v81, 0, v81
	v_max_f32_e32 v79, 0, v79
	v_mul_f32_e32 v82, v76, v76
	v_mul_f32_e32 v83, v77, v77
	v_lshlrev_b64 v[76:77], 13, v[142:143]
	v_mul_f32_e32 v80, v80, v80
	v_mul_f32_e32 v81, v81, v81
	v_mul_f32_e32 v88, v78, v78
	v_mul_f32_e32 v89, v79, v79
	v_lshl_add_u64 v[76:77], s[94:95], 0, v[76:77]
	v_mul_f32_e32 v60, v60, v160
	v_mul_f32_e32 v61, v61, v160
	v_lshl_add_u64 v[76:77], v[76:77], 0, v[126:127]
	v_cvt_pk_bf16_f32 v78, v80, v81
	v_cvt_pk_bf16_f32 v79, v82, v83
	v_cvt_pk_bf16_f32 v80, v86, v87
	v_cvt_pk_bf16_f32 v81, v88, v89
	v_max_f32_e32 v60, 0, v60
	v_max_f32_e32 v61, 0, v61
	global_store_dwordx4 v[76:77], v[78:81], off
	v_mul_f32_e32 v64, v64, v160
	v_mul_f32_e32 v65, v65, v160
	v_mul_f32_e32 v78, v60, v60
	v_mul_f32_e32 v79, v61, v61
	v_mul_f32_e32 v61, v62, v160
	v_mul_f32_e32 v60, v66, v160
	v_max_f32_e32 v62, 0, v61
	v_mul_f32_e32 v61, v67, v160
	v_max_f32_e32 v60, 0, v60
	v_max_f32_e32 v61, 0, v61
	v_mul_f32_e32 v63, v63, v160
	v_max_f32_e32 v64, 0, v64
	v_max_f32_e32 v65, 0, v65
	v_max_f32_e32 v63, 0, v63
	v_mul_f32_e32 v66, v60, v60
	v_mul_f32_e32 v67, v61, v61
	v_lshlrev_b64 v[60:61], 13, v[140:141]
	v_mul_f32_e32 v64, v64, v64
	v_mul_f32_e32 v65, v65, v65
	v_mul_f32_e32 v80, v62, v62
	v_mul_f32_e32 v81, v63, v63
	v_lshl_add_u64 v[60:61], s[94:95], 0, v[60:61]
	v_lshl_add_u64 v[60:61], v[60:61], 0, v[126:127]
	v_cvt_pk_bf16_f32 v62, v64, v65
	v_cvt_pk_bf16_f32 v63, v66, v67
	v_cvt_pk_bf16_f32 v64, v78, v79
	v_cvt_pk_bf16_f32 v65, v80, v81
	global_store_dwordx4 v[60:61], v[62:65], off
	v_mul_f32_e32 v67, v70, v174
	v_mul_f32_e32 v66, v74, v174
	v_mul_f32_e32 v63, v68, v174
	v_mul_f32_e32 v62, v72, v174
	v_max_f32_e32 v64, 0, v63
	v_mul_f32_e32 v63, v73, v174
	v_mul_f32_e32 v65, v69, v174
	v_max_f32_e32 v68, 0, v67
	v_mul_f32_e32 v67, v75, v174
	v_mul_f32_e32 v69, v71, v174
	v_max_f32_e32 v62, 0, v62
	v_max_f32_e32 v63, 0, v63
	v_max_f32_e32 v65, 0, v65
	v_max_f32_e32 v66, 0, v66
	v_max_f32_e32 v67, 0, v67
	v_max_f32_e32 v69, 0, v69
	v_mul_f32_e32 v62, v62, v62
	v_mul_f32_e32 v63, v63, v63
	v_mul_f32_e32 v64, v64, v64
	v_mul_f32_e32 v65, v65, v65
	v_mul_f32_e32 v66, v66, v66
	v_mul_f32_e32 v67, v67, v67
	v_mul_f32_e32 v68, v68, v68
	v_mul_f32_e32 v69, v69, v69
	v_mul_f32_e32 v52, v52, v173
	v_mul_f32_e32 v53, v53, v173
	v_cvt_pk_bf16_f32 v62, v62, v63
	v_cvt_pk_bf16_f32 v63, v66, v67
	v_cvt_pk_bf16_f32 v64, v64, v65
	v_cvt_pk_bf16_f32 v65, v68, v69
	v_max_f32_e32 v52, 0, v52
	v_max_f32_e32 v53, 0, v53
	global_store_dwordx4 v[124:125], v[62:65], off offset:256
	v_mul_f32_e32 v56, v56, v173
	v_mul_f32_e32 v57, v57, v173
	v_mul_f32_e32 v62, v52, v52
	v_mul_f32_e32 v63, v53, v53
	v_mul_f32_e32 v53, v54, v173
	v_mul_f32_e32 v52, v58, v173
	v_max_f32_e32 v54, 0, v53
	v_mul_f32_e32 v53, v59, v173
	v_mul_f32_e32 v55, v55, v173
	v_max_f32_e32 v56, 0, v56
	v_max_f32_e32 v57, 0, v57
	v_max_f32_e32 v52, 0, v52
	v_max_f32_e32 v53, 0, v53
	v_max_f32_e32 v55, 0, v55
	v_mul_f32_e32 v56, v56, v56
	v_mul_f32_e32 v57, v57, v57
	v_mul_f32_e32 v58, v52, v52
	v_mul_f32_e32 v59, v53, v53
	v_mul_f32_e32 v64, v54, v54
	v_mul_f32_e32 v65, v55, v55
	v_mul_f32_e32 v44, v44, v172
	v_mul_f32_e32 v45, v45, v172
	v_cvt_pk_bf16_f32 v52, v56, v57
	v_cvt_pk_bf16_f32 v53, v58, v59
	v_cvt_pk_bf16_f32 v54, v62, v63
	v_cvt_pk_bf16_f32 v55, v64, v65
	v_max_f32_e32 v44, 0, v44
	v_max_f32_e32 v45, 0, v45
	global_store_dwordx4 v[116:117], v[52:55], off offset:256
	v_mul_f32_e32 v48, v48, v172
	v_mul_f32_e32 v49, v49, v172
	v_mul_f32_e32 v52, v44, v44
	v_mul_f32_e32 v53, v45, v45
	v_mul_f32_e32 v45, v46, v172
	v_mul_f32_e32 v44, v50, v172
	v_max_f32_e32 v46, 0, v45
	v_mul_f32_e32 v45, v51, v172
	v_mul_f32_e32 v47, v47, v172
	v_max_f32_e32 v48, 0, v48
	v_max_f32_e32 v49, 0, v49
	v_max_f32_e32 v44, 0, v44
	v_max_f32_e32 v45, 0, v45
	v_max_f32_e32 v47, 0, v47
	v_mul_f32_e32 v48, v48, v48
	v_mul_f32_e32 v49, v49, v49
	v_mul_f32_e32 v50, v44, v44
	v_mul_f32_e32 v51, v45, v45
	v_mul_f32_e32 v54, v46, v46
	v_mul_f32_e32 v55, v47, v47
	v_mul_f32_e32 v36, v36, v170
	v_mul_f32_e32 v37, v37, v170
	v_cvt_pk_bf16_f32 v44, v48, v49
	v_cvt_pk_bf16_f32 v45, v50, v51
	v_cvt_pk_bf16_f32 v46, v52, v53
	v_cvt_pk_bf16_f32 v47, v54, v55
	v_max_f32_e32 v36, 0, v36
	v_max_f32_e32 v37, 0, v37
	global_store_dwordx4 v[108:109], v[44:47], off offset:256
	v_mul_f32_e32 v40, v40, v170
	v_mul_f32_e32 v41, v41, v170
	v_mul_f32_e32 v44, v36, v36
	v_mul_f32_e32 v45, v37, v37
	v_mul_f32_e32 v37, v38, v170
	v_mul_f32_e32 v36, v42, v170
	v_max_f32_e32 v38, 0, v37
	v_mul_f32_e32 v37, v43, v170
	v_mul_f32_e32 v39, v39, v170
	v_max_f32_e32 v40, 0, v40
	v_max_f32_e32 v41, 0, v41
	v_max_f32_e32 v36, 0, v36
	v_max_f32_e32 v37, 0, v37
	v_max_f32_e32 v39, 0, v39
	v_mul_f32_e32 v40, v40, v40
	v_mul_f32_e32 v41, v41, v41
	v_mul_f32_e32 v42, v36, v36
	v_mul_f32_e32 v43, v37, v37
	v_mul_f32_e32 v46, v38, v38
	v_mul_f32_e32 v47, v39, v39
	v_mul_f32_e32 v28, v28, v163
	v_mul_f32_e32 v29, v29, v163
	v_cvt_pk_bf16_f32 v36, v40, v41
	v_cvt_pk_bf16_f32 v37, v42, v43
	v_cvt_pk_bf16_f32 v38, v44, v45
	v_cvt_pk_bf16_f32 v39, v46, v47
	v_max_f32_e32 v28, 0, v28
	v_max_f32_e32 v29, 0, v29
	global_store_dwordx4 v[100:101], v[36:39], off offset:256
	v_mul_f32_e32 v32, v32, v163
	v_mul_f32_e32 v33, v33, v163
	v_mul_f32_e32 v36, v28, v28
	v_mul_f32_e32 v37, v29, v29
	v_mul_f32_e32 v29, v30, v163
	v_mul_f32_e32 v28, v34, v163
	v_max_f32_e32 v30, 0, v29
	v_mul_f32_e32 v29, v35, v163
	v_mul_f32_e32 v31, v31, v163
	v_max_f32_e32 v32, 0, v32
	v_max_f32_e32 v33, 0, v33
	v_max_f32_e32 v28, 0, v28
	v_max_f32_e32 v29, 0, v29
	v_max_f32_e32 v31, 0, v31
	v_mul_f32_e32 v32, v32, v32
	v_mul_f32_e32 v33, v33, v33
	v_mul_f32_e32 v34, v28, v28
	v_mul_f32_e32 v35, v29, v29
	v_mul_f32_e32 v38, v30, v30
	v_mul_f32_e32 v39, v31, v31
	v_mul_f32_e32 v20, v20, v162
	v_mul_f32_e32 v21, v21, v162
	v_cvt_pk_bf16_f32 v28, v32, v33
	v_cvt_pk_bf16_f32 v29, v34, v35
	v_cvt_pk_bf16_f32 v30, v36, v37
	v_cvt_pk_bf16_f32 v31, v38, v39
	v_max_f32_e32 v20, 0, v20
	v_max_f32_e32 v21, 0, v21
	global_store_dwordx4 v[92:93], v[28:31], off offset:256
	v_mul_f32_e32 v24, v24, v162
	v_mul_f32_e32 v25, v25, v162
	v_mul_f32_e32 v28, v20, v20
	v_mul_f32_e32 v29, v21, v21
	v_mul_f32_e32 v21, v22, v162
	v_mul_f32_e32 v20, v26, v162
	v_max_f32_e32 v22, 0, v21
	v_mul_f32_e32 v21, v27, v162
	v_mul_f32_e32 v23, v23, v162
	v_max_f32_e32 v24, 0, v24
	v_max_f32_e32 v25, 0, v25
	v_max_f32_e32 v20, 0, v20
	v_max_f32_e32 v21, 0, v21
	v_max_f32_e32 v23, 0, v23
	v_mul_f32_e32 v24, v24, v24
	v_mul_f32_e32 v25, v25, v25
	v_mul_f32_e32 v26, v20, v20
	v_mul_f32_e32 v27, v21, v21
	v_mul_f32_e32 v30, v22, v22
	v_mul_f32_e32 v31, v23, v23
	v_mul_f32_e32 v12, v12, v161
	v_mul_f32_e32 v13, v13, v161
	v_cvt_pk_bf16_f32 v20, v24, v25
	v_cvt_pk_bf16_f32 v21, v26, v27
	v_cvt_pk_bf16_f32 v22, v28, v29
	v_cvt_pk_bf16_f32 v23, v30, v31
	v_max_f32_e32 v12, 0, v12
	v_max_f32_e32 v13, 0, v13
	global_store_dwordx4 v[84:85], v[20:23], off offset:256
	v_mul_f32_e32 v16, v16, v161
	v_mul_f32_e32 v17, v17, v161
	v_mul_f32_e32 v20, v12, v12
	v_mul_f32_e32 v21, v13, v13
	v_mul_f32_e32 v13, v14, v161
	v_mul_f32_e32 v12, v18, v161
	v_max_f32_e32 v14, 0, v13
	v_mul_f32_e32 v13, v19, v161
	v_mul_f32_e32 v15, v15, v161
	v_max_f32_e32 v16, 0, v16
	v_max_f32_e32 v17, 0, v17
	v_max_f32_e32 v12, 0, v12
	v_max_f32_e32 v13, 0, v13
	v_max_f32_e32 v15, 0, v15
	v_mul_f32_e32 v16, v16, v16
	v_mul_f32_e32 v17, v17, v17
	v_mul_f32_e32 v18, v12, v12
	v_mul_f32_e32 v19, v13, v13
	v_mul_f32_e32 v22, v14, v14
	v_mul_f32_e32 v23, v15, v15
	v_mul_f32_e32 v4, v4, v160
	v_mul_f32_e32 v5, v5, v160
	v_cvt_pk_bf16_f32 v12, v16, v17
	v_cvt_pk_bf16_f32 v13, v18, v19
	v_cvt_pk_bf16_f32 v14, v20, v21
	v_cvt_pk_bf16_f32 v15, v22, v23
	v_max_f32_e32 v4, 0, v4
	v_max_f32_e32 v5, 0, v5
	global_store_dwordx4 v[76:77], v[12:15], off offset:256
	v_mul_f32_e32 v8, v8, v160
	v_mul_f32_e32 v9, v9, v160
	v_mul_f32_e32 v12, v4, v4
	v_mul_f32_e32 v13, v5, v5
	v_mul_f32_e32 v5, v6, v160
	v_mul_f32_e32 v4, v10, v160
	v_max_f32_e32 v6, 0, v5
	v_mul_f32_e32 v5, v11, v160
	v_mul_f32_e32 v7, v7, v160
	v_max_f32_e32 v8, 0, v8
	v_max_f32_e32 v9, 0, v9
	v_max_f32_e32 v4, 0, v4
	v_max_f32_e32 v5, 0, v5
	v_max_f32_e32 v7, 0, v7
	v_mul_f32_e32 v8, v8, v8
	v_mul_f32_e32 v9, v9, v9
	v_mul_f32_e32 v10, v4, v4
	v_mul_f32_e32 v11, v5, v5
	v_mul_f32_e32 v14, v6, v6
	v_mul_f32_e32 v15, v7, v7
	v_cvt_pk_bf16_f32 v4, v8, v9
	v_cvt_pk_bf16_f32 v5, v10, v11
	v_cvt_pk_bf16_f32 v6, v12, v13
	v_cvt_pk_bf16_f32 v7, v14, v15
	global_store_dwordx4 v[60:61], v[4:7], off offset:256
	s_cbranch_vccz .LBB0_1089
	s_waitcnt vmcnt(0)
	v_mov_b64_e32 v[164:165], 0x100
	v_mov_b64_e32 v[166:167], 0xff
	v_mov_b32_e32 v246, 0
	v_mov_b32_e32 v247, 0
	v_mov_b32_e32 v248, 0
	v_mov_b32_e32 v249, 0
	v_mov_b32_e32 v171, 0x3f2aaaaa
	s_cmpk_gt_u32 s22, 0xff
	v_readlane_b32 s36, v254, 31
	v_readlane_b32 s37, v254, 32
	s_cbranch_scc1 .LBB0_1102
	s_barrier
